# 4-phase K-loop without per-segment setprio toggles
# speedup vs baseline: 1.0457x; 1.0024x over previous
; #define PG8_STAGE(bufoff, gbase, voff) do { _Pragma("unroll") for (int _i = 0; _i < 2; ++_i) \
;         __builtin_amdgcn_global_load_lds((const unsigned*)((const char*)(gbase) + (voff)[_i]), (PG8_LAS unsigned*)(lds + (bufoff) + ldsw + _i * 8192), 16, 0, 0); } while (0)
; #define PG8_LDA(dst, b, h) do { _Pragma("unroll") for (int m = 0; m < 4; ++m) _Pragma("unroll") for (int k = 0; k < 2; ++k) dst[m][k] = *(const PG8_LAS bf16x8*)(lds + PG8_SA(b, h) + aoff + m * 2048 + k * 1024); } while (0)
; #define PG8_LDB(dst, b, h) do { _Pragma("unroll") for (int n = 0; n < 2; ++n) _Pragma("unroll") for (int k = 0; k < 2; ++k) dst[n][k] = *(const PG8_LAS bf16x8*)(lds + PG8_SB(b, h) + boff + n * 2048 + k * 1024); } while (0)
; #define PG8_MMA(ai, bj, At, Bt) do { __builtin_amdgcn_s_setprio(1); _Pragma("unroll") for (int m = 0; m < 4; ++m) _Pragma("unroll") for (int n = 0; n < 2; ++n) _Pragma("unroll") for (int k = 0; k < 2; ++k) \
;         acc[ai][bj][m][n] = __builtin_amdgcn_mfma_f32_16x16x32_bf16(Bt[n][k], At[m][k], acc[ai][bj][m][n], 0, 0, 0); __builtin_amdgcn_s_setprio(0); } while (0)
; #define PG8_WAIT_V(n) asm volatile("s_waitcnt vmcnt(" #n ")" ::: "memory")
; #define PG8_WAIT_L(n) asm volatile("s_waitcnt lgkmcnt(" #n ")" ::: "memory")
; template <class Epi, class Sched>
; __device__ __forceinline__ void gemm_phase(PG8_LAS unsigned char* lds, const Gemm g, const Sched& S, const Epi& E) {
;     ...
;             const bool last = (t == nt - 2);
;             const char* a1 = cA + (size_t)(t + 1) * kstep;
;             const char* a2 = last ? nA : cA + (size_t)(t + 2) * kstep; const char* b2 = last ? nB : cB + (size_t)(t + 2) * kstepB;
;             const char* a3 = a2 + kstep; const char* b3 = b2 + kstepB;
;             if (last && has_next) S.a_ready(nxt);
;             PG8_LDB(B0, 0, 0); PG8_SCHED; PG8_LDA(At, 0, 0); PG8_STAGE(PG8_SA(1, 1), a1 + hstep, voffA);
;             PG8_WAIT_L(8); PG8_BAR; PG8_WAIT_L(0); PG8_MMA(0, 0, At, B0); PG8_BAR; PG8_SCHED;
;             PG8_LDB(B1, 0, 1); PG8_STAGE(PG8_SB(0, 0), b2, voffB);
;             PG8_BAR; PG8_WAIT_L(0); PG8_MMA(0, 1, At, B1); PG8_BAR;
;             PG8_LDA(At, 0, 1); PG8_STAGE(PG8_SA(0, 0), a2, voffA);
;             PG8_BAR; PG8_WAIT_L(0); PG8_MMA(1, 0, At, B0); PG8_BAR; PG8_SCHED;
;             PG8_STAGE(PG8_SB(0, 1), b2 + hstepB, voffB);
;             PG8_WAIT_V(6); PG8_BAR; PG8_MMA(1, 1, At, B1); PG8_BAR;
.Lhalf_skip_y_0:
.LBB0_79:
	ds_read_b128 v[152:155], v149
	ds_read_b128 v[156:159], v149 offset:1024
	ds_read_b128 v[160:163], v149 offset:2048
	ds_read_b128 v[164:167], v149 offset:3072
	s_add_u32 s24, s22, 0xfff80080
	s_addc_u32 s25, s23, -1
	s_cmp_eq_u32 s61, 28
	s_cselect_b32 s27, s13, s25
	s_cselect_b32 s26, s57, s24
	s_cselect_b32 s25, s15, s60
	s_cselect_b32 s24, s58, s59
	v_lshl_add_u64 v[144:145], s[22:23], 0, v[136:137]
	s_add_i32 m0, s21, 0xc000
	ds_read_b128 v[168:171], v150
	ds_read_b128 v[172:175], v150 offset:1024
	ds_read_b128 v[176:179], v150 offset:2048
	ds_read_b128 v[180:183], v150 offset:3072
	ds_read_b128 v[184:187], v150 offset:4096
	ds_read_b128 v[188:191], v150 offset:5120
	ds_read_b128 v[192:195], v150 offset:6144
	ds_read_b128 v[196:199], v150 offset:7168
	global_load_lds_dwordx4 v[144:145], off
	v_lshl_add_u64 v[144:145], s[22:23], 0, v[138:139]
	s_add_i32 m0, s21, 0xe000
	s_nop 0
	global_load_lds_dwordx4 v[144:145], off
	s_add_i32 s62, s53, s38
	v_lshl_add_u64 v[144:145], s[24:25], 0, v[128:129]
	s_mov_b32 m0, s62
	ds_read_b128 v[200:203], v151
	ds_read_b128 v[204:207], v151 offset:1024
	ds_read_b128 v[208:211], v151 offset:2048
	ds_read_b128 v[212:215], v151 offset:3072
	s_waitcnt vmcnt(8)
	s_waitcnt lgkmcnt(0)
	s_barrier
	v_mfma_f32_16x16x32_bf16 v[124:127], v[152:155], v[168:171], v[124:127]
	v_mfma_f32_16x16x32_bf16 v[120:123], v[160:163], v[168:171], v[120:123]
	v_mfma_f32_16x16x32_bf16 v[108:111], v[152:155], v[176:179], v[108:111]
	v_mfma_f32_16x16x32_bf16 v[104:107], v[160:163], v[176:179], v[104:107]
	v_mfma_f32_16x16x32_bf16 v[92:95], v[152:155], v[184:187], v[92:95]
	v_mfma_f32_16x16x32_bf16 v[88:91], v[160:163], v[184:187], v[88:91]
	v_mfma_f32_16x16x32_bf16 v[76:79], v[152:155], v[192:195], v[76:79]
	v_mfma_f32_16x16x32_bf16 v[72:75], v[160:163], v[192:195], v[72:75]
	v_mfma_f32_16x16x32_bf16 v[124:127], v[156:159], v[172:175], v[124:127]
	v_mfma_f32_16x16x32_bf16 v[120:123], v[164:167], v[172:175], v[120:123]
	v_mfma_f32_16x16x32_bf16 v[108:111], v[156:159], v[180:183], v[108:111]
	v_mfma_f32_16x16x32_bf16 v[104:107], v[164:167], v[180:183], v[104:107]
	v_mfma_f32_16x16x32_bf16 v[92:95], v[156:159], v[188:191], v[92:95]
	v_mfma_f32_16x16x32_bf16 v[88:91], v[164:167], v[188:191], v[88:91]
	v_mfma_f32_16x16x32_bf16 v[76:79], v[156:159], v[196:199], v[76:79]
	v_mfma_f32_16x16x32_bf16 v[72:75], v[164:167], v[196:199], v[72:75]
	v_mfma_f32_16x16x32_bf16 v[116:119], v[200:203], v[168:171], v[116:119]
	v_mfma_f32_16x16x32_bf16 v[112:115], v[208:211], v[168:171], v[112:115]
	v_mfma_f32_16x16x32_bf16 v[100:103], v[200:203], v[176:179], v[100:103]
	v_mfma_f32_16x16x32_bf16 v[96:99], v[208:211], v[176:179], v[96:99]
	v_mfma_f32_16x16x32_bf16 v[84:87], v[200:203], v[184:187], v[84:87]
	v_mfma_f32_16x16x32_bf16 v[80:83], v[208:211], v[184:187], v[80:83]
	v_mfma_f32_16x16x32_bf16 v[68:71], v[200:203], v[192:195], v[68:71]
	v_mfma_f32_16x16x32_bf16 v[64:67], v[208:211], v[192:195], v[64:67]
	v_mfma_f32_16x16x32_bf16 v[116:119], v[204:207], v[172:175], v[116:119]
	v_mfma_f32_16x16x32_bf16 v[112:115], v[212:215], v[172:175], v[112:115]
	v_mfma_f32_16x16x32_bf16 v[100:103], v[204:207], v[180:183], v[100:103]
	v_mfma_f32_16x16x32_bf16 v[96:99], v[212:215], v[180:183], v[96:99]
	v_mfma_f32_16x16x32_bf16 v[84:87], v[204:207], v[188:191], v[84:87]
	v_mfma_f32_16x16x32_bf16 v[80:83], v[212:215], v[188:191], v[80:83]
	v_mfma_f32_16x16x32_bf16 v[68:71], v[204:207], v[196:199], v[68:71]
	v_mfma_f32_16x16x32_bf16 v[64:67], v[212:215], v[196:199], v[64:67]
	s_barrier
	global_load_lds_dwordx4 v[144:145], off
	v_lshl_add_u64 v[144:145], s[24:25], 0, v[130:131]
	s_add_i32 m0, s62, 0x2000
	s_nop 0
	global_load_lds_dwordx4 v[144:145], off
	s_mov_b32 m0, s21
	v_lshl_add_u64 v[144:145], s[26:27], 0, v[134:135]
	ds_read_b128 v[168:171], v150 offset:16384
	ds_read_b128 v[172:175], v150 offset:17408
	ds_read_b128 v[176:179], v150 offset:18432
	ds_read_b128 v[180:183], v150 offset:19456
	ds_read_b128 v[184:187], v150 offset:20480
	ds_read_b128 v[188:191], v150 offset:21504
	ds_read_b128 v[192:195], v150 offset:22528
	ds_read_b128 v[196:199], v150 offset:23552
	global_load_lds_dwordx4 v[144:145], off
	v_lshl_add_u64 v[216:217], s[26:27], 0, v[132:133]
	s_mov_b32 m0, s46
	s_nop 0
	global_load_lds_dwordx4 v[216:217], off
	s_add_u32 s62, s24, 0x4000
	s_addc_u32 s63, s25, 0
	s_add_i32 s64, s54, s38
	v_lshl_add_u64 v[250:251], s[62:63], 0, v[128:129]
	s_mov_b32 m0, s64
	s_nop 0
	global_load_lds_dwordx4 v[250:251], off
	v_lshl_add_u64 v[250:251], s[62:63], 0, v[130:131]
	s_add_i32 m0, s64, 0x2000
	s_nop 0
	global_load_lds_dwordx4 v[250:251], off
	s_waitcnt vmcnt(8)
	s_waitcnt lgkmcnt(0)
	s_barrier
; #define PG8_STAGE(bufoff, gbase, voff) do { _Pragma("unroll") for (int _i = 0; _i < 2; ++_i) \
;         __builtin_amdgcn_global_load_lds((const unsigned*)((const char*)(gbase) + (voff)[_i]), (PG8_LAS unsigned*)(lds + (bufoff) + ldsw + _i * 8192), 16, 0, 0); } while (0)
; #define PG8_LDA(dst, b, h) do { _Pragma("unroll") for (int m = 0; m < 4; ++m) _Pragma("unroll") for (int k = 0; k < 2; ++k) dst[m][k] = *(const PG8_LAS bf16x8*)(lds + PG8_SA(b, h) + aoff + m * 2048 + k * 1024); } while (0)
; #define PG8_LDB(dst, b, h) do { _Pragma("unroll") for (int n = 0; n < 2; ++n) _Pragma("unroll") for (int k = 0; k < 2; ++k) dst[n][k] = *(const PG8_LAS bf16x8*)(lds + PG8_SB(b, h) + boff + n * 2048 + k * 1024); } while (0)
; #define PG8_MMA(ai, bj, At, Bt) do { __builtin_amdgcn_s_setprio(1); _Pragma("unroll") for (int m = 0; m < 4; ++m) _Pragma("unroll") for (int n = 0; n < 2; ++n) _Pragma("unroll") for (int k = 0; k < 2; ++k) \
;         acc[ai][bj][m][n] = __builtin_amdgcn_mfma_f32_16x16x32_bf16(Bt[n][k], At[m][k], acc[ai][bj][m][n], 0, 0, 0); __builtin_amdgcn_s_setprio(0); } while (0)
; #define PG8_WAIT_V(n) asm volatile("s_waitcnt vmcnt(" #n ")" ::: "memory")
; #define PG8_WAIT_L(n) asm volatile("s_waitcnt lgkmcnt(" #n ")" ::: "memory")
; #define PG8_BAR __builtin_amdgcn_s_barrier()
; #define PG8_SCHED __builtin_amdgcn_sched_barrier(0)
; template <class Epi, class Sched>
; __device__ __forceinline__ void gemm_phase(PG8_LAS unsigned char* lds, const Gemm g, const Sched& S, const Epi& E) {
;     ...
;             PG8_BAR; PG8_WAIT_L(0); PG8_MMA(1, 0, At, B0); PG8_BAR; PG8_SCHED;
;             PG8_STAGE(PG8_SB(0, 1), b2 + hstepB, voffB);
;             PG8_WAIT_V(6); PG8_BAR; PG8_MMA(1, 1, At, B1); PG8_BAR;
;             PG8_LDB(B0, 1, 0); PG8_SCHED; PG8_LDA(At, 1, 0); PG8_STAGE(PG8_SA(0, 1), a2 + hstep, voffA);
;             PG8_WAIT_L(8); PG8_BAR; PG8_WAIT_L(0); PG8_MMA(0, 0, At, B0); PG8_BAR; PG8_SCHED;
;             PG8_LDB(B1, 1, 1); PG8_STAGE(PG8_SB(1, 0), b3, voffB);
;             PG8_BAR; PG8_WAIT_L(0); PG8_MMA(0, 1, At, B1); PG8_BAR;
	v_mfma_f32_16x16x32_bf16 v[60:63], v[152:155], v[168:171], v[60:63]
	v_mfma_f32_16x16x32_bf16 v[56:59], v[160:163], v[168:171], v[56:59]
	v_mfma_f32_16x16x32_bf16 v[44:47], v[152:155], v[176:179], v[44:47]
	v_mfma_f32_16x16x32_bf16 v[40:43], v[160:163], v[176:179], v[40:43]
	v_mfma_f32_16x16x32_bf16 v[28:31], v[152:155], v[184:187], v[28:31]
	v_mfma_f32_16x16x32_bf16 v[24:27], v[160:163], v[184:187], v[24:27]
	v_mfma_f32_16x16x32_bf16 v[12:15], v[152:155], v[192:195], v[12:15]
	v_mfma_f32_16x16x32_bf16 v[8:11], v[160:163], v[192:195], v[8:11]
	v_mfma_f32_16x16x32_bf16 v[60:63], v[156:159], v[172:175], v[60:63]
	v_mfma_f32_16x16x32_bf16 v[56:59], v[164:167], v[172:175], v[56:59]
	v_mfma_f32_16x16x32_bf16 v[44:47], v[156:159], v[180:183], v[44:47]
	v_mfma_f32_16x16x32_bf16 v[40:43], v[164:167], v[180:183], v[40:43]
	v_mfma_f32_16x16x32_bf16 v[28:31], v[156:159], v[188:191], v[28:31]
	v_mfma_f32_16x16x32_bf16 v[24:27], v[164:167], v[188:191], v[24:27]
	v_mfma_f32_16x16x32_bf16 v[12:15], v[156:159], v[196:199], v[12:15]
	v_mfma_f32_16x16x32_bf16 v[8:11], v[164:167], v[196:199], v[8:11]
	v_mfma_f32_16x16x32_bf16 v[52:55], v[200:203], v[168:171], v[52:55]
	v_mfma_f32_16x16x32_bf16 v[48:51], v[208:211], v[168:171], v[48:51]
	v_mfma_f32_16x16x32_bf16 v[36:39], v[200:203], v[176:179], v[36:39]
	v_mfma_f32_16x16x32_bf16 v[32:35], v[208:211], v[176:179], v[32:35]
	v_mfma_f32_16x16x32_bf16 v[20:23], v[200:203], v[184:187], v[20:23]
	v_mfma_f32_16x16x32_bf16 v[16:19], v[208:211], v[184:187], v[16:19]
	v_mfma_f32_16x16x32_bf16 v[4:7], v[200:203], v[192:195], v[4:7]
	v_mfma_f32_16x16x32_bf16 v[0:3], v[208:211], v[192:195], v[0:3]
	v_mfma_f32_16x16x32_bf16 v[52:55], v[204:207], v[172:175], v[52:55]
	v_mfma_f32_16x16x32_bf16 v[48:51], v[212:215], v[172:175], v[48:51]
	v_mfma_f32_16x16x32_bf16 v[36:39], v[204:207], v[180:183], v[36:39]
	v_mfma_f32_16x16x32_bf16 v[32:35], v[212:215], v[180:183], v[32:35]
	v_mfma_f32_16x16x32_bf16 v[20:23], v[204:207], v[188:191], v[20:23]
	v_mfma_f32_16x16x32_bf16 v[16:19], v[212:215], v[188:191], v[16:19]
	v_mfma_f32_16x16x32_bf16 v[4:7], v[204:207], v[196:199], v[4:7]
	v_mfma_f32_16x16x32_bf16 v[0:3], v[212:215], v[196:199], v[0:3]
	s_barrier
	s_add_i32 s62, 0, 0x18000
	v_add_u32_e32 v164, s62, v147
	ds_read_b128 v[152:155], v164
	ds_read_b128 v[156:159], v164 offset:1024
	ds_read_b128 v[160:163], v164 offset:2048
	ds_read_b128 v[164:167], v164 offset:3072
	s_add_u32 s26, s26, 0x80000
	s_addc_u32 s27, s27, 0
	s_mov_b32 m0, s47
	v_lshl_add_u64 v[200:201], s[26:27], 0, v[134:135]
	ds_read_b128 v[168:171], v150 offset:32768
	ds_read_b128 v[172:175], v150 offset:33792
	ds_read_b128 v[176:179], v150 offset:34816
	ds_read_b128 v[180:183], v150 offset:35840
	ds_read_b128 v[184:187], v150 offset:36864
	ds_read_b128 v[188:191], v150 offset:37888
	ds_read_b128 v[192:195], v150 offset:38912
	ds_read_b128 v[196:199], v150 offset:39936
	global_load_lds_dwordx4 v[200:201], off
	v_lshl_add_u64 v[200:201], s[26:27], 0, v[132:133]
	s_mov_b32 m0, s48
	s_nop 0
	global_load_lds_dwordx4 v[200:201], off
	s_add_i32 s63, 0, 0x1c000
	s_add_u32 s26, s24, 0x8000
	s_addc_u32 s27, s25, 0
	s_add_i32 s62, s62, s38
	v_add_u32_e32 v212, s63, v147
	v_lshl_add_u64 v[218:219], s[26:27], 0, v[128:129]
	s_mov_b32 m0, s62
	ds_read_b128 v[200:203], v212
	ds_read_b128 v[204:207], v212 offset:1024
	ds_read_b128 v[208:211], v212 offset:2048
	ds_read_b128 v[212:215], v212 offset:3072
	s_waitcnt vmcnt(8)
	s_waitcnt lgkmcnt(0)
	s_barrier
	v_mfma_f32_16x16x32_bf16 v[124:127], v[152:155], v[168:171], v[124:127]
	v_mfma_f32_16x16x32_bf16 v[120:123], v[160:163], v[168:171], v[120:123]
	v_mfma_f32_16x16x32_bf16 v[108:111], v[152:155], v[176:179], v[108:111]
	v_mfma_f32_16x16x32_bf16 v[104:107], v[160:163], v[176:179], v[104:107]
	v_mfma_f32_16x16x32_bf16 v[92:95], v[152:155], v[184:187], v[92:95]
	v_mfma_f32_16x16x32_bf16 v[88:91], v[160:163], v[184:187], v[88:91]
	v_mfma_f32_16x16x32_bf16 v[76:79], v[152:155], v[192:195], v[76:79]
	v_mfma_f32_16x16x32_bf16 v[72:75], v[160:163], v[192:195], v[72:75]
	v_mfma_f32_16x16x32_bf16 v[124:127], v[156:159], v[172:175], v[124:127]
	v_mfma_f32_16x16x32_bf16 v[120:123], v[164:167], v[172:175], v[120:123]
	v_mfma_f32_16x16x32_bf16 v[108:111], v[156:159], v[180:183], v[108:111]
	v_mfma_f32_16x16x32_bf16 v[104:107], v[164:167], v[180:183], v[104:107]
	v_mfma_f32_16x16x32_bf16 v[92:95], v[156:159], v[188:191], v[92:95]
	v_mfma_f32_16x16x32_bf16 v[88:91], v[164:167], v[188:191], v[88:91]
	v_mfma_f32_16x16x32_bf16 v[76:79], v[156:159], v[196:199], v[76:79]
	v_mfma_f32_16x16x32_bf16 v[72:75], v[164:167], v[196:199], v[72:75]
	v_mfma_f32_16x16x32_bf16 v[116:119], v[200:203], v[168:171], v[116:119]
	v_mfma_f32_16x16x32_bf16 v[112:115], v[208:211], v[168:171], v[112:115]
	v_mfma_f32_16x16x32_bf16 v[100:103], v[200:203], v[176:179], v[100:103]
	v_mfma_f32_16x16x32_bf16 v[96:99], v[208:211], v[176:179], v[96:99]
	v_mfma_f32_16x16x32_bf16 v[84:87], v[200:203], v[184:187], v[84:87]
	v_mfma_f32_16x16x32_bf16 v[80:83], v[208:211], v[184:187], v[80:83]
	v_mfma_f32_16x16x32_bf16 v[68:71], v[200:203], v[192:195], v[68:71]
	v_mfma_f32_16x16x32_bf16 v[64:67], v[208:211], v[192:195], v[64:67]
	v_mfma_f32_16x16x32_bf16 v[116:119], v[204:207], v[172:175], v[116:119]
	v_mfma_f32_16x16x32_bf16 v[112:115], v[212:215], v[172:175], v[112:115]
	v_mfma_f32_16x16x32_bf16 v[100:103], v[204:207], v[180:183], v[100:103]
	v_mfma_f32_16x16x32_bf16 v[96:99], v[212:215], v[180:183], v[96:99]
	v_mfma_f32_16x16x32_bf16 v[84:87], v[204:207], v[188:191], v[84:87]
	v_mfma_f32_16x16x32_bf16 v[80:83], v[212:215], v[188:191], v[80:83]
	v_mfma_f32_16x16x32_bf16 v[68:71], v[204:207], v[196:199], v[68:71]
	v_mfma_f32_16x16x32_bf16 v[64:67], v[212:215], v[196:199], v[64:67]
	s_barrier
; #define PG8_STAGE(bufoff, gbase, voff) do { _Pragma("unroll") for (int _i = 0; _i < 2; ++_i) \
;         __builtin_amdgcn_global_load_lds((const unsigned*)((const char*)(gbase) + (voff)[_i]), (PG8_LAS unsigned*)(lds + (bufoff) + ldsw + _i * 8192), 16, 0, 0); } while (0)
; #define PG8_LDA(dst, b, h) do { _Pragma("unroll") for (int m = 0; m < 4; ++m) _Pragma("unroll") for (int k = 0; k < 2; ++k) dst[m][k] = *(const PG8_LAS bf16x8*)(lds + PG8_SA(b, h) + aoff + m * 2048 + k * 1024); } while (0)
; #define PG8_LDB(dst, b, h) do { _Pragma("unroll") for (int n = 0; n < 2; ++n) _Pragma("unroll") for (int k = 0; k < 2; ++k) dst[n][k] = *(const PG8_LAS bf16x8*)(lds + PG8_SB(b, h) + boff + n * 2048 + k * 1024); } while (0)
; #define PG8_MMA(ai, bj, At, Bt) do { __builtin_amdgcn_s_setprio(1); _Pragma("unroll") for (int m = 0; m < 4; ++m) _Pragma("unroll") for (int n = 0; n < 2; ++n) _Pragma("unroll") for (int k = 0; k < 2; ++k) \
;         acc[ai][bj][m][n] = __builtin_amdgcn_mfma_f32_16x16x32_bf16(Bt[n][k], At[m][k], acc[ai][bj][m][n], 0, 0, 0); __builtin_amdgcn_s_setprio(0); } while (0)
; #define PG8_WAIT_V(n) asm volatile("s_waitcnt vmcnt(" #n ")" ::: "memory")
; #define PG8_WAIT_L(n) asm volatile("s_waitcnt lgkmcnt(" #n ")" ::: "memory")
; #define PG8_BAR __builtin_amdgcn_s_barrier()
; #define PG8_SCHED __builtin_amdgcn_sched_barrier(0)
; template <class Epi, class Sched>
; __device__ __forceinline__ void gemm_phase(PG8_LAS unsigned char* lds, const Gemm g, const Sched& S, const Epi& E) {
;     ...
;             PG8_LDB(B1, 1, 1); PG8_STAGE(PG8_SB(1, 0), b3, voffB);
;             PG8_BAR; PG8_WAIT_L(0); PG8_MMA(0, 1, At, B1); PG8_BAR;
;             PG8_LDA(At, 1, 1); PG8_STAGE(PG8_SA(1, 0), a3, voffA);
;             PG8_BAR; PG8_WAIT_L(0); PG8_MMA(1, 0, At, B0); PG8_BAR; PG8_SCHED;
;             PG8_STAGE(PG8_SB(1, 1), b3 + hstepB, voffB);
;             PG8_WAIT_V(6); PG8_BAR; PG8_MMA(1, 1, At, B1); PG8_BAR;
;         }
	global_load_lds_dwordx4 v[218:219], off
	v_lshl_add_u64 v[218:219], s[26:27], 0, v[130:131]
	s_add_i32 m0, s62, 0x2000
	s_nop 0
	global_load_lds_dwordx4 v[218:219], off
	s_mov_b32 m0, s50
	v_lshl_add_u64 v[144:145], v[144:145], 0, s[10:11]
	ds_read_b128 v[168:171], v150 offset:49152
	ds_read_b128 v[172:175], v150 offset:50176
	ds_read_b128 v[176:179], v150 offset:51200
	ds_read_b128 v[180:183], v150 offset:52224
	ds_read_b128 v[184:187], v150 offset:53248
	ds_read_b128 v[188:191], v150 offset:54272
	ds_read_b128 v[192:195], v150 offset:55296
	ds_read_b128 v[196:199], v150 offset:56320
	global_load_lds_dwordx4 v[144:145], off
	v_lshl_add_u64 v[144:145], v[216:217], 0, s[10:11]
	s_mov_b32 m0, s51
	s_nop 0
	global_load_lds_dwordx4 v[144:145], off
	s_add_u32 s24, s24, 0xc000
	s_addc_u32 s25, s25, 0
	s_add_i32 s26, s63, s38
	v_lshl_add_u64 v[144:145], s[24:25], 0, v[128:129]
	s_mov_b32 m0, s26
	s_nop 0
	global_load_lds_dwordx4 v[144:145], off
	v_lshl_add_u64 v[144:145], s[24:25], 0, v[130:131]
	s_add_i32 m0, s26, 0x2000
	s_nop 0
	global_load_lds_dwordx4 v[144:145], off
	s_waitcnt vmcnt(8)
	s_waitcnt lgkmcnt(0)
	s_barrier
	v_mfma_f32_16x16x32_bf16 v[60:63], v[152:155], v[168:171], v[60:63]
	v_mfma_f32_16x16x32_bf16 v[56:59], v[160:163], v[168:171], v[56:59]
	v_mfma_f32_16x16x32_bf16 v[44:47], v[152:155], v[176:179], v[44:47]
	v_mfma_f32_16x16x32_bf16 v[40:43], v[160:163], v[176:179], v[40:43]
	v_mfma_f32_16x16x32_bf16 v[28:31], v[152:155], v[184:187], v[28:31]
	v_mfma_f32_16x16x32_bf16 v[24:27], v[160:163], v[184:187], v[24:27]
	v_mfma_f32_16x16x32_bf16 v[12:15], v[152:155], v[192:195], v[12:15]
	v_mfma_f32_16x16x32_bf16 v[8:11], v[160:163], v[192:195], v[8:11]
	v_mfma_f32_16x16x32_bf16 v[60:63], v[156:159], v[172:175], v[60:63]
	v_mfma_f32_16x16x32_bf16 v[56:59], v[164:167], v[172:175], v[56:59]
	v_mfma_f32_16x16x32_bf16 v[44:47], v[156:159], v[180:183], v[44:47]
	v_mfma_f32_16x16x32_bf16 v[40:43], v[164:167], v[180:183], v[40:43]
	v_mfma_f32_16x16x32_bf16 v[28:31], v[156:159], v[188:191], v[28:31]
	v_mfma_f32_16x16x32_bf16 v[24:27], v[164:167], v[188:191], v[24:27]
	v_mfma_f32_16x16x32_bf16 v[12:15], v[156:159], v[196:199], v[12:15]
	v_mfma_f32_16x16x32_bf16 v[8:11], v[164:167], v[196:199], v[8:11]
	v_mfma_f32_16x16x32_bf16 v[52:55], v[200:203], v[168:171], v[52:55]
	v_mfma_f32_16x16x32_bf16 v[48:51], v[208:211], v[168:171], v[48:51]
	v_mfma_f32_16x16x32_bf16 v[36:39], v[200:203], v[176:179], v[36:39]
	v_mfma_f32_16x16x32_bf16 v[32:35], v[208:211], v[176:179], v[32:35]
	v_mfma_f32_16x16x32_bf16 v[20:23], v[200:203], v[184:187], v[20:23]
	v_mfma_f32_16x16x32_bf16 v[16:19], v[208:211], v[184:187], v[16:19]
	v_mfma_f32_16x16x32_bf16 v[4:7], v[200:203], v[192:195], v[4:7]
	v_mfma_f32_16x16x32_bf16 v[0:3], v[208:211], v[192:195], v[0:3]
	v_mfma_f32_16x16x32_bf16 v[52:55], v[204:207], v[172:175], v[52:55]
	v_mfma_f32_16x16x32_bf16 v[48:51], v[212:215], v[172:175], v[48:51]
	v_mfma_f32_16x16x32_bf16 v[36:39], v[204:207], v[180:183], v[36:39]
	v_mfma_f32_16x16x32_bf16 v[32:35], v[212:215], v[180:183], v[32:35]
	v_mfma_f32_16x16x32_bf16 v[20:23], v[204:207], v[188:191], v[20:23]
	v_mfma_f32_16x16x32_bf16 v[16:19], v[212:215], v[188:191], v[16:19]
	v_mfma_f32_16x16x32_bf16 v[4:7], v[204:207], v[196:199], v[4:7]
	v_mfma_f32_16x16x32_bf16 v[0:3], v[212:215], v[196:199], v[0:3]
	s_add_i32 s61, s61, 2
	s_add_u32 s59, s59, 0x10000
	s_addc_u32 s60, s60, 0
	s_add_u32 s22, s22, 0x100
	s_addc_u32 s23, s23, 0
	s_cmp_gt_u32 s61, 29
	s_barrier
	s_cbranch_scc0 .LBB0_79
	s_cmp_eq_u32 s78, 0
	s_cbranch_scc0 .Lhalf_skip_x_0
	s_barrier

; #define PG8_STAGE(bufoff, gbase, voff) do { _Pragma("unroll") for (int _i = 0; _i < 2; ++_i) \
;         __builtin_amdgcn_global_load_lds((const unsigned*)((const char*)(gbase) + (voff)[_i]), (PG8_LAS unsigned*)(lds + (bufoff) + ldsw + _i * 8192), 16, 0, 0); } while (0)
; #define PG8_LDA(dst, b, h) do { _Pragma("unroll") for (int m = 0; m < 4; ++m) _Pragma("unroll") for (int k = 0; k < 2; ++k) dst[m][k] = *(const PG8_LAS bf16x8*)(lds + PG8_SA(b, h) + aoff + m * 2048 + k * 1024); } while (0)
; #define PG8_LDB(dst, b, h) do { _Pragma("unroll") for (int n = 0; n < 2; ++n) _Pragma("unroll") for (int k = 0; k < 2; ++k) dst[n][k] = *(const PG8_LAS bf16x8*)(lds + PG8_SB(b, h) + boff + n * 2048 + k * 1024); } while (0)
; #define PG8_MMA(ai, bj, At, Bt) do { __builtin_amdgcn_s_setprio(1); _Pragma("unroll") for (int m = 0; m < 4; ++m) _Pragma("unroll") for (int n = 0; n < 2; ++n) _Pragma("unroll") for (int k = 0; k < 2; ++k) \
;         acc[ai][bj][m][n] = __builtin_amdgcn_mfma_f32_16x16x32_bf16(Bt[n][k], At[m][k], acc[ai][bj][m][n], 0, 0, 0); __builtin_amdgcn_s_setprio(0); } while (0)
; #define PG8_WAIT_V(n) asm volatile("s_waitcnt vmcnt(" #n ")" ::: "memory")
; #define PG8_WAIT_L(n) asm volatile("s_waitcnt lgkmcnt(" #n ")" ::: "memory")
; template <class Epi, class Sched>
; __device__ __forceinline__ void gemm_phase(PG8_LAS unsigned char* lds, const Gemm g, const Sched& S, const Epi& E) {
;     ...
;             const bool last = (t == nt - 2);
;             const char* a1 = cA + (size_t)(t + 1) * kstep;
;             const char* a2 = last ? nA : cA + (size_t)(t + 2) * kstep; const char* b2 = last ? nB : cB + (size_t)(t + 2) * kstepB;
;             const char* a3 = a2 + kstep; const char* b3 = b2 + kstepB;
;             if (last && has_next) S.a_ready(nxt);
;             PG8_LDB(B0, 0, 0); PG8_SCHED; PG8_LDA(At, 0, 0); PG8_STAGE(PG8_SA(1, 1), a1 + hstep, voffA);
;             PG8_WAIT_L(8); PG8_BAR; PG8_WAIT_L(0); PG8_MMA(0, 0, At, B0); PG8_BAR; PG8_SCHED;
;             PG8_LDB(B1, 0, 1); PG8_STAGE(PG8_SB(0, 0), b2, voffB);
;             PG8_BAR; PG8_WAIT_L(0); PG8_MMA(0, 1, At, B1); PG8_BAR;
;             PG8_LDA(At, 0, 1); PG8_STAGE(PG8_SA(0, 0), a2, voffA);
;             PG8_BAR; PG8_WAIT_L(0); PG8_MMA(1, 0, At, B0); PG8_BAR; PG8_SCHED;
;             PG8_STAGE(PG8_SB(0, 1), b2 + hstepB, voffB);
;             PG8_WAIT_V(6); PG8_BAR; PG8_MMA(1, 1, At, B1); PG8_BAR;
.Lhalf_skip_y_1:
.LBB0_155:
	ds_read_b128 v[144:147], v153
	ds_read_b128 v[156:159], v153 offset:1024
	ds_read_b128 v[160:163], v153 offset:2048
	ds_read_b128 v[164:167], v153 offset:3072
	s_add_u32 s26, s24, 0x100
	s_addc_u32 s27, s25, 0
	s_cmpk_eq_i32 s67, 0x52
	s_cselect_b32 s31, s7, s27
	s_cselect_b32 s30, s6, s26
	s_cselect_b32 s29, s9, s66
	s_cselect_b32 s28, s8, s65
	v_lshl_add_u64 v[148:149], s[24:25], 0, v[136:137]
	s_add_i32 m0, s51, 0xc000
	ds_read_b128 v[168:171], v154
	ds_read_b128 v[172:175], v154 offset:1024
	ds_read_b128 v[176:179], v154 offset:2048
	ds_read_b128 v[180:183], v154 offset:3072
	ds_read_b128 v[184:187], v154 offset:4096
	ds_read_b128 v[188:191], v154 offset:5120
	ds_read_b128 v[192:195], v154 offset:6144
	ds_read_b128 v[196:199], v154 offset:7168
	global_load_lds_dwordx4 v[148:149], off
	v_lshl_add_u64 v[148:149], s[24:25], 0, v[138:139]
	s_add_i32 m0, s51, 0xe000
	s_nop 0
	global_load_lds_dwordx4 v[148:149], off
	s_add_i32 s24, s59, s50
	v_lshl_add_u64 v[148:149], s[28:29], 0, v[128:129]
	s_mov_b32 m0, s24
	ds_read_b128 v[200:203], v155
	ds_read_b128 v[204:207], v155 offset:1024
	ds_read_b128 v[208:211], v155 offset:2048
	ds_read_b128 v[212:215], v155 offset:3072
	s_waitcnt vmcnt(8)
	s_waitcnt lgkmcnt(0)
	s_barrier
	v_mfma_f32_16x16x32_bf16 v[124:127], v[144:147], v[168:171], v[124:127]
	v_mfma_f32_16x16x32_bf16 v[120:123], v[160:163], v[168:171], v[120:123]
	v_mfma_f32_16x16x32_bf16 v[108:111], v[144:147], v[176:179], v[108:111]
	v_mfma_f32_16x16x32_bf16 v[104:107], v[160:163], v[176:179], v[104:107]
	v_mfma_f32_16x16x32_bf16 v[92:95], v[144:147], v[184:187], v[92:95]
	v_mfma_f32_16x16x32_bf16 v[88:91], v[160:163], v[184:187], v[88:91]
	v_mfma_f32_16x16x32_bf16 v[76:79], v[144:147], v[192:195], v[76:79]
	v_mfma_f32_16x16x32_bf16 v[72:75], v[160:163], v[192:195], v[72:75]
	v_mfma_f32_16x16x32_bf16 v[124:127], v[156:159], v[172:175], v[124:127]
	v_mfma_f32_16x16x32_bf16 v[120:123], v[164:167], v[172:175], v[120:123]
	v_mfma_f32_16x16x32_bf16 v[108:111], v[156:159], v[180:183], v[108:111]
	v_mfma_f32_16x16x32_bf16 v[104:107], v[164:167], v[180:183], v[104:107]
	v_mfma_f32_16x16x32_bf16 v[92:95], v[156:159], v[188:191], v[92:95]
	v_mfma_f32_16x16x32_bf16 v[88:91], v[164:167], v[188:191], v[88:91]
	v_mfma_f32_16x16x32_bf16 v[76:79], v[156:159], v[196:199], v[76:79]
	v_mfma_f32_16x16x32_bf16 v[72:75], v[164:167], v[196:199], v[72:75]
	v_mfma_f32_16x16x32_bf16 v[116:119], v[200:203], v[168:171], v[116:119]
	v_mfma_f32_16x16x32_bf16 v[112:115], v[208:211], v[168:171], v[112:115]
	v_mfma_f32_16x16x32_bf16 v[100:103], v[200:203], v[176:179], v[100:103]
	v_mfma_f32_16x16x32_bf16 v[96:99], v[208:211], v[176:179], v[96:99]
	v_mfma_f32_16x16x32_bf16 v[84:87], v[200:203], v[184:187], v[84:87]
	v_mfma_f32_16x16x32_bf16 v[80:83], v[208:211], v[184:187], v[80:83]
	v_mfma_f32_16x16x32_bf16 v[68:71], v[200:203], v[192:195], v[68:71]
	v_mfma_f32_16x16x32_bf16 v[64:67], v[208:211], v[192:195], v[64:67]
	v_mfma_f32_16x16x32_bf16 v[116:119], v[204:207], v[172:175], v[116:119]
	v_mfma_f32_16x16x32_bf16 v[112:115], v[212:215], v[172:175], v[112:115]
	v_mfma_f32_16x16x32_bf16 v[100:103], v[204:207], v[180:183], v[100:103]
	v_mfma_f32_16x16x32_bf16 v[96:99], v[212:215], v[180:183], v[96:99]
	v_mfma_f32_16x16x32_bf16 v[84:87], v[204:207], v[188:191], v[84:87]
	v_mfma_f32_16x16x32_bf16 v[80:83], v[212:215], v[188:191], v[80:83]
	v_mfma_f32_16x16x32_bf16 v[68:71], v[204:207], v[196:199], v[68:71]
	v_mfma_f32_16x16x32_bf16 v[64:67], v[212:215], v[196:199], v[64:67]
	s_barrier
	global_load_lds_dwordx4 v[148:149], off
	v_lshl_add_u64 v[148:149], s[28:29], 0, v[132:133]
	s_add_i32 m0, s24, 0x2000
	s_nop 0
	global_load_lds_dwordx4 v[148:149], off
	s_mov_b32 m0, s51
	v_lshl_add_u64 v[148:149], s[30:31], 0, v[130:131]
	ds_read_b128 v[168:171], v154 offset:16384
	ds_read_b128 v[172:175], v154 offset:17408
	ds_read_b128 v[176:179], v154 offset:18432
	ds_read_b128 v[180:183], v154 offset:19456
	ds_read_b128 v[184:187], v154 offset:20480
	ds_read_b128 v[188:191], v154 offset:21504
	ds_read_b128 v[192:195], v154 offset:22528
	ds_read_b128 v[196:199], v154 offset:23552
	global_load_lds_dwordx4 v[148:149], off
	v_lshl_add_u64 v[216:217], s[30:31], 0, v[134:135]
	s_mov_b32 m0, s52
	s_nop 0
	global_load_lds_dwordx4 v[216:217], off
	s_add_u32 s24, s28, 0x4000
	s_addc_u32 s25, s29, 0
	s_add_i32 s68, s60, s50
	v_lshl_add_u64 v[250:251], s[24:25], 0, v[128:129]
	s_mov_b32 m0, s68
	s_nop 0
	global_load_lds_dwordx4 v[250:251], off
	v_lshl_add_u64 v[250:251], s[24:25], 0, v[132:133]
	s_add_i32 m0, s68, 0x2000
	s_nop 0
	global_load_lds_dwordx4 v[250:251], off
	s_waitcnt vmcnt(8)
	s_waitcnt lgkmcnt(0)
	s_barrier
; #define PG8_STAGE(bufoff, gbase, voff) do { _Pragma("unroll") for (int _i = 0; _i < 2; ++_i) \
;         __builtin_amdgcn_global_load_lds((const unsigned*)((const char*)(gbase) + (voff)[_i]), (PG8_LAS unsigned*)(lds + (bufoff) + ldsw + _i * 8192), 16, 0, 0); } while (0)
; #define PG8_LDA(dst, b, h) do { _Pragma("unroll") for (int m = 0; m < 4; ++m) _Pragma("unroll") for (int k = 0; k < 2; ++k) dst[m][k] = *(const PG8_LAS bf16x8*)(lds + PG8_SA(b, h) + aoff + m * 2048 + k * 1024); } while (0)
; #define PG8_LDB(dst, b, h) do { _Pragma("unroll") for (int n = 0; n < 2; ++n) _Pragma("unroll") for (int k = 0; k < 2; ++k) dst[n][k] = *(const PG8_LAS bf16x8*)(lds + PG8_SB(b, h) + boff + n * 2048 + k * 1024); } while (0)
; #define PG8_MMA(ai, bj, At, Bt) do { __builtin_amdgcn_s_setprio(1); _Pragma("unroll") for (int m = 0; m < 4; ++m) _Pragma("unroll") for (int n = 0; n < 2; ++n) _Pragma("unroll") for (int k = 0; k < 2; ++k) \
;         acc[ai][bj][m][n] = __builtin_amdgcn_mfma_f32_16x16x32_bf16(Bt[n][k], At[m][k], acc[ai][bj][m][n], 0, 0, 0); __builtin_amdgcn_s_setprio(0); } while (0)
; #define PG8_WAIT_V(n) asm volatile("s_waitcnt vmcnt(" #n ")" ::: "memory")
; #define PG8_WAIT_L(n) asm volatile("s_waitcnt lgkmcnt(" #n ")" ::: "memory")
; #define PG8_BAR __builtin_amdgcn_s_barrier()
; #define PG8_SCHED __builtin_amdgcn_sched_barrier(0)
; template <class Epi, class Sched>
; __device__ __forceinline__ void gemm_phase(PG8_LAS unsigned char* lds, const Gemm g, const Sched& S, const Epi& E) {
;     ...
;             PG8_BAR; PG8_WAIT_L(0); PG8_MMA(1, 0, At, B0); PG8_BAR; PG8_SCHED;
;             PG8_STAGE(PG8_SB(0, 1), b2 + hstepB, voffB);
;             PG8_WAIT_V(6); PG8_BAR; PG8_MMA(1, 1, At, B1); PG8_BAR;
;             PG8_LDB(B0, 1, 0); PG8_SCHED; PG8_LDA(At, 1, 0); PG8_STAGE(PG8_SA(0, 1), a2 + hstep, voffA);
;             PG8_WAIT_L(8); PG8_BAR; PG8_WAIT_L(0); PG8_MMA(0, 0, At, B0); PG8_BAR; PG8_SCHED;
;             PG8_LDB(B1, 1, 1); PG8_STAGE(PG8_SB(1, 0), b3, voffB);
;             PG8_BAR; PG8_WAIT_L(0); PG8_MMA(0, 1, At, B1); PG8_BAR;
	v_mfma_f32_16x16x32_bf16 v[60:63], v[144:147], v[168:171], v[60:63]
	v_mfma_f32_16x16x32_bf16 v[56:59], v[160:163], v[168:171], v[56:59]
	v_mfma_f32_16x16x32_bf16 v[44:47], v[144:147], v[176:179], v[44:47]
	v_mfma_f32_16x16x32_bf16 v[40:43], v[160:163], v[176:179], v[40:43]
	v_mfma_f32_16x16x32_bf16 v[28:31], v[144:147], v[184:187], v[28:31]
	v_mfma_f32_16x16x32_bf16 v[24:27], v[160:163], v[184:187], v[24:27]
	v_mfma_f32_16x16x32_bf16 v[12:15], v[144:147], v[192:195], v[12:15]
	v_mfma_f32_16x16x32_bf16 v[8:11], v[160:163], v[192:195], v[8:11]
	v_mfma_f32_16x16x32_bf16 v[60:63], v[156:159], v[172:175], v[60:63]
	v_mfma_f32_16x16x32_bf16 v[56:59], v[164:167], v[172:175], v[56:59]
	v_mfma_f32_16x16x32_bf16 v[44:47], v[156:159], v[180:183], v[44:47]
	v_mfma_f32_16x16x32_bf16 v[40:43], v[164:167], v[180:183], v[40:43]
	v_mfma_f32_16x16x32_bf16 v[28:31], v[156:159], v[188:191], v[28:31]
	v_mfma_f32_16x16x32_bf16 v[24:27], v[164:167], v[188:191], v[24:27]
	v_mfma_f32_16x16x32_bf16 v[12:15], v[156:159], v[196:199], v[12:15]
	v_mfma_f32_16x16x32_bf16 v[8:11], v[164:167], v[196:199], v[8:11]
	v_mfma_f32_16x16x32_bf16 v[52:55], v[200:203], v[168:171], v[52:55]
	v_mfma_f32_16x16x32_bf16 v[48:51], v[208:211], v[168:171], v[48:51]
	v_mfma_f32_16x16x32_bf16 v[36:39], v[200:203], v[176:179], v[36:39]
	v_mfma_f32_16x16x32_bf16 v[32:35], v[208:211], v[176:179], v[32:35]
	v_mfma_f32_16x16x32_bf16 v[20:23], v[200:203], v[184:187], v[20:23]
	v_mfma_f32_16x16x32_bf16 v[16:19], v[208:211], v[184:187], v[16:19]
	v_mfma_f32_16x16x32_bf16 v[4:7], v[200:203], v[192:195], v[4:7]
	v_mfma_f32_16x16x32_bf16 v[0:3], v[208:211], v[192:195], v[0:3]
	v_mfma_f32_16x16x32_bf16 v[52:55], v[204:207], v[172:175], v[52:55]
	v_mfma_f32_16x16x32_bf16 v[48:51], v[212:215], v[172:175], v[48:51]
	v_mfma_f32_16x16x32_bf16 v[36:39], v[204:207], v[180:183], v[36:39]
	v_mfma_f32_16x16x32_bf16 v[32:35], v[212:215], v[180:183], v[32:35]
	v_mfma_f32_16x16x32_bf16 v[20:23], v[204:207], v[188:191], v[20:23]
	v_mfma_f32_16x16x32_bf16 v[16:19], v[212:215], v[188:191], v[16:19]
	v_mfma_f32_16x16x32_bf16 v[4:7], v[204:207], v[196:199], v[4:7]
	v_mfma_f32_16x16x32_bf16 v[0:3], v[212:215], v[196:199], v[0:3]
	s_barrier
	s_add_i32 s68, 0, 0x18000
	v_add_u32_e32 v164, s68, v151
	ds_read_b128 v[144:147], v164
	ds_read_b128 v[156:159], v164 offset:1024
	ds_read_b128 v[160:163], v164 offset:2048
	ds_read_b128 v[164:167], v164 offset:3072
	s_add_u32 s24, s30, 0x158000
	s_addc_u32 s25, s31, 0
	s_mov_b32 m0, s53
	v_lshl_add_u64 v[200:201], s[24:25], 0, v[130:131]
	ds_read_b128 v[168:171], v154 offset:32768
	ds_read_b128 v[172:175], v154 offset:33792
	ds_read_b128 v[176:179], v154 offset:34816
	ds_read_b128 v[180:183], v154 offset:35840
	ds_read_b128 v[184:187], v154 offset:36864
	ds_read_b128 v[188:191], v154 offset:37888
	ds_read_b128 v[192:195], v154 offset:38912
	ds_read_b128 v[196:199], v154 offset:39936
	global_load_lds_dwordx4 v[200:201], off
	v_lshl_add_u64 v[200:201], s[24:25], 0, v[134:135]
	s_mov_b32 m0, s54
	s_nop 0
	global_load_lds_dwordx4 v[200:201], off
	s_add_i32 s30, 0, 0x1c000
	s_add_u32 s24, s28, 0x8000
	s_addc_u32 s25, s29, 0
	s_add_i32 s31, s68, s50
	v_add_u32_e32 v212, s30, v151
	v_lshl_add_u64 v[218:219], s[24:25], 0, v[128:129]
	s_mov_b32 m0, s31
	ds_read_b128 v[200:203], v212
	ds_read_b128 v[204:207], v212 offset:1024
	ds_read_b128 v[208:211], v212 offset:2048
	ds_read_b128 v[212:215], v212 offset:3072
	s_waitcnt vmcnt(8)
	s_waitcnt lgkmcnt(0)
	s_barrier
	v_mfma_f32_16x16x32_bf16 v[124:127], v[144:147], v[168:171], v[124:127]
	v_mfma_f32_16x16x32_bf16 v[120:123], v[160:163], v[168:171], v[120:123]
	v_mfma_f32_16x16x32_bf16 v[108:111], v[144:147], v[176:179], v[108:111]
	v_mfma_f32_16x16x32_bf16 v[104:107], v[160:163], v[176:179], v[104:107]
	v_mfma_f32_16x16x32_bf16 v[92:95], v[144:147], v[184:187], v[92:95]
	v_mfma_f32_16x16x32_bf16 v[88:91], v[160:163], v[184:187], v[88:91]
	v_mfma_f32_16x16x32_bf16 v[76:79], v[144:147], v[192:195], v[76:79]
	v_mfma_f32_16x16x32_bf16 v[72:75], v[160:163], v[192:195], v[72:75]
	v_mfma_f32_16x16x32_bf16 v[124:127], v[156:159], v[172:175], v[124:127]
	v_mfma_f32_16x16x32_bf16 v[120:123], v[164:167], v[172:175], v[120:123]
	v_mfma_f32_16x16x32_bf16 v[108:111], v[156:159], v[180:183], v[108:111]
	v_mfma_f32_16x16x32_bf16 v[104:107], v[164:167], v[180:183], v[104:107]
	v_mfma_f32_16x16x32_bf16 v[92:95], v[156:159], v[188:191], v[92:95]
	v_mfma_f32_16x16x32_bf16 v[88:91], v[164:167], v[188:191], v[88:91]
	v_mfma_f32_16x16x32_bf16 v[76:79], v[156:159], v[196:199], v[76:79]
	v_mfma_f32_16x16x32_bf16 v[72:75], v[164:167], v[196:199], v[72:75]
	v_mfma_f32_16x16x32_bf16 v[116:119], v[200:203], v[168:171], v[116:119]
	v_mfma_f32_16x16x32_bf16 v[112:115], v[208:211], v[168:171], v[112:115]
	v_mfma_f32_16x16x32_bf16 v[100:103], v[200:203], v[176:179], v[100:103]
	v_mfma_f32_16x16x32_bf16 v[96:99], v[208:211], v[176:179], v[96:99]
	v_mfma_f32_16x16x32_bf16 v[84:87], v[200:203], v[184:187], v[84:87]
	v_mfma_f32_16x16x32_bf16 v[80:83], v[208:211], v[184:187], v[80:83]
	v_mfma_f32_16x16x32_bf16 v[68:71], v[200:203], v[192:195], v[68:71]
	v_mfma_f32_16x16x32_bf16 v[64:67], v[208:211], v[192:195], v[64:67]
	v_mfma_f32_16x16x32_bf16 v[116:119], v[204:207], v[172:175], v[116:119]
	v_mfma_f32_16x16x32_bf16 v[112:115], v[212:215], v[172:175], v[112:115]
	v_mfma_f32_16x16x32_bf16 v[100:103], v[204:207], v[180:183], v[100:103]
	v_mfma_f32_16x16x32_bf16 v[96:99], v[212:215], v[180:183], v[96:99]
	v_mfma_f32_16x16x32_bf16 v[84:87], v[204:207], v[188:191], v[84:87]
	v_mfma_f32_16x16x32_bf16 v[80:83], v[212:215], v[188:191], v[80:83]
	v_mfma_f32_16x16x32_bf16 v[68:71], v[204:207], v[196:199], v[68:71]
	v_mfma_f32_16x16x32_bf16 v[64:67], v[212:215], v[196:199], v[64:67]
	s_barrier
; #define PG8_STAGE(bufoff, gbase, voff) do { _Pragma("unroll") for (int _i = 0; _i < 2; ++_i) \
;         __builtin_amdgcn_global_load_lds((const unsigned*)((const char*)(gbase) + (voff)[_i]), (PG8_LAS unsigned*)(lds + (bufoff) + ldsw + _i * 8192), 16, 0, 0); } while (0)
; #define PG8_LDA(dst, b, h) do { _Pragma("unroll") for (int m = 0; m < 4; ++m) _Pragma("unroll") for (int k = 0; k < 2; ++k) dst[m][k] = *(const PG8_LAS bf16x8*)(lds + PG8_SA(b, h) + aoff + m * 2048 + k * 1024); } while (0)
; #define PG8_LDB(dst, b, h) do { _Pragma("unroll") for (int n = 0; n < 2; ++n) _Pragma("unroll") for (int k = 0; k < 2; ++k) dst[n][k] = *(const PG8_LAS bf16x8*)(lds + PG8_SB(b, h) + boff + n * 2048 + k * 1024); } while (0)
; #define PG8_MMA(ai, bj, At, Bt) do { __builtin_amdgcn_s_setprio(1); _Pragma("unroll") for (int m = 0; m < 4; ++m) _Pragma("unroll") for (int n = 0; n < 2; ++n) _Pragma("unroll") for (int k = 0; k < 2; ++k) \
;         acc[ai][bj][m][n] = __builtin_amdgcn_mfma_f32_16x16x32_bf16(Bt[n][k], At[m][k], acc[ai][bj][m][n], 0, 0, 0); __builtin_amdgcn_s_setprio(0); } while (0)
; #define PG8_WAIT_V(n) asm volatile("s_waitcnt vmcnt(" #n ")" ::: "memory")
; #define PG8_WAIT_L(n) asm volatile("s_waitcnt lgkmcnt(" #n ")" ::: "memory")
; #define PG8_BAR __builtin_amdgcn_s_barrier()
; #define PG8_SCHED __builtin_amdgcn_sched_barrier(0)
; template <class Epi, class Sched>
; __device__ __forceinline__ void gemm_phase(PG8_LAS unsigned char* lds, const Gemm g, const Sched& S, const Epi& E) {
;     ...
;             PG8_LDB(B1, 1, 1); PG8_STAGE(PG8_SB(1, 0), b3, voffB);
;             PG8_BAR; PG8_WAIT_L(0); PG8_MMA(0, 1, At, B1); PG8_BAR;
;             PG8_LDA(At, 1, 1); PG8_STAGE(PG8_SA(1, 0), a3, voffA);
;             PG8_BAR; PG8_WAIT_L(0); PG8_MMA(1, 0, At, B0); PG8_BAR; PG8_SCHED;
;             PG8_STAGE(PG8_SB(1, 1), b3 + hstepB, voffB);
;             PG8_WAIT_V(6); PG8_BAR; PG8_MMA(1, 1, At, B1); PG8_BAR;
;         }
	global_load_lds_dwordx4 v[218:219], off
	v_lshl_add_u64 v[218:219], s[24:25], 0, v[132:133]
	s_add_i32 m0, s31, 0x2000
	s_nop 0
	global_load_lds_dwordx4 v[218:219], off
	s_mov_b32 m0, s56
	v_lshl_add_u64 v[148:149], v[148:149], 0, s[14:15]
	ds_read_b128 v[168:171], v154 offset:49152
	ds_read_b128 v[172:175], v154 offset:50176
	ds_read_b128 v[176:179], v154 offset:51200
	ds_read_b128 v[180:183], v154 offset:52224
	ds_read_b128 v[184:187], v154 offset:53248
	ds_read_b128 v[188:191], v154 offset:54272
	ds_read_b128 v[192:195], v154 offset:55296
	ds_read_b128 v[196:199], v154 offset:56320
	global_load_lds_dwordx4 v[148:149], off
	v_lshl_add_u64 v[148:149], v[216:217], 0, s[14:15]
	s_mov_b32 m0, s57
	s_nop 0
	global_load_lds_dwordx4 v[148:149], off
	s_add_u32 s24, s28, 0xc000
	s_addc_u32 s25, s29, 0
	s_add_i32 s28, s30, s50
	v_lshl_add_u64 v[252:253], s[24:25], 0, v[128:129]
	s_mov_b32 m0, s28
	s_nop 0
	global_load_lds_dwordx4 v[252:253], off
	v_lshl_add_u64 v[252:253], s[24:25], 0, v[132:133]
	s_add_i32 m0, s28, 0x2000
	s_nop 0
	global_load_lds_dwordx4 v[252:253], off
	s_waitcnt vmcnt(8)
	s_waitcnt lgkmcnt(0)
	s_barrier
	v_mfma_f32_16x16x32_bf16 v[60:63], v[144:147], v[168:171], v[60:63]
	v_mfma_f32_16x16x32_bf16 v[56:59], v[160:163], v[168:171], v[56:59]
	v_mfma_f32_16x16x32_bf16 v[44:47], v[144:147], v[176:179], v[44:47]
	v_mfma_f32_16x16x32_bf16 v[40:43], v[160:163], v[176:179], v[40:43]
	v_mfma_f32_16x16x32_bf16 v[28:31], v[144:147], v[184:187], v[28:31]
	v_mfma_f32_16x16x32_bf16 v[24:27], v[160:163], v[184:187], v[24:27]
	v_mfma_f32_16x16x32_bf16 v[12:15], v[144:147], v[192:195], v[12:15]
	v_mfma_f32_16x16x32_bf16 v[8:11], v[160:163], v[192:195], v[8:11]
	v_mfma_f32_16x16x32_bf16 v[60:63], v[156:159], v[172:175], v[60:63]
	v_mfma_f32_16x16x32_bf16 v[56:59], v[164:167], v[172:175], v[56:59]
	v_mfma_f32_16x16x32_bf16 v[44:47], v[156:159], v[180:183], v[44:47]
	v_mfma_f32_16x16x32_bf16 v[40:43], v[164:167], v[180:183], v[40:43]
	v_mfma_f32_16x16x32_bf16 v[28:31], v[156:159], v[188:191], v[28:31]
	v_mfma_f32_16x16x32_bf16 v[24:27], v[164:167], v[188:191], v[24:27]
	v_mfma_f32_16x16x32_bf16 v[12:15], v[156:159], v[196:199], v[12:15]
	v_mfma_f32_16x16x32_bf16 v[8:11], v[164:167], v[196:199], v[8:11]
	v_mfma_f32_16x16x32_bf16 v[52:55], v[200:203], v[168:171], v[52:55]
	v_mfma_f32_16x16x32_bf16 v[48:51], v[208:211], v[168:171], v[48:51]
	v_mfma_f32_16x16x32_bf16 v[36:39], v[200:203], v[176:179], v[36:39]
	v_mfma_f32_16x16x32_bf16 v[32:35], v[208:211], v[176:179], v[32:35]
	v_mfma_f32_16x16x32_bf16 v[20:23], v[200:203], v[184:187], v[20:23]
	v_mfma_f32_16x16x32_bf16 v[16:19], v[208:211], v[184:187], v[16:19]
	v_mfma_f32_16x16x32_bf16 v[4:7], v[200:203], v[192:195], v[4:7]
	v_mfma_f32_16x16x32_bf16 v[0:3], v[208:211], v[192:195], v[0:3]
	v_mfma_f32_16x16x32_bf16 v[52:55], v[204:207], v[172:175], v[52:55]
	v_mfma_f32_16x16x32_bf16 v[48:51], v[212:215], v[172:175], v[48:51]
	v_mfma_f32_16x16x32_bf16 v[36:39], v[204:207], v[180:183], v[36:39]
	v_mfma_f32_16x16x32_bf16 v[32:35], v[212:215], v[180:183], v[32:35]
	v_mfma_f32_16x16x32_bf16 v[20:23], v[204:207], v[188:191], v[20:23]
	v_mfma_f32_16x16x32_bf16 v[16:19], v[212:215], v[188:191], v[16:19]
	v_mfma_f32_16x16x32_bf16 v[4:7], v[204:207], v[196:199], v[4:7]
	v_mfma_f32_16x16x32_bf16 v[0:3], v[212:215], v[196:199], v[0:3]
	s_add_i32 s67, s67, 2
	s_add_u32 s65, s65, 0x10000
	s_addc_u32 s66, s66, 0
	s_cmpk_gt_u32 s67, 0x53
	s_mov_b64 s[24:25], s[26:27]
	s_barrier
	s_cbranch_scc0 .LBB0_155
	s_cmp_eq_u32 s78, 0
	s_cbranch_scc0 .Lhalf_skip_x_1
	s_barrier

; #define PG8_STAGE(bufoff, gbase, voff) do { _Pragma("unroll") for (int _i = 0; _i < 2; ++_i) \
;         __builtin_amdgcn_global_load_lds((const unsigned*)((const char*)(gbase) + (voff)[_i]), (PG8_LAS unsigned*)(lds + (bufoff) + ldsw + _i * 8192), 16, 0, 0); } while (0)
; #define PG8_LDA(dst, b, h) do { _Pragma("unroll") for (int m = 0; m < 4; ++m) _Pragma("unroll") for (int k = 0; k < 2; ++k) dst[m][k] = *(const PG8_LAS bf16x8*)(lds + PG8_SA(b, h) + aoff + m * 2048 + k * 1024); } while (0)
; #define PG8_LDB(dst, b, h) do { _Pragma("unroll") for (int n = 0; n < 2; ++n) _Pragma("unroll") for (int k = 0; k < 2; ++k) dst[n][k] = *(const PG8_LAS bf16x8*)(lds + PG8_SB(b, h) + boff + n * 2048 + k * 1024); } while (0)
; #define PG8_MMA(ai, bj, At, Bt) do { __builtin_amdgcn_s_setprio(1); _Pragma("unroll") for (int m = 0; m < 4; ++m) _Pragma("unroll") for (int n = 0; n < 2; ++n) _Pragma("unroll") for (int k = 0; k < 2; ++k) \
;         acc[ai][bj][m][n] = __builtin_amdgcn_mfma_f32_16x16x32_bf16(Bt[n][k], At[m][k], acc[ai][bj][m][n], 0, 0, 0); __builtin_amdgcn_s_setprio(0); } while (0)
; #define PG8_WAIT_V(n) asm volatile("s_waitcnt vmcnt(" #n ")" ::: "memory")
; template <class Epi, class Sched>
; __device__ __forceinline__ void gemm_phase(PG8_LAS unsigned char* lds, const Gemm g, const Sched& S, const Epi& E) {
;     ...
;         for (int t = 0; t < nt; t += 2) {
;             const bool last = (t == nt - 2);
;             const char* a1 = cA + (size_t)(t + 1) * kstep;
;             const char* a2 = last ? nA : cA + (size_t)(t + 2) * kstep; const char* b2 = last ? nB : cB + (size_t)(t + 2) * kstepB;
;             const char* a3 = a2 + kstep; const char* b3 = b2 + kstepB;
;             if (last && has_next) S.a_ready(nxt);
;             PG8_LDB(B0, 0, 0); PG8_SCHED; PG8_LDA(At, 0, 0); PG8_STAGE(PG8_SA(1, 1), a1 + hstep, voffA);
;             PG8_WAIT_L(8); PG8_BAR; PG8_WAIT_L(0); PG8_MMA(0, 0, At, B0); PG8_BAR; PG8_SCHED;
;             PG8_LDB(B1, 0, 1); PG8_STAGE(PG8_SB(0, 0), b2, voffB);
;             PG8_BAR; PG8_WAIT_L(0); PG8_MMA(0, 1, At, B1); PG8_BAR;
;             PG8_LDA(At, 0, 1); PG8_STAGE(PG8_SA(0, 0), a2, voffA);
;             PG8_BAR; PG8_WAIT_L(0); PG8_MMA(1, 0, At, B0); PG8_BAR; PG8_SCHED;
;             PG8_STAGE(PG8_SB(0, 1), b2 + hstepB, voffB);
;             PG8_WAIT_V(6); PG8_BAR; PG8_MMA(1, 1, At, B1); PG8_BAR;
.Lhalf_skip_y_2:
.LBB0_280:
	ds_read_b128 v[150:153], v147
	ds_read_b128 v[154:157], v147 offset:1024
	ds_read_b128 v[158:161], v147 offset:2048
	ds_read_b128 v[162:165], v147 offset:3072
	s_add_u32 s48, s6, 0xfff80080
	s_addc_u32 s49, s7, -1
	s_cmp_eq_u32 s69, 28
	s_cselect_b32 s51, s9, s49
	s_cselect_b32 s50, s29, s48
	s_cselect_b32 s49, s31, s68
	s_cselect_b32 s48, s47, s67
	v_lshl_add_u64 v[198:199], s[6:7], 0, v[136:137]
	s_add_i32 m0, s54, 0xc000
	ds_read_b128 v[166:169], v148
	ds_read_b128 v[170:173], v148 offset:1024
	ds_read_b128 v[174:177], v148 offset:2048
	ds_read_b128 v[178:181], v148 offset:3072
	ds_read_b128 v[182:185], v148 offset:4096
	ds_read_b128 v[186:189], v148 offset:5120
	ds_read_b128 v[190:193], v148 offset:6144
	ds_read_b128 v[194:197], v148 offset:7168
	global_load_lds_dwordx4 v[198:199], off
	v_lshl_add_u64 v[198:199], s[6:7], 0, v[138:139]
	s_add_i32 m0, s54, 0xe000
	s_nop 0
	global_load_lds_dwordx4 v[198:199], off
	s_add_i32 s70, s63, s53
	v_lshl_add_u64 v[214:215], s[48:49], 0, v[128:129]
	s_mov_b32 m0, s70
	ds_read_b128 v[198:201], v149
	ds_read_b128 v[202:205], v149 offset:1024
	ds_read_b128 v[206:209], v149 offset:2048
	ds_read_b128 v[210:213], v149 offset:3072
	s_waitcnt vmcnt(8)
	s_waitcnt lgkmcnt(0)
	s_barrier
	v_mfma_f32_16x16x32_bf16 v[124:127], v[150:153], v[166:169], v[124:127]
	v_mfma_f32_16x16x32_bf16 v[120:123], v[158:161], v[166:169], v[120:123]
	v_mfma_f32_16x16x32_bf16 v[108:111], v[150:153], v[174:177], v[108:111]
	v_mfma_f32_16x16x32_bf16 v[104:107], v[158:161], v[174:177], v[104:107]
	v_mfma_f32_16x16x32_bf16 v[92:95], v[150:153], v[182:185], v[92:95]
	v_mfma_f32_16x16x32_bf16 v[88:91], v[158:161], v[182:185], v[88:91]
	v_mfma_f32_16x16x32_bf16 v[76:79], v[150:153], v[190:193], v[76:79]
	v_mfma_f32_16x16x32_bf16 v[72:75], v[158:161], v[190:193], v[72:75]
	v_mfma_f32_16x16x32_bf16 v[124:127], v[154:157], v[170:173], v[124:127]
	v_mfma_f32_16x16x32_bf16 v[120:123], v[162:165], v[170:173], v[120:123]
	v_mfma_f32_16x16x32_bf16 v[108:111], v[154:157], v[178:181], v[108:111]
	v_mfma_f32_16x16x32_bf16 v[104:107], v[162:165], v[178:181], v[104:107]
	v_mfma_f32_16x16x32_bf16 v[92:95], v[154:157], v[186:189], v[92:95]
	v_mfma_f32_16x16x32_bf16 v[88:91], v[162:165], v[186:189], v[88:91]
	v_mfma_f32_16x16x32_bf16 v[76:79], v[154:157], v[194:197], v[76:79]
	v_mfma_f32_16x16x32_bf16 v[72:75], v[162:165], v[194:197], v[72:75]
	v_mfma_f32_16x16x32_bf16 v[116:119], v[198:201], v[166:169], v[116:119]
	v_mfma_f32_16x16x32_bf16 v[112:115], v[206:209], v[166:169], v[112:115]
	v_mfma_f32_16x16x32_bf16 v[100:103], v[198:201], v[174:177], v[100:103]
	v_mfma_f32_16x16x32_bf16 v[96:99], v[206:209], v[174:177], v[96:99]
	v_mfma_f32_16x16x32_bf16 v[84:87], v[198:201], v[182:185], v[84:87]
	v_mfma_f32_16x16x32_bf16 v[80:83], v[206:209], v[182:185], v[80:83]
	v_mfma_f32_16x16x32_bf16 v[68:71], v[198:201], v[190:193], v[68:71]
	v_mfma_f32_16x16x32_bf16 v[64:67], v[206:209], v[190:193], v[64:67]
	v_mfma_f32_16x16x32_bf16 v[116:119], v[202:205], v[170:173], v[116:119]
	v_mfma_f32_16x16x32_bf16 v[112:115], v[210:213], v[170:173], v[112:115]
	v_mfma_f32_16x16x32_bf16 v[100:103], v[202:205], v[178:181], v[100:103]
	v_mfma_f32_16x16x32_bf16 v[96:99], v[210:213], v[178:181], v[96:99]
	v_mfma_f32_16x16x32_bf16 v[84:87], v[202:205], v[186:189], v[84:87]
	v_mfma_f32_16x16x32_bf16 v[80:83], v[210:213], v[186:189], v[80:83]
	v_mfma_f32_16x16x32_bf16 v[68:71], v[202:205], v[194:197], v[68:71]
	v_mfma_f32_16x16x32_bf16 v[64:67], v[210:213], v[194:197], v[64:67]
	s_barrier
	global_load_lds_dwordx4 v[214:215], off
	v_lshl_add_u64 v[214:215], s[48:49], 0, v[132:133]
	s_add_i32 m0, s70, 0x2000
	s_nop 0
	global_load_lds_dwordx4 v[214:215], off
	s_mov_b32 m0, s54
	v_lshl_add_u64 v[214:215], s[50:51], 0, v[130:131]
	ds_read_b128 v[166:169], v148 offset:16384
	ds_read_b128 v[170:173], v148 offset:17408
	ds_read_b128 v[174:177], v148 offset:18432
	ds_read_b128 v[178:181], v148 offset:19456
	ds_read_b128 v[182:185], v148 offset:20480
	ds_read_b128 v[186:189], v148 offset:21504
	ds_read_b128 v[190:193], v148 offset:22528
	ds_read_b128 v[194:197], v148 offset:23552
	global_load_lds_dwordx4 v[214:215], off
	v_lshl_add_u64 v[216:217], s[50:51], 0, v[134:135]
	s_mov_b32 m0, s55
	s_nop 0
	global_load_lds_dwordx4 v[216:217], off
	s_add_u32 s70, s48, 0x4000
	s_addc_u32 s71, s49, 0
	s_add_i32 s72, s64, s53
	v_lshl_add_u64 v[250:251], s[70:71], 0, v[128:129]
	s_mov_b32 m0, s72
	s_nop 0
	global_load_lds_dwordx4 v[250:251], off
	v_lshl_add_u64 v[250:251], s[70:71], 0, v[132:133]
	s_add_i32 m0, s72, 0x2000
	s_nop 0
	global_load_lds_dwordx4 v[250:251], off
	s_waitcnt vmcnt(8)
	s_waitcnt lgkmcnt(0)
	s_barrier
; #define PG8_STAGE(bufoff, gbase, voff) do { _Pragma("unroll") for (int _i = 0; _i < 2; ++_i) \
;         __builtin_amdgcn_global_load_lds((const unsigned*)((const char*)(gbase) + (voff)[_i]), (PG8_LAS unsigned*)(lds + (bufoff) + ldsw + _i * 8192), 16, 0, 0); } while (0)
; #define PG8_LDA(dst, b, h) do { _Pragma("unroll") for (int m = 0; m < 4; ++m) _Pragma("unroll") for (int k = 0; k < 2; ++k) dst[m][k] = *(const PG8_LAS bf16x8*)(lds + PG8_SA(b, h) + aoff + m * 2048 + k * 1024); } while (0)
; #define PG8_LDB(dst, b, h) do { _Pragma("unroll") for (int n = 0; n < 2; ++n) _Pragma("unroll") for (int k = 0; k < 2; ++k) dst[n][k] = *(const PG8_LAS bf16x8*)(lds + PG8_SB(b, h) + boff + n * 2048 + k * 1024); } while (0)
; #define PG8_MMA(ai, bj, At, Bt) do { __builtin_amdgcn_s_setprio(1); _Pragma("unroll") for (int m = 0; m < 4; ++m) _Pragma("unroll") for (int n = 0; n < 2; ++n) _Pragma("unroll") for (int k = 0; k < 2; ++k) \
;         acc[ai][bj][m][n] = __builtin_amdgcn_mfma_f32_16x16x32_bf16(Bt[n][k], At[m][k], acc[ai][bj][m][n], 0, 0, 0); __builtin_amdgcn_s_setprio(0); } while (0)
; #define PG8_WAIT_V(n) asm volatile("s_waitcnt vmcnt(" #n ")" ::: "memory")
; #define PG8_WAIT_L(n) asm volatile("s_waitcnt lgkmcnt(" #n ")" ::: "memory")
; #define PG8_BAR __builtin_amdgcn_s_barrier()
; #define PG8_SCHED __builtin_amdgcn_sched_barrier(0)
; template <class Epi, class Sched>
; __device__ __forceinline__ void gemm_phase(PG8_LAS unsigned char* lds, const Gemm g, const Sched& S, const Epi& E) {
;     ...
;             PG8_BAR; PG8_WAIT_L(0); PG8_MMA(1, 0, At, B0); PG8_BAR; PG8_SCHED;
;             PG8_STAGE(PG8_SB(0, 1), b2 + hstepB, voffB);
;             PG8_WAIT_V(6); PG8_BAR; PG8_MMA(1, 1, At, B1); PG8_BAR;
;             PG8_LDB(B0, 1, 0); PG8_SCHED; PG8_LDA(At, 1, 0); PG8_STAGE(PG8_SA(0, 1), a2 + hstep, voffA);
;             PG8_WAIT_L(8); PG8_BAR; PG8_WAIT_L(0); PG8_MMA(0, 0, At, B0); PG8_BAR; PG8_SCHED;
;             PG8_LDB(B1, 1, 1); PG8_STAGE(PG8_SB(1, 0), b3, voffB);
;             PG8_BAR; PG8_WAIT_L(0); PG8_MMA(0, 1, At, B1); PG8_BAR;
	v_mfma_f32_16x16x32_bf16 v[60:63], v[150:153], v[166:169], v[60:63]
	v_mfma_f32_16x16x32_bf16 v[56:59], v[158:161], v[166:169], v[56:59]
	v_mfma_f32_16x16x32_bf16 v[44:47], v[150:153], v[174:177], v[44:47]
	v_mfma_f32_16x16x32_bf16 v[40:43], v[158:161], v[174:177], v[40:43]
	v_mfma_f32_16x16x32_bf16 v[28:31], v[150:153], v[182:185], v[28:31]
	v_mfma_f32_16x16x32_bf16 v[24:27], v[158:161], v[182:185], v[24:27]
	v_mfma_f32_16x16x32_bf16 v[12:15], v[150:153], v[190:193], v[12:15]
	v_mfma_f32_16x16x32_bf16 v[8:11], v[158:161], v[190:193], v[8:11]
	v_mfma_f32_16x16x32_bf16 v[60:63], v[154:157], v[170:173], v[60:63]
	v_mfma_f32_16x16x32_bf16 v[56:59], v[162:165], v[170:173], v[56:59]
	v_mfma_f32_16x16x32_bf16 v[44:47], v[154:157], v[178:181], v[44:47]
	v_mfma_f32_16x16x32_bf16 v[40:43], v[162:165], v[178:181], v[40:43]
	v_mfma_f32_16x16x32_bf16 v[28:31], v[154:157], v[186:189], v[28:31]
	v_mfma_f32_16x16x32_bf16 v[24:27], v[162:165], v[186:189], v[24:27]
	v_mfma_f32_16x16x32_bf16 v[12:15], v[154:157], v[194:197], v[12:15]
	v_mfma_f32_16x16x32_bf16 v[8:11], v[162:165], v[194:197], v[8:11]
	v_mfma_f32_16x16x32_bf16 v[52:55], v[198:201], v[166:169], v[52:55]
	v_mfma_f32_16x16x32_bf16 v[48:51], v[206:209], v[166:169], v[48:51]
	v_mfma_f32_16x16x32_bf16 v[36:39], v[198:201], v[174:177], v[36:39]
	v_mfma_f32_16x16x32_bf16 v[32:35], v[206:209], v[174:177], v[32:35]
	v_mfma_f32_16x16x32_bf16 v[20:23], v[198:201], v[182:185], v[20:23]
	v_mfma_f32_16x16x32_bf16 v[16:19], v[206:209], v[182:185], v[16:19]
	v_mfma_f32_16x16x32_bf16 v[4:7], v[198:201], v[190:193], v[4:7]
	v_mfma_f32_16x16x32_bf16 v[0:3], v[206:209], v[190:193], v[0:3]
	v_mfma_f32_16x16x32_bf16 v[52:55], v[202:205], v[170:173], v[52:55]
	v_mfma_f32_16x16x32_bf16 v[48:51], v[210:213], v[170:173], v[48:51]
	v_mfma_f32_16x16x32_bf16 v[36:39], v[202:205], v[178:181], v[36:39]
	v_mfma_f32_16x16x32_bf16 v[32:35], v[210:213], v[178:181], v[32:35]
	v_mfma_f32_16x16x32_bf16 v[20:23], v[202:205], v[186:189], v[20:23]
	v_mfma_f32_16x16x32_bf16 v[16:19], v[210:213], v[186:189], v[16:19]
	v_mfma_f32_16x16x32_bf16 v[4:7], v[202:205], v[194:197], v[4:7]
	v_mfma_f32_16x16x32_bf16 v[0:3], v[210:213], v[194:197], v[0:3]
	s_barrier
	s_add_i32 s70, 0, 0x18000
	v_add_u32_e32 v162, s70, v145
	ds_read_b128 v[150:153], v162
	ds_read_b128 v[154:157], v162 offset:1024
	ds_read_b128 v[158:161], v162 offset:2048
	ds_read_b128 v[162:165], v162 offset:3072
	s_add_u32 s50, s50, 0x80000
	s_addc_u32 s51, s51, 0
	s_mov_b32 m0, s56
	v_lshl_add_u64 v[198:199], s[50:51], 0, v[130:131]
	ds_read_b128 v[166:169], v148 offset:32768
	ds_read_b128 v[170:173], v148 offset:33792
	ds_read_b128 v[174:177], v148 offset:34816
	ds_read_b128 v[178:181], v148 offset:35840
	ds_read_b128 v[182:185], v148 offset:36864
	ds_read_b128 v[186:189], v148 offset:37888
	ds_read_b128 v[190:193], v148 offset:38912
	ds_read_b128 v[194:197], v148 offset:39936
	global_load_lds_dwordx4 v[198:199], off
	v_lshl_add_u64 v[198:199], s[50:51], 0, v[134:135]
	s_mov_b32 m0, s57
	s_nop 0
	global_load_lds_dwordx4 v[198:199], off
	s_add_i32 s71, 0, 0x1c000
	s_add_u32 s50, s48, 0x8000
	s_addc_u32 s51, s49, 0
	s_add_i32 s70, s70, s53
	v_add_u32_e32 v210, s71, v145
	v_lshl_add_u64 v[218:219], s[50:51], 0, v[128:129]
	s_mov_b32 m0, s70
	ds_read_b128 v[198:201], v210
	ds_read_b128 v[202:205], v210 offset:1024
	ds_read_b128 v[206:209], v210 offset:2048
	ds_read_b128 v[210:213], v210 offset:3072
	s_waitcnt vmcnt(8)
	s_waitcnt lgkmcnt(0)
	s_barrier
	v_mfma_f32_16x16x32_bf16 v[124:127], v[150:153], v[166:169], v[124:127]
	v_mfma_f32_16x16x32_bf16 v[120:123], v[158:161], v[166:169], v[120:123]
	v_mfma_f32_16x16x32_bf16 v[108:111], v[150:153], v[174:177], v[108:111]
	v_mfma_f32_16x16x32_bf16 v[104:107], v[158:161], v[174:177], v[104:107]
	v_mfma_f32_16x16x32_bf16 v[92:95], v[150:153], v[182:185], v[92:95]
	v_mfma_f32_16x16x32_bf16 v[88:91], v[158:161], v[182:185], v[88:91]
	v_mfma_f32_16x16x32_bf16 v[76:79], v[150:153], v[190:193], v[76:79]
	v_mfma_f32_16x16x32_bf16 v[72:75], v[158:161], v[190:193], v[72:75]
	v_mfma_f32_16x16x32_bf16 v[124:127], v[154:157], v[170:173], v[124:127]
	v_mfma_f32_16x16x32_bf16 v[120:123], v[162:165], v[170:173], v[120:123]
	v_mfma_f32_16x16x32_bf16 v[108:111], v[154:157], v[178:181], v[108:111]
	v_mfma_f32_16x16x32_bf16 v[104:107], v[162:165], v[178:181], v[104:107]
	v_mfma_f32_16x16x32_bf16 v[92:95], v[154:157], v[186:189], v[92:95]
	v_mfma_f32_16x16x32_bf16 v[88:91], v[162:165], v[186:189], v[88:91]
	v_mfma_f32_16x16x32_bf16 v[76:79], v[154:157], v[194:197], v[76:79]
	v_mfma_f32_16x16x32_bf16 v[72:75], v[162:165], v[194:197], v[72:75]
	v_mfma_f32_16x16x32_bf16 v[116:119], v[198:201], v[166:169], v[116:119]
	v_mfma_f32_16x16x32_bf16 v[112:115], v[206:209], v[166:169], v[112:115]
	v_mfma_f32_16x16x32_bf16 v[100:103], v[198:201], v[174:177], v[100:103]
	v_mfma_f32_16x16x32_bf16 v[96:99], v[206:209], v[174:177], v[96:99]
	v_mfma_f32_16x16x32_bf16 v[84:87], v[198:201], v[182:185], v[84:87]
	v_mfma_f32_16x16x32_bf16 v[80:83], v[206:209], v[182:185], v[80:83]
	v_mfma_f32_16x16x32_bf16 v[68:71], v[198:201], v[190:193], v[68:71]
	v_mfma_f32_16x16x32_bf16 v[64:67], v[206:209], v[190:193], v[64:67]
	v_mfma_f32_16x16x32_bf16 v[116:119], v[202:205], v[170:173], v[116:119]
	v_mfma_f32_16x16x32_bf16 v[112:115], v[210:213], v[170:173], v[112:115]
	v_mfma_f32_16x16x32_bf16 v[100:103], v[202:205], v[178:181], v[100:103]
	v_mfma_f32_16x16x32_bf16 v[96:99], v[210:213], v[178:181], v[96:99]
	v_mfma_f32_16x16x32_bf16 v[84:87], v[202:205], v[186:189], v[84:87]
	v_mfma_f32_16x16x32_bf16 v[80:83], v[210:213], v[186:189], v[80:83]
	v_mfma_f32_16x16x32_bf16 v[68:71], v[202:205], v[194:197], v[68:71]
	v_mfma_f32_16x16x32_bf16 v[64:67], v[210:213], v[194:197], v[64:67]
	s_barrier
; #define PG8_STAGE(bufoff, gbase, voff) do { _Pragma("unroll") for (int _i = 0; _i < 2; ++_i) \
;         __builtin_amdgcn_global_load_lds((const unsigned*)((const char*)(gbase) + (voff)[_i]), (PG8_LAS unsigned*)(lds + (bufoff) + ldsw + _i * 8192), 16, 0, 0); } while (0)
; #define PG8_LDA(dst, b, h) do { _Pragma("unroll") for (int m = 0; m < 4; ++m) _Pragma("unroll") for (int k = 0; k < 2; ++k) dst[m][k] = *(const PG8_LAS bf16x8*)(lds + PG8_SA(b, h) + aoff + m * 2048 + k * 1024); } while (0)
; #define PG8_LDB(dst, b, h) do { _Pragma("unroll") for (int n = 0; n < 2; ++n) _Pragma("unroll") for (int k = 0; k < 2; ++k) dst[n][k] = *(const PG8_LAS bf16x8*)(lds + PG8_SB(b, h) + boff + n * 2048 + k * 1024); } while (0)
; #define PG8_MMA(ai, bj, At, Bt) do { __builtin_amdgcn_s_setprio(1); _Pragma("unroll") for (int m = 0; m < 4; ++m) _Pragma("unroll") for (int n = 0; n < 2; ++n) _Pragma("unroll") for (int k = 0; k < 2; ++k) \
;         acc[ai][bj][m][n] = __builtin_amdgcn_mfma_f32_16x16x32_bf16(Bt[n][k], At[m][k], acc[ai][bj][m][n], 0, 0, 0); __builtin_amdgcn_s_setprio(0); } while (0)
; #define PG8_WAIT_V(n) asm volatile("s_waitcnt vmcnt(" #n ")" ::: "memory")
; #define PG8_WAIT_L(n) asm volatile("s_waitcnt lgkmcnt(" #n ")" ::: "memory")
; #define PG8_BAR __builtin_amdgcn_s_barrier()
; #define PG8_SCHED __builtin_amdgcn_sched_barrier(0)
; template <class Epi, class Sched>
; __device__ __forceinline__ void gemm_phase(PG8_LAS unsigned char* lds, const Gemm g, const Sched& S, const Epi& E) {
;     ...
;             PG8_LDB(B1, 1, 1); PG8_STAGE(PG8_SB(1, 0), b3, voffB);
;             PG8_BAR; PG8_WAIT_L(0); PG8_MMA(0, 1, At, B1); PG8_BAR;
;             PG8_LDA(At, 1, 1); PG8_STAGE(PG8_SA(1, 0), a3, voffA);
;             PG8_BAR; PG8_WAIT_L(0); PG8_MMA(1, 0, At, B0); PG8_BAR; PG8_SCHED;
;             PG8_STAGE(PG8_SB(1, 1), b3 + hstepB, voffB);
;             PG8_WAIT_V(6); PG8_BAR; PG8_MMA(1, 1, At, B1); PG8_BAR;
;         }
	global_load_lds_dwordx4 v[218:219], off
	v_lshl_add_u64 v[218:219], s[50:51], 0, v[132:133]
	s_add_i32 m0, s70, 0x2000
	s_nop 0
	global_load_lds_dwordx4 v[218:219], off
	s_mov_b32 m0, s59
	v_lshl_add_u64 v[214:215], v[214:215], 0, s[12:13]
	ds_read_b128 v[166:169], v148 offset:49152
	ds_read_b128 v[170:173], v148 offset:50176
	ds_read_b128 v[174:177], v148 offset:51200
	ds_read_b128 v[178:181], v148 offset:52224
	ds_read_b128 v[182:185], v148 offset:53248
	ds_read_b128 v[186:189], v148 offset:54272
	ds_read_b128 v[190:193], v148 offset:55296
	ds_read_b128 v[194:197], v148 offset:56320
	global_load_lds_dwordx4 v[214:215], off
	v_lshl_add_u64 v[214:215], v[216:217], 0, s[12:13]
	s_mov_b32 m0, s60
	s_nop 0
	global_load_lds_dwordx4 v[214:215], off
	s_add_u32 s48, s48, 0xc000
	s_addc_u32 s49, s49, 0
	s_add_i32 s50, s71, s53
	v_lshl_add_u64 v[252:253], s[48:49], 0, v[128:129]
	s_mov_b32 m0, s50
	s_nop 0
	global_load_lds_dwordx4 v[252:253], off
	v_lshl_add_u64 v[252:253], s[48:49], 0, v[132:133]
	s_add_i32 m0, s50, 0x2000
	s_nop 0
	global_load_lds_dwordx4 v[252:253], off
	s_waitcnt vmcnt(8)
	s_waitcnt lgkmcnt(0)
	s_barrier
	v_mfma_f32_16x16x32_bf16 v[60:63], v[150:153], v[166:169], v[60:63]
	v_mfma_f32_16x16x32_bf16 v[56:59], v[158:161], v[166:169], v[56:59]
	v_mfma_f32_16x16x32_bf16 v[44:47], v[150:153], v[174:177], v[44:47]
	v_mfma_f32_16x16x32_bf16 v[40:43], v[158:161], v[174:177], v[40:43]
	v_mfma_f32_16x16x32_bf16 v[28:31], v[150:153], v[182:185], v[28:31]
	v_mfma_f32_16x16x32_bf16 v[24:27], v[158:161], v[182:185], v[24:27]
	v_mfma_f32_16x16x32_bf16 v[12:15], v[150:153], v[190:193], v[12:15]
	v_mfma_f32_16x16x32_bf16 v[8:11], v[158:161], v[190:193], v[8:11]
	v_mfma_f32_16x16x32_bf16 v[60:63], v[154:157], v[170:173], v[60:63]
	v_mfma_f32_16x16x32_bf16 v[56:59], v[162:165], v[170:173], v[56:59]
	v_mfma_f32_16x16x32_bf16 v[44:47], v[154:157], v[178:181], v[44:47]
	v_mfma_f32_16x16x32_bf16 v[40:43], v[162:165], v[178:181], v[40:43]
	v_mfma_f32_16x16x32_bf16 v[28:31], v[154:157], v[186:189], v[28:31]
	v_mfma_f32_16x16x32_bf16 v[24:27], v[162:165], v[186:189], v[24:27]
	v_mfma_f32_16x16x32_bf16 v[12:15], v[154:157], v[194:197], v[12:15]
	v_mfma_f32_16x16x32_bf16 v[8:11], v[162:165], v[194:197], v[8:11]
	v_mfma_f32_16x16x32_bf16 v[52:55], v[198:201], v[166:169], v[52:55]
	v_mfma_f32_16x16x32_bf16 v[48:51], v[206:209], v[166:169], v[48:51]
	v_mfma_f32_16x16x32_bf16 v[36:39], v[198:201], v[174:177], v[36:39]
	v_mfma_f32_16x16x32_bf16 v[32:35], v[206:209], v[174:177], v[32:35]
	v_mfma_f32_16x16x32_bf16 v[20:23], v[198:201], v[182:185], v[20:23]
	v_mfma_f32_16x16x32_bf16 v[16:19], v[206:209], v[182:185], v[16:19]
	v_mfma_f32_16x16x32_bf16 v[4:7], v[198:201], v[190:193], v[4:7]
	v_mfma_f32_16x16x32_bf16 v[0:3], v[206:209], v[190:193], v[0:3]
	v_mfma_f32_16x16x32_bf16 v[52:55], v[202:205], v[170:173], v[52:55]
	v_mfma_f32_16x16x32_bf16 v[48:51], v[210:213], v[170:173], v[48:51]
	v_mfma_f32_16x16x32_bf16 v[36:39], v[202:205], v[178:181], v[36:39]
	v_mfma_f32_16x16x32_bf16 v[32:35], v[210:213], v[178:181], v[32:35]
	v_mfma_f32_16x16x32_bf16 v[20:23], v[202:205], v[186:189], v[20:23]
	v_mfma_f32_16x16x32_bf16 v[16:19], v[210:213], v[186:189], v[16:19]
	v_mfma_f32_16x16x32_bf16 v[4:7], v[202:205], v[194:197], v[4:7]
	v_mfma_f32_16x16x32_bf16 v[0:3], v[210:213], v[194:197], v[0:3]
	s_add_i32 s69, s69, 2
	s_add_u32 s67, s67, 0x10000
	s_addc_u32 s68, s68, 0
	s_add_u32 s6, s6, 0x100
	s_addc_u32 s7, s7, 0
	s_cmp_gt_u32 s69, 29
	s_barrier
	s_cbranch_scc0 .LBB0_280
	s_cmp_eq_u32 s78, 0
	s_cbranch_scc0 .Lhalf_skip_x_2
	s_barrier

; #define PG8_STAGE(bufoff, gbase, voff) do { _Pragma("unroll") for (int _i = 0; _i < 2; ++_i) \
;         __builtin_amdgcn_global_load_lds((const unsigned*)((const char*)(gbase) + (voff)[_i]), (PG8_LAS unsigned*)(lds + (bufoff) + ldsw + _i * 8192), 16, 0, 0); } while (0)
; #define PG8_LDA(dst, b, h) do { _Pragma("unroll") for (int m = 0; m < 4; ++m) _Pragma("unroll") for (int k = 0; k < 2; ++k) dst[m][k] = *(const PG8_LAS bf16x8*)(lds + PG8_SA(b, h) + aoff + m * 2048 + k * 1024); } while (0)
; #define PG8_LDB(dst, b, h) do { _Pragma("unroll") for (int n = 0; n < 2; ++n) _Pragma("unroll") for (int k = 0; k < 2; ++k) dst[n][k] = *(const PG8_LAS bf16x8*)(lds + PG8_SB(b, h) + boff + n * 2048 + k * 1024); } while (0)
; #define PG8_MMA(ai, bj, At, Bt) do { __builtin_amdgcn_s_setprio(1); _Pragma("unroll") for (int m = 0; m < 4; ++m) _Pragma("unroll") for (int n = 0; n < 2; ++n) _Pragma("unroll") for (int k = 0; k < 2; ++k) \
;         acc[ai][bj][m][n] = __builtin_amdgcn_mfma_f32_16x16x32_bf16(Bt[n][k], At[m][k], acc[ai][bj][m][n], 0, 0, 0); __builtin_amdgcn_s_setprio(0); } while (0)
; #define PG8_WAIT_V(n) asm volatile("s_waitcnt vmcnt(" #n ")" ::: "memory")
; template <class Epi, class Sched>
; __device__ __forceinline__ void gemm_phase(PG8_LAS unsigned char* lds, const Gemm g, const Sched& S, const Epi& E) {
;     ...
;         for (int t = 0; t < nt; t += 2) {
;             const bool last = (t == nt - 2);
;             const char* a1 = cA + (size_t)(t + 1) * kstep;
;             const char* a2 = last ? nA : cA + (size_t)(t + 2) * kstep; const char* b2 = last ? nB : cB + (size_t)(t + 2) * kstepB;
;             const char* a3 = a2 + kstep; const char* b3 = b2 + kstepB;
;             if (last && has_next) S.a_ready(nxt);
;             PG8_LDB(B0, 0, 0); PG8_SCHED; PG8_LDA(At, 0, 0); PG8_STAGE(PG8_SA(1, 1), a1 + hstep, voffA);
;             PG8_WAIT_L(8); PG8_BAR; PG8_WAIT_L(0); PG8_MMA(0, 0, At, B0); PG8_BAR; PG8_SCHED;
;             PG8_LDB(B1, 0, 1); PG8_STAGE(PG8_SB(0, 0), b2, voffB);
;             PG8_BAR; PG8_WAIT_L(0); PG8_MMA(0, 1, At, B1); PG8_BAR;
;             PG8_LDA(At, 0, 1); PG8_STAGE(PG8_SA(0, 0), a2, voffA);
;             PG8_BAR; PG8_WAIT_L(0); PG8_MMA(1, 0, At, B0); PG8_BAR; PG8_SCHED;
;             PG8_STAGE(PG8_SB(0, 1), b2 + hstepB, voffB);
;             PG8_WAIT_V(6); PG8_BAR; PG8_MMA(1, 1, At, B1); PG8_BAR;
.Lhalf_skip_y_3:
.LBB0_397:
	ds_read_b128 v[142:145], v150
	ds_read_b128 v[154:157], v150 offset:1024
	ds_read_b128 v[158:161], v150 offset:2048
	ds_read_b128 v[162:165], v150 offset:3072
	s_add_u32 s26, s24, 0xfff80080
	s_addc_u32 s27, s25, -1
	s_cmp_eq_u32 s66, 28
	s_cselect_b32 s29, s5, s27
	s_cselect_b32 s28, s15, s26
	s_cselect_b32 s27, s17, s65
	s_cselect_b32 s26, s23, s64
	v_lshl_add_u64 v[198:199], s[24:25], 0, v[138:139]
	s_add_i32 m0, s48, 0xc000
	ds_read_b128 v[166:169], v151
	ds_read_b128 v[170:173], v151 offset:1024
	ds_read_b128 v[174:177], v151 offset:2048
	ds_read_b128 v[178:181], v151 offset:3072
	ds_read_b128 v[182:185], v151 offset:4096
	ds_read_b128 v[186:189], v151 offset:5120
	ds_read_b128 v[190:193], v151 offset:6144
	ds_read_b128 v[194:197], v151 offset:7168
	global_load_lds_dwordx4 v[198:199], off
	v_lshl_add_u64 v[198:199], s[24:25], 0, v[140:141]
	s_add_i32 m0, s48, 0xe000
	s_nop 0
	global_load_lds_dwordx4 v[198:199], off
	s_add_i32 s67, s59, s39
	v_lshl_add_u64 v[214:215], s[26:27], 0, v[128:129]
	s_mov_b32 m0, s67
	ds_read_b128 v[198:201], v152
	ds_read_b128 v[202:205], v152 offset:1024
	ds_read_b128 v[206:209], v152 offset:2048
	ds_read_b128 v[210:213], v152 offset:3072
	s_waitcnt vmcnt(8)
	s_waitcnt lgkmcnt(0)
	s_barrier
	v_mfma_f32_16x16x32_bf16 v[124:127], v[142:145], v[166:169], v[124:127]
	v_mfma_f32_16x16x32_bf16 v[120:123], v[158:161], v[166:169], v[120:123]
	v_mfma_f32_16x16x32_bf16 v[108:111], v[142:145], v[174:177], v[108:111]
	v_mfma_f32_16x16x32_bf16 v[104:107], v[158:161], v[174:177], v[104:107]
	v_mfma_f32_16x16x32_bf16 v[92:95], v[142:145], v[182:185], v[92:95]
	v_mfma_f32_16x16x32_bf16 v[88:91], v[158:161], v[182:185], v[88:91]
	v_mfma_f32_16x16x32_bf16 v[76:79], v[142:145], v[190:193], v[76:79]
	v_mfma_f32_16x16x32_bf16 v[72:75], v[158:161], v[190:193], v[72:75]
	v_mfma_f32_16x16x32_bf16 v[124:127], v[154:157], v[170:173], v[124:127]
	v_mfma_f32_16x16x32_bf16 v[120:123], v[162:165], v[170:173], v[120:123]
	v_mfma_f32_16x16x32_bf16 v[108:111], v[154:157], v[178:181], v[108:111]
	v_mfma_f32_16x16x32_bf16 v[104:107], v[162:165], v[178:181], v[104:107]
	v_mfma_f32_16x16x32_bf16 v[92:95], v[154:157], v[186:189], v[92:95]
	v_mfma_f32_16x16x32_bf16 v[88:91], v[162:165], v[186:189], v[88:91]
	v_mfma_f32_16x16x32_bf16 v[76:79], v[154:157], v[194:197], v[76:79]
	v_mfma_f32_16x16x32_bf16 v[72:75], v[162:165], v[194:197], v[72:75]
	v_mfma_f32_16x16x32_bf16 v[116:119], v[198:201], v[166:169], v[116:119]
	v_mfma_f32_16x16x32_bf16 v[112:115], v[206:209], v[166:169], v[112:115]
	v_mfma_f32_16x16x32_bf16 v[100:103], v[198:201], v[174:177], v[100:103]
	v_mfma_f32_16x16x32_bf16 v[96:99], v[206:209], v[174:177], v[96:99]
	v_mfma_f32_16x16x32_bf16 v[84:87], v[198:201], v[182:185], v[84:87]
	v_mfma_f32_16x16x32_bf16 v[80:83], v[206:209], v[182:185], v[80:83]
	v_mfma_f32_16x16x32_bf16 v[68:71], v[198:201], v[190:193], v[68:71]
	v_mfma_f32_16x16x32_bf16 v[64:67], v[206:209], v[190:193], v[64:67]
	v_mfma_f32_16x16x32_bf16 v[116:119], v[202:205], v[170:173], v[116:119]
	v_mfma_f32_16x16x32_bf16 v[112:115], v[210:213], v[170:173], v[112:115]
	v_mfma_f32_16x16x32_bf16 v[100:103], v[202:205], v[178:181], v[100:103]
	v_mfma_f32_16x16x32_bf16 v[96:99], v[210:213], v[178:181], v[96:99]
	v_mfma_f32_16x16x32_bf16 v[84:87], v[202:205], v[186:189], v[84:87]
	v_mfma_f32_16x16x32_bf16 v[80:83], v[210:213], v[186:189], v[80:83]
	v_mfma_f32_16x16x32_bf16 v[68:71], v[202:205], v[194:197], v[68:71]
	v_mfma_f32_16x16x32_bf16 v[64:67], v[210:213], v[194:197], v[64:67]
	s_barrier
	global_load_lds_dwordx4 v[214:215], off
	v_lshl_add_u64 v[214:215], s[26:27], 0, v[132:133]
	s_add_i32 m0, s67, 0x2000
	s_nop 0
	global_load_lds_dwordx4 v[214:215], off
	s_mov_b32 m0, s48
	v_lshl_add_u64 v[214:215], s[28:29], 0, v[130:131]
	ds_read_b128 v[166:169], v151 offset:16384
	ds_read_b128 v[170:173], v151 offset:17408
	ds_read_b128 v[174:177], v151 offset:18432
	ds_read_b128 v[178:181], v151 offset:19456
	ds_read_b128 v[182:185], v151 offset:20480
	ds_read_b128 v[186:189], v151 offset:21504
	ds_read_b128 v[190:193], v151 offset:22528
	ds_read_b128 v[194:197], v151 offset:23552
	global_load_lds_dwordx4 v[214:215], off
	v_lshl_add_u64 v[216:217], s[28:29], 0, v[134:135]
	s_mov_b32 m0, s49
	s_nop 0
	global_load_lds_dwordx4 v[216:217], off
	s_add_u32 s68, s26, 0x4000
	s_addc_u32 s69, s27, 0
	s_add_i32 s67, s60, s39
	v_lshl_add_u64 v[250:251], s[68:69], 0, v[128:129]
	s_mov_b32 m0, s67
	s_nop 0
	global_load_lds_dwordx4 v[250:251], off
	v_lshl_add_u64 v[250:251], s[68:69], 0, v[132:133]
	s_add_i32 m0, s67, 0x2000
	s_nop 0
	global_load_lds_dwordx4 v[250:251], off
	s_waitcnt vmcnt(8)
	s_waitcnt lgkmcnt(0)
	s_barrier
; #define PG8_STAGE(bufoff, gbase, voff) do { _Pragma("unroll") for (int _i = 0; _i < 2; ++_i) \
;         __builtin_amdgcn_global_load_lds((const unsigned*)((const char*)(gbase) + (voff)[_i]), (PG8_LAS unsigned*)(lds + (bufoff) + ldsw + _i * 8192), 16, 0, 0); } while (0)
; #define PG8_LDA(dst, b, h) do { _Pragma("unroll") for (int m = 0; m < 4; ++m) _Pragma("unroll") for (int k = 0; k < 2; ++k) dst[m][k] = *(const PG8_LAS bf16x8*)(lds + PG8_SA(b, h) + aoff + m * 2048 + k * 1024); } while (0)
; #define PG8_LDB(dst, b, h) do { _Pragma("unroll") for (int n = 0; n < 2; ++n) _Pragma("unroll") for (int k = 0; k < 2; ++k) dst[n][k] = *(const PG8_LAS bf16x8*)(lds + PG8_SB(b, h) + boff + n * 2048 + k * 1024); } while (0)
; #define PG8_MMA(ai, bj, At, Bt) do { __builtin_amdgcn_s_setprio(1); _Pragma("unroll") for (int m = 0; m < 4; ++m) _Pragma("unroll") for (int n = 0; n < 2; ++n) _Pragma("unroll") for (int k = 0; k < 2; ++k) \
;         acc[ai][bj][m][n] = __builtin_amdgcn_mfma_f32_16x16x32_bf16(Bt[n][k], At[m][k], acc[ai][bj][m][n], 0, 0, 0); __builtin_amdgcn_s_setprio(0); } while (0)
; #define PG8_WAIT_V(n) asm volatile("s_waitcnt vmcnt(" #n ")" ::: "memory")
; #define PG8_WAIT_L(n) asm volatile("s_waitcnt lgkmcnt(" #n ")" ::: "memory")
; #define PG8_BAR __builtin_amdgcn_s_barrier()
; #define PG8_SCHED __builtin_amdgcn_sched_barrier(0)
; template <class Epi, class Sched>
; __device__ __forceinline__ void gemm_phase(PG8_LAS unsigned char* lds, const Gemm g, const Sched& S, const Epi& E) {
;     ...
;             PG8_BAR; PG8_WAIT_L(0); PG8_MMA(1, 0, At, B0); PG8_BAR; PG8_SCHED;
;             PG8_STAGE(PG8_SB(0, 1), b2 + hstepB, voffB);
;             PG8_WAIT_V(6); PG8_BAR; PG8_MMA(1, 1, At, B1); PG8_BAR;
;             PG8_LDB(B0, 1, 0); PG8_SCHED; PG8_LDA(At, 1, 0); PG8_STAGE(PG8_SA(0, 1), a2 + hstep, voffA);
;             PG8_WAIT_L(8); PG8_BAR; PG8_WAIT_L(0); PG8_MMA(0, 0, At, B0); PG8_BAR; PG8_SCHED;
;             PG8_LDB(B1, 1, 1); PG8_STAGE(PG8_SB(1, 0), b3, voffB);
;             PG8_BAR; PG8_WAIT_L(0); PG8_MMA(0, 1, At, B1); PG8_BAR;
	v_mfma_f32_16x16x32_bf16 v[60:63], v[142:145], v[166:169], v[60:63]
	v_mfma_f32_16x16x32_bf16 v[56:59], v[158:161], v[166:169], v[56:59]
	v_mfma_f32_16x16x32_bf16 v[44:47], v[142:145], v[174:177], v[44:47]
	v_mfma_f32_16x16x32_bf16 v[40:43], v[158:161], v[174:177], v[40:43]
	v_mfma_f32_16x16x32_bf16 v[28:31], v[142:145], v[182:185], v[28:31]
	v_mfma_f32_16x16x32_bf16 v[24:27], v[158:161], v[182:185], v[24:27]
	v_mfma_f32_16x16x32_bf16 v[12:15], v[142:145], v[190:193], v[12:15]
	v_mfma_f32_16x16x32_bf16 v[8:11], v[158:161], v[190:193], v[8:11]
	v_mfma_f32_16x16x32_bf16 v[60:63], v[154:157], v[170:173], v[60:63]
	v_mfma_f32_16x16x32_bf16 v[56:59], v[162:165], v[170:173], v[56:59]
	v_mfma_f32_16x16x32_bf16 v[44:47], v[154:157], v[178:181], v[44:47]
	v_mfma_f32_16x16x32_bf16 v[40:43], v[162:165], v[178:181], v[40:43]
	v_mfma_f32_16x16x32_bf16 v[28:31], v[154:157], v[186:189], v[28:31]
	v_mfma_f32_16x16x32_bf16 v[24:27], v[162:165], v[186:189], v[24:27]
	v_mfma_f32_16x16x32_bf16 v[12:15], v[154:157], v[194:197], v[12:15]
	v_mfma_f32_16x16x32_bf16 v[8:11], v[162:165], v[194:197], v[8:11]
	v_mfma_f32_16x16x32_bf16 v[52:55], v[198:201], v[166:169], v[52:55]
	v_mfma_f32_16x16x32_bf16 v[48:51], v[206:209], v[166:169], v[48:51]
	v_mfma_f32_16x16x32_bf16 v[36:39], v[198:201], v[174:177], v[36:39]
	v_mfma_f32_16x16x32_bf16 v[32:35], v[206:209], v[174:177], v[32:35]
	v_mfma_f32_16x16x32_bf16 v[20:23], v[198:201], v[182:185], v[20:23]
	v_mfma_f32_16x16x32_bf16 v[16:19], v[206:209], v[182:185], v[16:19]
	v_mfma_f32_16x16x32_bf16 v[4:7], v[198:201], v[190:193], v[4:7]
	v_mfma_f32_16x16x32_bf16 v[0:3], v[206:209], v[190:193], v[0:3]
	v_mfma_f32_16x16x32_bf16 v[52:55], v[202:205], v[170:173], v[52:55]
	v_mfma_f32_16x16x32_bf16 v[48:51], v[210:213], v[170:173], v[48:51]
	v_mfma_f32_16x16x32_bf16 v[36:39], v[202:205], v[178:181], v[36:39]
	v_mfma_f32_16x16x32_bf16 v[32:35], v[210:213], v[178:181], v[32:35]
	v_mfma_f32_16x16x32_bf16 v[20:23], v[202:205], v[186:189], v[20:23]
	v_mfma_f32_16x16x32_bf16 v[16:19], v[210:213], v[186:189], v[16:19]
	v_mfma_f32_16x16x32_bf16 v[4:7], v[202:205], v[194:197], v[4:7]
	v_mfma_f32_16x16x32_bf16 v[0:3], v[210:213], v[194:197], v[0:3]
	s_barrier
	s_add_i32 s67, 0, 0x18000
	v_add_u32_e32 v136, s67, v148
	ds_read_b128 v[142:145], v136
	ds_read_b128 v[154:157], v136 offset:1024
	ds_read_b128 v[158:161], v136 offset:2048
	ds_read_b128 v[162:165], v136 offset:3072
	s_add_u32 s28, s28, 0x80000
	s_addc_u32 s29, s29, 0
	s_mov_b32 m0, s50
	v_lshl_add_u64 v[198:199], s[28:29], 0, v[130:131]
	ds_read_b128 v[166:169], v151 offset:32768
	ds_read_b128 v[170:173], v151 offset:33792
	ds_read_b128 v[174:177], v151 offset:34816
	ds_read_b128 v[178:181], v151 offset:35840
	ds_read_b128 v[182:185], v151 offset:36864
	ds_read_b128 v[186:189], v151 offset:37888
	ds_read_b128 v[190:193], v151 offset:38912
	ds_read_b128 v[194:197], v151 offset:39936
	global_load_lds_dwordx4 v[198:199], off
	v_lshl_add_u64 v[198:199], s[28:29], 0, v[134:135]
	s_mov_b32 m0, s51
	s_nop 0
	global_load_lds_dwordx4 v[198:199], off
	s_add_i32 s68, 0, 0x1c000
	s_add_u32 s28, s26, 0x8000
	s_addc_u32 s29, s27, 0
	s_add_i32 s67, s67, s39
	v_add_u32_e32 v136, s68, v148
	v_lshl_add_u64 v[218:219], s[28:29], 0, v[128:129]
	s_mov_b32 m0, s67
	ds_read_b128 v[198:201], v136
	ds_read_b128 v[202:205], v136 offset:1024
	ds_read_b128 v[206:209], v136 offset:2048
	ds_read_b128 v[210:213], v136 offset:3072
	s_waitcnt vmcnt(8)
	s_waitcnt lgkmcnt(0)
	s_barrier
	v_mfma_f32_16x16x32_bf16 v[124:127], v[142:145], v[166:169], v[124:127]
	v_mfma_f32_16x16x32_bf16 v[120:123], v[158:161], v[166:169], v[120:123]
	v_mfma_f32_16x16x32_bf16 v[108:111], v[142:145], v[174:177], v[108:111]
	v_mfma_f32_16x16x32_bf16 v[104:107], v[158:161], v[174:177], v[104:107]
	v_mfma_f32_16x16x32_bf16 v[92:95], v[142:145], v[182:185], v[92:95]
	v_mfma_f32_16x16x32_bf16 v[88:91], v[158:161], v[182:185], v[88:91]
	v_mfma_f32_16x16x32_bf16 v[76:79], v[142:145], v[190:193], v[76:79]
	v_mfma_f32_16x16x32_bf16 v[72:75], v[158:161], v[190:193], v[72:75]
	v_mfma_f32_16x16x32_bf16 v[124:127], v[154:157], v[170:173], v[124:127]
	v_mfma_f32_16x16x32_bf16 v[120:123], v[162:165], v[170:173], v[120:123]
	v_mfma_f32_16x16x32_bf16 v[108:111], v[154:157], v[178:181], v[108:111]
	v_mfma_f32_16x16x32_bf16 v[104:107], v[162:165], v[178:181], v[104:107]
	v_mfma_f32_16x16x32_bf16 v[92:95], v[154:157], v[186:189], v[92:95]
	v_mfma_f32_16x16x32_bf16 v[88:91], v[162:165], v[186:189], v[88:91]
	v_mfma_f32_16x16x32_bf16 v[76:79], v[154:157], v[194:197], v[76:79]
	v_mfma_f32_16x16x32_bf16 v[72:75], v[162:165], v[194:197], v[72:75]
	v_mfma_f32_16x16x32_bf16 v[116:119], v[198:201], v[166:169], v[116:119]
	v_mfma_f32_16x16x32_bf16 v[112:115], v[206:209], v[166:169], v[112:115]
	v_mfma_f32_16x16x32_bf16 v[100:103], v[198:201], v[174:177], v[100:103]
	v_mfma_f32_16x16x32_bf16 v[96:99], v[206:209], v[174:177], v[96:99]
	v_mfma_f32_16x16x32_bf16 v[84:87], v[198:201], v[182:185], v[84:87]
	v_mfma_f32_16x16x32_bf16 v[80:83], v[206:209], v[182:185], v[80:83]
	v_mfma_f32_16x16x32_bf16 v[68:71], v[198:201], v[190:193], v[68:71]
	v_mfma_f32_16x16x32_bf16 v[64:67], v[206:209], v[190:193], v[64:67]
	v_mfma_f32_16x16x32_bf16 v[116:119], v[202:205], v[170:173], v[116:119]
	v_mfma_f32_16x16x32_bf16 v[112:115], v[210:213], v[170:173], v[112:115]
	v_mfma_f32_16x16x32_bf16 v[100:103], v[202:205], v[178:181], v[100:103]
	v_mfma_f32_16x16x32_bf16 v[96:99], v[210:213], v[178:181], v[96:99]
	v_mfma_f32_16x16x32_bf16 v[84:87], v[202:205], v[186:189], v[84:87]
	v_mfma_f32_16x16x32_bf16 v[80:83], v[210:213], v[186:189], v[80:83]
	v_mfma_f32_16x16x32_bf16 v[68:71], v[202:205], v[194:197], v[68:71]
	v_mfma_f32_16x16x32_bf16 v[64:67], v[210:213], v[194:197], v[64:67]
	s_barrier
; #define PG8_STAGE(bufoff, gbase, voff) do { _Pragma("unroll") for (int _i = 0; _i < 2; ++_i) \
;         __builtin_amdgcn_global_load_lds((const unsigned*)((const char*)(gbase) + (voff)[_i]), (PG8_LAS unsigned*)(lds + (bufoff) + ldsw + _i * 8192), 16, 0, 0); } while (0)
; #define PG8_LDA(dst, b, h) do { _Pragma("unroll") for (int m = 0; m < 4; ++m) _Pragma("unroll") for (int k = 0; k < 2; ++k) dst[m][k] = *(const PG8_LAS bf16x8*)(lds + PG8_SA(b, h) + aoff + m * 2048 + k * 1024); } while (0)
; #define PG8_LDB(dst, b, h) do { _Pragma("unroll") for (int n = 0; n < 2; ++n) _Pragma("unroll") for (int k = 0; k < 2; ++k) dst[n][k] = *(const PG8_LAS bf16x8*)(lds + PG8_SB(b, h) + boff + n * 2048 + k * 1024); } while (0)
; #define PG8_MMA(ai, bj, At, Bt) do { __builtin_amdgcn_s_setprio(1); _Pragma("unroll") for (int m = 0; m < 4; ++m) _Pragma("unroll") for (int n = 0; n < 2; ++n) _Pragma("unroll") for (int k = 0; k < 2; ++k) \
;         acc[ai][bj][m][n] = __builtin_amdgcn_mfma_f32_16x16x32_bf16(Bt[n][k], At[m][k], acc[ai][bj][m][n], 0, 0, 0); __builtin_amdgcn_s_setprio(0); } while (0)
; #define PG8_WAIT_V(n) asm volatile("s_waitcnt vmcnt(" #n ")" ::: "memory")
; #define PG8_WAIT_L(n) asm volatile("s_waitcnt lgkmcnt(" #n ")" ::: "memory")
; #define PG8_BAR __builtin_amdgcn_s_barrier()
; #define PG8_SCHED __builtin_amdgcn_sched_barrier(0)
; template <class Epi, class Sched>
; __device__ __forceinline__ void gemm_phase(PG8_LAS unsigned char* lds, const Gemm g, const Sched& S, const Epi& E) {
;     ...
;             PG8_LDB(B1, 1, 1); PG8_STAGE(PG8_SB(1, 0), b3, voffB);
;             PG8_BAR; PG8_WAIT_L(0); PG8_MMA(0, 1, At, B1); PG8_BAR;
;             PG8_LDA(At, 1, 1); PG8_STAGE(PG8_SA(1, 0), a3, voffA);
;             PG8_BAR; PG8_WAIT_L(0); PG8_MMA(1, 0, At, B0); PG8_BAR; PG8_SCHED;
;             PG8_STAGE(PG8_SB(1, 1), b3 + hstepB, voffB);
;             PG8_WAIT_V(6); PG8_BAR; PG8_MMA(1, 1, At, B1); PG8_BAR;
;         }
	global_load_lds_dwordx4 v[218:219], off
	v_lshl_add_u64 v[218:219], s[28:29], 0, v[132:133]
	s_add_i32 m0, s67, 0x2000
	s_nop 0
	global_load_lds_dwordx4 v[218:219], off
	s_mov_b32 m0, s55
	v_lshl_add_u64 v[214:215], v[214:215], 0, s[10:11]
	ds_read_b128 v[166:169], v151 offset:49152
	ds_read_b128 v[170:173], v151 offset:50176
	ds_read_b128 v[174:177], v151 offset:51200
	ds_read_b128 v[178:181], v151 offset:52224
	ds_read_b128 v[182:185], v151 offset:53248
	ds_read_b128 v[186:189], v151 offset:54272
	ds_read_b128 v[190:193], v151 offset:55296
	ds_read_b128 v[194:197], v151 offset:56320
	global_load_lds_dwordx4 v[214:215], off
	v_lshl_add_u64 v[214:215], v[216:217], 0, s[10:11]
	s_mov_b32 m0, s56
	s_nop 0
	global_load_lds_dwordx4 v[214:215], off
	s_add_u32 s26, s26, 0xc000
	s_addc_u32 s27, s27, 0
	s_add_i32 s28, s68, s39
	v_lshl_add_u64 v[252:253], s[26:27], 0, v[128:129]
	s_mov_b32 m0, s28
	s_nop 0
	global_load_lds_dwordx4 v[252:253], off
	v_lshl_add_u64 v[252:253], s[26:27], 0, v[132:133]
	s_add_i32 m0, s28, 0x2000
	s_nop 0
	global_load_lds_dwordx4 v[252:253], off
	s_waitcnt vmcnt(8)
	s_waitcnt lgkmcnt(0)
	s_barrier
	v_mfma_f32_16x16x32_bf16 v[60:63], v[142:145], v[166:169], v[60:63]
	v_mfma_f32_16x16x32_bf16 v[56:59], v[158:161], v[166:169], v[56:59]
	v_mfma_f32_16x16x32_bf16 v[44:47], v[142:145], v[174:177], v[44:47]
	v_mfma_f32_16x16x32_bf16 v[40:43], v[158:161], v[174:177], v[40:43]
	v_mfma_f32_16x16x32_bf16 v[28:31], v[142:145], v[182:185], v[28:31]
	v_mfma_f32_16x16x32_bf16 v[24:27], v[158:161], v[182:185], v[24:27]
	v_mfma_f32_16x16x32_bf16 v[12:15], v[142:145], v[190:193], v[12:15]
	v_mfma_f32_16x16x32_bf16 v[8:11], v[158:161], v[190:193], v[8:11]
	v_mfma_f32_16x16x32_bf16 v[60:63], v[154:157], v[170:173], v[60:63]
	v_mfma_f32_16x16x32_bf16 v[56:59], v[162:165], v[170:173], v[56:59]
	v_mfma_f32_16x16x32_bf16 v[44:47], v[154:157], v[178:181], v[44:47]
	v_mfma_f32_16x16x32_bf16 v[40:43], v[162:165], v[178:181], v[40:43]
	v_mfma_f32_16x16x32_bf16 v[28:31], v[154:157], v[186:189], v[28:31]
	v_mfma_f32_16x16x32_bf16 v[24:27], v[162:165], v[186:189], v[24:27]
	v_mfma_f32_16x16x32_bf16 v[12:15], v[154:157], v[194:197], v[12:15]
	v_mfma_f32_16x16x32_bf16 v[8:11], v[162:165], v[194:197], v[8:11]
	v_mfma_f32_16x16x32_bf16 v[52:55], v[198:201], v[166:169], v[52:55]
	v_mfma_f32_16x16x32_bf16 v[48:51], v[206:209], v[166:169], v[48:51]
	v_mfma_f32_16x16x32_bf16 v[36:39], v[198:201], v[174:177], v[36:39]
	v_mfma_f32_16x16x32_bf16 v[32:35], v[206:209], v[174:177], v[32:35]
	v_mfma_f32_16x16x32_bf16 v[20:23], v[198:201], v[182:185], v[20:23]
	v_mfma_f32_16x16x32_bf16 v[16:19], v[206:209], v[182:185], v[16:19]
	v_mfma_f32_16x16x32_bf16 v[4:7], v[198:201], v[190:193], v[4:7]
	v_mfma_f32_16x16x32_bf16 v[0:3], v[206:209], v[190:193], v[0:3]
	v_mfma_f32_16x16x32_bf16 v[52:55], v[202:205], v[170:173], v[52:55]
	v_mfma_f32_16x16x32_bf16 v[48:51], v[210:213], v[170:173], v[48:51]
	v_mfma_f32_16x16x32_bf16 v[36:39], v[202:205], v[178:181], v[36:39]
	v_mfma_f32_16x16x32_bf16 v[32:35], v[210:213], v[178:181], v[32:35]
	v_mfma_f32_16x16x32_bf16 v[20:23], v[202:205], v[186:189], v[20:23]
	v_mfma_f32_16x16x32_bf16 v[16:19], v[210:213], v[186:189], v[16:19]
	v_mfma_f32_16x16x32_bf16 v[4:7], v[202:205], v[194:197], v[4:7]
	v_mfma_f32_16x16x32_bf16 v[0:3], v[210:213], v[194:197], v[0:3]
	s_add_i32 s66, s66, 2
	s_add_u32 s64, s64, 0x10000
	s_addc_u32 s65, s65, 0
	s_add_u32 s24, s24, 0x100
	s_addc_u32 s25, s25, 0
	s_cmp_gt_u32 s66, 29
	s_barrier
	s_cbranch_scc0 .LBB0_397
	s_cmp_eq_u32 s78, 0
	s_cbranch_scc0 .Lhalf_skip_x_3
	s_barrier

; #define PG8_STAGE(bufoff, gbase, voff) do { _Pragma("unroll") for (int _i = 0; _i < 2; ++_i) \
;         __builtin_amdgcn_global_load_lds((const unsigned*)((const char*)(gbase) + (voff)[_i]), (PG8_LAS unsigned*)(lds + (bufoff) + ldsw + _i * 8192), 16, 0, 0); } while (0)
; #define PG8_LDA(dst, b, h) do { _Pragma("unroll") for (int m = 0; m < 4; ++m) _Pragma("unroll") for (int k = 0; k < 2; ++k) dst[m][k] = *(const PG8_LAS bf16x8*)(lds + PG8_SA(b, h) + aoff + m * 2048 + k * 1024); } while (0)
; #define PG8_LDB(dst, b, h) do { _Pragma("unroll") for (int n = 0; n < 2; ++n) _Pragma("unroll") for (int k = 0; k < 2; ++k) dst[n][k] = *(const PG8_LAS bf16x8*)(lds + PG8_SB(b, h) + boff + n * 2048 + k * 1024); } while (0)
; #define PG8_MMA(ai, bj, At, Bt) do { __builtin_amdgcn_s_setprio(1); _Pragma("unroll") for (int m = 0; m < 4; ++m) _Pragma("unroll") for (int n = 0; n < 2; ++n) _Pragma("unroll") for (int k = 0; k < 2; ++k) \
;         acc[ai][bj][m][n] = __builtin_amdgcn_mfma_f32_16x16x32_bf16(Bt[n][k], At[m][k], acc[ai][bj][m][n], 0, 0, 0); __builtin_amdgcn_s_setprio(0); } while (0)
; #define PG8_WAIT_V(n) asm volatile("s_waitcnt vmcnt(" #n ")" ::: "memory")
; template <class Epi, class Sched>
; __device__ __forceinline__ void gemm_phase(PG8_LAS unsigned char* lds, const Gemm g, const Sched& S, const Epi& E) {
;     ...
;         for (int t = 0; t < nt; t += 2) {
;             const bool last = (t == nt - 2);
;             const char* a1 = cA + (size_t)(t + 1) * kstep;
;             const char* a2 = last ? nA : cA + (size_t)(t + 2) * kstep; const char* b2 = last ? nB : cB + (size_t)(t + 2) * kstepB;
;             const char* a3 = a2 + kstep; const char* b3 = b2 + kstepB;
;             if (last && has_next) S.a_ready(nxt);
;             PG8_LDB(B0, 0, 0); PG8_SCHED; PG8_LDA(At, 0, 0); PG8_STAGE(PG8_SA(1, 1), a1 + hstep, voffA);
;             PG8_WAIT_L(8); PG8_BAR; PG8_WAIT_L(0); PG8_MMA(0, 0, At, B0); PG8_BAR; PG8_SCHED;
;             PG8_LDB(B1, 0, 1); PG8_STAGE(PG8_SB(0, 0), b2, voffB);
;             PG8_BAR; PG8_WAIT_L(0); PG8_MMA(0, 1, At, B1); PG8_BAR;
;             PG8_LDA(At, 0, 1); PG8_STAGE(PG8_SA(0, 0), a2, voffA);
;             PG8_BAR; PG8_WAIT_L(0); PG8_MMA(1, 0, At, B0); PG8_BAR; PG8_SCHED;
;             PG8_STAGE(PG8_SB(0, 1), b2 + hstepB, voffB);
;             PG8_WAIT_V(6); PG8_BAR; PG8_MMA(1, 1, At, B1); PG8_BAR;
.Lhalf_skip_y_4:
.LBB0_613:
	v_add_u32_e32 v1, s57, v231
	ds_read_b128 v[132:135], v1
	ds_read_b128 v[136:139], v1 offset:1024
	ds_read_b128 v[140:143], v1 offset:2048
	ds_read_b128 v[144:147], v1 offset:3072
	s_add_u32 s26, s24, 0xfffc0080
	s_addc_u32 s27, s25, -1
	s_cmp_eq_u32 s63, 12
	s_cselect_b32 s29, s7, s27
	s_cselect_b32 s28, s15, s26
	s_cselect_b32 s27, s17, s62
	s_cselect_b32 s26, s19, s61
	v_lshl_add_u64 v[2:3], s[24:25], 0, v[204:205]
	s_add_i32 m0, s49, 0xc000
	ds_read_b128 v[148:151], v233
	ds_read_b128 v[152:155], v233 offset:1024
	ds_read_b128 v[156:159], v233 offset:2048
	ds_read_b128 v[160:163], v233 offset:3072
	ds_read_b128 v[164:167], v233 offset:4096
	ds_read_b128 v[168:171], v233 offset:5120
	ds_read_b128 v[172:175], v233 offset:6144
	ds_read_b128 v[176:179], v233 offset:7168
	global_load_lds_dwordx4 v[2:3], off
	v_lshl_add_u64 v[2:3], s[24:25], 0, v[206:207]
	s_add_i32 m0, s49, 0xe000
	s_nop 0
	global_load_lds_dwordx4 v[2:3], off
	s_add_i32 s64, s57, s48
	v_add_u32_e32 v1, s58, v231
	v_lshl_add_u64 v[250:251], s[26:27], 0, v[196:197]
	s_mov_b32 m0, s64
	ds_read_b128 v[180:183], v1
	ds_read_b128 v[184:187], v1 offset:1024
	ds_read_b128 v[188:191], v1 offset:2048
	ds_read_b128 v[192:195], v1 offset:3072
	s_waitcnt vmcnt(8)
	s_waitcnt lgkmcnt(0)
	s_barrier
	v_mfma_f32_16x16x32_bf16 v[2:5], v[132:135], v[148:151], v[4:7]
	v_mfma_f32_16x16x32_bf16 v[6:9], v[140:143], v[148:151], v[8:11]
	v_mfma_f32_16x16x32_bf16 v[32:35], v[132:135], v[156:159], v[32:35]
	v_mfma_f32_16x16x32_bf16 v[28:31], v[140:143], v[156:159], v[28:31]
	v_mfma_f32_16x16x32_bf16 v[24:27], v[132:135], v[164:167], v[24:27]
	v_mfma_f32_16x16x32_bf16 v[20:23], v[140:143], v[164:167], v[20:23]
	v_mfma_f32_16x16x32_bf16 v[16:19], v[132:135], v[172:175], v[16:19]
	v_mfma_f32_16x16x32_bf16 v[12:15], v[140:143], v[172:175], v[12:15]
	v_mfma_f32_16x16x32_bf16 v[2:5], v[136:139], v[152:155], v[2:5]
	v_mfma_f32_16x16x32_bf16 v[8:11], v[144:147], v[152:155], v[6:9]
	v_mfma_f32_16x16x32_bf16 v[32:35], v[136:139], v[160:163], v[32:35]
	v_mfma_f32_16x16x32_bf16 v[28:31], v[144:147], v[160:163], v[28:31]
	v_mfma_f32_16x16x32_bf16 v[24:27], v[136:139], v[168:171], v[24:27]
	v_mfma_f32_16x16x32_bf16 v[20:23], v[144:147], v[168:171], v[20:23]
	v_mfma_f32_16x16x32_bf16 v[16:19], v[136:139], v[176:179], v[16:19]
	v_mfma_f32_16x16x32_bf16 v[12:15], v[144:147], v[176:179], v[12:15]
	v_mfma_f32_16x16x32_bf16 v[128:131], v[180:183], v[148:151], v[128:131]
	v_mfma_f32_16x16x32_bf16 v[124:127], v[188:191], v[148:151], v[124:127]
	v_mfma_f32_16x16x32_bf16 v[120:123], v[180:183], v[156:159], v[120:123]
	v_mfma_f32_16x16x32_bf16 v[116:119], v[188:191], v[156:159], v[116:119]
	v_mfma_f32_16x16x32_bf16 v[112:115], v[180:183], v[164:167], v[112:115]
	v_mfma_f32_16x16x32_bf16 v[108:111], v[188:191], v[164:167], v[108:111]
	v_mfma_f32_16x16x32_bf16 v[104:107], v[180:183], v[172:175], v[104:107]
	v_mfma_f32_16x16x32_bf16 v[100:103], v[188:191], v[172:175], v[100:103]
	v_mfma_f32_16x16x32_bf16 v[128:131], v[184:187], v[152:155], v[128:131]
	v_mfma_f32_16x16x32_bf16 v[124:127], v[192:195], v[152:155], v[124:127]
	v_mfma_f32_16x16x32_bf16 v[120:123], v[184:187], v[160:163], v[120:123]
	v_mfma_f32_16x16x32_bf16 v[116:119], v[192:195], v[160:163], v[116:119]
	v_mfma_f32_16x16x32_bf16 v[112:115], v[184:187], v[168:171], v[112:115]
	v_mfma_f32_16x16x32_bf16 v[108:111], v[192:195], v[168:171], v[108:111]
	v_mfma_f32_16x16x32_bf16 v[104:107], v[184:187], v[176:179], v[104:107]
	v_mfma_f32_16x16x32_bf16 v[100:103], v[192:195], v[176:179], v[100:103]
	s_barrier
	global_load_lds_dwordx4 v[250:251], off
	v_lshl_add_u64 v[250:251], s[26:27], 0, v[200:201]
	s_add_i32 m0, s64, 0x2000
	s_nop 0
	global_load_lds_dwordx4 v[250:251], off
	s_mov_b32 m0, s49
	v_lshl_add_u64 v[212:213], s[28:29], 0, v[198:199]
	ds_read_b128 v[148:151], v233 offset:16384
	ds_read_b128 v[152:155], v233 offset:17408
	ds_read_b128 v[156:159], v233 offset:18432
	ds_read_b128 v[160:163], v233 offset:19456
	ds_read_b128 v[164:167], v233 offset:20480
	ds_read_b128 v[168:171], v233 offset:21504
	ds_read_b128 v[172:175], v233 offset:22528
	ds_read_b128 v[176:179], v233 offset:23552
	global_load_lds_dwordx4 v[212:213], off
	v_lshl_add_u64 v[214:215], s[28:29], 0, v[202:203]
	s_mov_b32 m0, s50
	s_nop 0
	global_load_lds_dwordx4 v[214:215], off
	s_add_u32 s64, s26, 0x4000
	s_addc_u32 s65, s27, 0
	s_add_i32 s66, s58, s48
	v_lshl_add_u64 v[6:7], s[64:65], 0, v[196:197]
	s_mov_b32 m0, s66
	s_nop 0
	global_load_lds_dwordx4 v[6:7], off
	v_lshl_add_u64 v[6:7], s[64:65], 0, v[200:201]
	s_add_i32 m0, s66, 0x2000
	s_nop 0
	global_load_lds_dwordx4 v[6:7], off
	s_waitcnt vmcnt(8)
	s_waitcnt lgkmcnt(0)
	s_barrier
; #define PG8_STAGE(bufoff, gbase, voff) do { _Pragma("unroll") for (int _i = 0; _i < 2; ++_i) \
;         __builtin_amdgcn_global_load_lds((const unsigned*)((const char*)(gbase) + (voff)[_i]), (PG8_LAS unsigned*)(lds + (bufoff) + ldsw + _i * 8192), 16, 0, 0); } while (0)
; #define PG8_LDA(dst, b, h) do { _Pragma("unroll") for (int m = 0; m < 4; ++m) _Pragma("unroll") for (int k = 0; k < 2; ++k) dst[m][k] = *(const PG8_LAS bf16x8*)(lds + PG8_SA(b, h) + aoff + m * 2048 + k * 1024); } while (0)
; #define PG8_LDB(dst, b, h) do { _Pragma("unroll") for (int n = 0; n < 2; ++n) _Pragma("unroll") for (int k = 0; k < 2; ++k) dst[n][k] = *(const PG8_LAS bf16x8*)(lds + PG8_SB(b, h) + boff + n * 2048 + k * 1024); } while (0)
; #define PG8_MMA(ai, bj, At, Bt) do { __builtin_amdgcn_s_setprio(1); _Pragma("unroll") for (int m = 0; m < 4; ++m) _Pragma("unroll") for (int n = 0; n < 2; ++n) _Pragma("unroll") for (int k = 0; k < 2; ++k) \
;         acc[ai][bj][m][n] = __builtin_amdgcn_mfma_f32_16x16x32_bf16(Bt[n][k], At[m][k], acc[ai][bj][m][n], 0, 0, 0); __builtin_amdgcn_s_setprio(0); } while (0)
; #define PG8_WAIT_V(n) asm volatile("s_waitcnt vmcnt(" #n ")" ::: "memory")
; #define PG8_WAIT_L(n) asm volatile("s_waitcnt lgkmcnt(" #n ")" ::: "memory")
; #define PG8_BAR __builtin_amdgcn_s_barrier()
; #define PG8_SCHED __builtin_amdgcn_sched_barrier(0)
; template <class Epi, class Sched>
; __device__ __forceinline__ void gemm_phase(PG8_LAS unsigned char* lds, const Gemm g, const Sched& S, const Epi& E) {
;     ...
;             PG8_BAR; PG8_WAIT_L(0); PG8_MMA(1, 0, At, B0); PG8_BAR; PG8_SCHED;
;             PG8_STAGE(PG8_SB(0, 1), b2 + hstepB, voffB);
;             PG8_WAIT_V(6); PG8_BAR; PG8_MMA(1, 1, At, B1); PG8_BAR;
;             PG8_LDB(B0, 1, 0); PG8_SCHED; PG8_LDA(At, 1, 0); PG8_STAGE(PG8_SA(0, 1), a2 + hstep, voffA);
;             PG8_WAIT_L(8); PG8_BAR; PG8_WAIT_L(0); PG8_MMA(0, 0, At, B0); PG8_BAR; PG8_SCHED;
;             PG8_LDB(B1, 1, 1); PG8_STAGE(PG8_SB(1, 0), b3, voffB);
;             PG8_BAR; PG8_WAIT_L(0); PG8_MMA(0, 1, At, B1); PG8_BAR;
	v_mfma_f32_16x16x32_bf16 v[96:99], v[132:135], v[148:151], v[96:99]
	v_mfma_f32_16x16x32_bf16 v[92:95], v[140:143], v[148:151], v[92:95]
	v_mfma_f32_16x16x32_bf16 v[88:91], v[132:135], v[156:159], v[88:91]
	v_mfma_f32_16x16x32_bf16 v[84:87], v[140:143], v[156:159], v[84:87]
	v_mfma_f32_16x16x32_bf16 v[80:83], v[132:135], v[164:167], v[80:83]
	v_mfma_f32_16x16x32_bf16 v[76:79], v[140:143], v[164:167], v[76:79]
	v_mfma_f32_16x16x32_bf16 v[72:75], v[132:135], v[172:175], v[72:75]
	v_mfma_f32_16x16x32_bf16 v[68:71], v[140:143], v[172:175], v[68:71]
	v_mfma_f32_16x16x32_bf16 v[96:99], v[136:139], v[152:155], v[96:99]
	v_mfma_f32_16x16x32_bf16 v[92:95], v[144:147], v[152:155], v[92:95]
	v_mfma_f32_16x16x32_bf16 v[88:91], v[136:139], v[160:163], v[88:91]
	v_mfma_f32_16x16x32_bf16 v[84:87], v[144:147], v[160:163], v[84:87]
	v_mfma_f32_16x16x32_bf16 v[80:83], v[136:139], v[168:171], v[80:83]
	v_mfma_f32_16x16x32_bf16 v[76:79], v[144:147], v[168:171], v[76:79]
	v_mfma_f32_16x16x32_bf16 v[72:75], v[136:139], v[176:179], v[72:75]
	v_mfma_f32_16x16x32_bf16 v[68:71], v[144:147], v[176:179], v[68:71]
	v_mfma_f32_16x16x32_bf16 v[64:67], v[180:183], v[148:151], v[64:67]
	v_mfma_f32_16x16x32_bf16 v[60:63], v[188:191], v[148:151], v[60:63]
	v_mfma_f32_16x16x32_bf16 v[56:59], v[180:183], v[156:159], v[56:59]
	v_mfma_f32_16x16x32_bf16 v[52:55], v[188:191], v[156:159], v[52:55]
	v_mfma_f32_16x16x32_bf16 v[48:51], v[180:183], v[164:167], v[48:51]
	v_mfma_f32_16x16x32_bf16 v[44:47], v[188:191], v[164:167], v[44:47]
	v_mfma_f32_16x16x32_bf16 v[40:43], v[180:183], v[172:175], v[40:43]
	v_mfma_f32_16x16x32_bf16 v[36:39], v[188:191], v[172:175], v[36:39]
	v_mfma_f32_16x16x32_bf16 v[64:67], v[184:187], v[152:155], v[64:67]
	v_mfma_f32_16x16x32_bf16 v[60:63], v[192:195], v[152:155], v[60:63]
	v_mfma_f32_16x16x32_bf16 v[56:59], v[184:187], v[160:163], v[56:59]
	v_mfma_f32_16x16x32_bf16 v[52:55], v[192:195], v[160:163], v[52:55]
	v_mfma_f32_16x16x32_bf16 v[48:51], v[184:187], v[168:171], v[48:51]
	v_mfma_f32_16x16x32_bf16 v[44:47], v[192:195], v[168:171], v[44:47]
	v_mfma_f32_16x16x32_bf16 v[40:43], v[184:187], v[176:179], v[40:43]
	v_mfma_f32_16x16x32_bf16 v[36:39], v[192:195], v[176:179], v[36:39]
	s_barrier
	s_add_i32 s64, 0, 0x18000
	v_add_u32_e32 v1, s64, v231
	ds_read_b128 v[132:135], v1
	ds_read_b128 v[136:139], v1 offset:1024
	ds_read_b128 v[140:143], v1 offset:2048
	ds_read_b128 v[144:147], v1 offset:3072
	s_add_u32 s28, s28, 0x40000
	s_addc_u32 s29, s29, 0
	s_mov_b32 m0, s51
	v_lshl_add_u64 v[6:7], s[28:29], 0, v[198:199]
	ds_read_b128 v[148:151], v233 offset:32768
	ds_read_b128 v[152:155], v233 offset:33792
	ds_read_b128 v[156:159], v233 offset:34816
	ds_read_b128 v[160:163], v233 offset:35840
	ds_read_b128 v[164:167], v233 offset:36864
	ds_read_b128 v[168:171], v233 offset:37888
	ds_read_b128 v[172:175], v233 offset:38912
	ds_read_b128 v[176:179], v233 offset:39936
	global_load_lds_dwordx4 v[6:7], off
	v_lshl_add_u64 v[6:7], s[28:29], 0, v[202:203]
	s_mov_b32 m0, s52
	s_nop 0
	global_load_lds_dwordx4 v[6:7], off
	s_add_i32 s65, 0, 0x1c000
	s_add_u32 s28, s26, 0x8000
	s_addc_u32 s29, s27, 0
	s_add_i32 s64, s64, s48
	v_add_u32_e32 v1, s65, v231
	v_lshl_add_u64 v[252:253], s[28:29], 0, v[196:197]
	s_mov_b32 m0, s64
	ds_read_b128 v[180:183], v1
	ds_read_b128 v[184:187], v1 offset:1024
	ds_read_b128 v[188:191], v1 offset:2048
	ds_read_b128 v[192:195], v1 offset:3072
	s_waitcnt vmcnt(8)
	s_waitcnt lgkmcnt(0)
	s_barrier
	v_mfma_f32_16x16x32_bf16 v[2:5], v[132:135], v[148:151], v[2:5]
	v_mfma_f32_16x16x32_bf16 v[8:11], v[140:143], v[148:151], v[8:11]
	v_mfma_f32_16x16x32_bf16 v[32:35], v[132:135], v[156:159], v[32:35]
	v_mfma_f32_16x16x32_bf16 v[28:31], v[140:143], v[156:159], v[28:31]
	v_mfma_f32_16x16x32_bf16 v[24:27], v[132:135], v[164:167], v[24:27]
	v_mfma_f32_16x16x32_bf16 v[20:23], v[140:143], v[164:167], v[20:23]
	v_mfma_f32_16x16x32_bf16 v[16:19], v[132:135], v[172:175], v[16:19]
	v_mfma_f32_16x16x32_bf16 v[12:15], v[140:143], v[172:175], v[12:15]
	v_mfma_f32_16x16x32_bf16 v[4:7], v[136:139], v[152:155], v[2:5]
	v_mfma_f32_16x16x32_bf16 v[8:11], v[144:147], v[152:155], v[8:11]
	v_mfma_f32_16x16x32_bf16 v[32:35], v[136:139], v[160:163], v[32:35]
	v_mfma_f32_16x16x32_bf16 v[28:31], v[144:147], v[160:163], v[28:31]
	v_mfma_f32_16x16x32_bf16 v[24:27], v[136:139], v[168:171], v[24:27]
	v_mfma_f32_16x16x32_bf16 v[20:23], v[144:147], v[168:171], v[20:23]
	v_mfma_f32_16x16x32_bf16 v[16:19], v[136:139], v[176:179], v[16:19]
	v_mfma_f32_16x16x32_bf16 v[12:15], v[144:147], v[176:179], v[12:15]
	v_mfma_f32_16x16x32_bf16 v[128:131], v[180:183], v[148:151], v[128:131]
	v_mfma_f32_16x16x32_bf16 v[124:127], v[188:191], v[148:151], v[124:127]
	v_mfma_f32_16x16x32_bf16 v[120:123], v[180:183], v[156:159], v[120:123]
	v_mfma_f32_16x16x32_bf16 v[116:119], v[188:191], v[156:159], v[116:119]
	v_mfma_f32_16x16x32_bf16 v[112:115], v[180:183], v[164:167], v[112:115]
	v_mfma_f32_16x16x32_bf16 v[108:111], v[188:191], v[164:167], v[108:111]
	v_mfma_f32_16x16x32_bf16 v[104:107], v[180:183], v[172:175], v[104:107]
	v_mfma_f32_16x16x32_bf16 v[100:103], v[188:191], v[172:175], v[100:103]
	v_mfma_f32_16x16x32_bf16 v[128:131], v[184:187], v[152:155], v[128:131]
	v_mfma_f32_16x16x32_bf16 v[124:127], v[192:195], v[152:155], v[124:127]
	v_mfma_f32_16x16x32_bf16 v[120:123], v[184:187], v[160:163], v[120:123]
	v_mfma_f32_16x16x32_bf16 v[116:119], v[192:195], v[160:163], v[116:119]
	v_mfma_f32_16x16x32_bf16 v[112:115], v[184:187], v[168:171], v[112:115]
	v_mfma_f32_16x16x32_bf16 v[108:111], v[192:195], v[168:171], v[108:111]
	v_mfma_f32_16x16x32_bf16 v[104:107], v[184:187], v[176:179], v[104:107]
	v_mfma_f32_16x16x32_bf16 v[100:103], v[192:195], v[176:179], v[100:103]
	s_barrier
; #define PG8_STAGE(bufoff, gbase, voff) do { _Pragma("unroll") for (int _i = 0; _i < 2; ++_i) \
;         __builtin_amdgcn_global_load_lds((const unsigned*)((const char*)(gbase) + (voff)[_i]), (PG8_LAS unsigned*)(lds + (bufoff) + ldsw + _i * 8192), 16, 0, 0); } while (0)
; #define PG8_LDA(dst, b, h) do { _Pragma("unroll") for (int m = 0; m < 4; ++m) _Pragma("unroll") for (int k = 0; k < 2; ++k) dst[m][k] = *(const PG8_LAS bf16x8*)(lds + PG8_SA(b, h) + aoff + m * 2048 + k * 1024); } while (0)
; #define PG8_LDB(dst, b, h) do { _Pragma("unroll") for (int n = 0; n < 2; ++n) _Pragma("unroll") for (int k = 0; k < 2; ++k) dst[n][k] = *(const PG8_LAS bf16x8*)(lds + PG8_SB(b, h) + boff + n * 2048 + k * 1024); } while (0)
; #define PG8_MMA(ai, bj, At, Bt) do { __builtin_amdgcn_s_setprio(1); _Pragma("unroll") for (int m = 0; m < 4; ++m) _Pragma("unroll") for (int n = 0; n < 2; ++n) _Pragma("unroll") for (int k = 0; k < 2; ++k) \
;         acc[ai][bj][m][n] = __builtin_amdgcn_mfma_f32_16x16x32_bf16(Bt[n][k], At[m][k], acc[ai][bj][m][n], 0, 0, 0); __builtin_amdgcn_s_setprio(0); } while (0)
; #define PG8_WAIT_V(n) asm volatile("s_waitcnt vmcnt(" #n ")" ::: "memory")
; #define PG8_WAIT_L(n) asm volatile("s_waitcnt lgkmcnt(" #n ")" ::: "memory")
; #define PG8_BAR __builtin_amdgcn_s_barrier()
; #define PG8_SCHED __builtin_amdgcn_sched_barrier(0)
; template <class Epi, class Sched>
; __device__ __forceinline__ void gemm_phase(PG8_LAS unsigned char* lds, const Gemm g, const Sched& S, const Epi& E) {
;     ...
;             PG8_LDB(B1, 1, 1); PG8_STAGE(PG8_SB(1, 0), b3, voffB);
;             PG8_BAR; PG8_WAIT_L(0); PG8_MMA(0, 1, At, B1); PG8_BAR;
;             PG8_LDA(At, 1, 1); PG8_STAGE(PG8_SA(1, 0), a3, voffA);
;             PG8_BAR; PG8_WAIT_L(0); PG8_MMA(1, 0, At, B0); PG8_BAR; PG8_SCHED;
;             PG8_STAGE(PG8_SB(1, 1), b3 + hstepB, voffB);
;             PG8_WAIT_V(6); PG8_BAR; PG8_MMA(1, 1, At, B1); PG8_BAR;
;         }
	global_load_lds_dwordx4 v[252:253], off
	v_lshl_add_u64 v[252:253], s[28:29], 0, v[200:201]
	s_add_i32 m0, s64, 0x2000
	s_nop 0
	global_load_lds_dwordx4 v[252:253], off
	s_mov_b32 m0, s55
	v_lshl_add_u64 v[2:3], v[212:213], 0, s[12:13]
	ds_read_b128 v[148:151], v233 offset:49152
	ds_read_b128 v[152:155], v233 offset:50176
	ds_read_b128 v[156:159], v233 offset:51200
	ds_read_b128 v[160:163], v233 offset:52224
	ds_read_b128 v[164:167], v233 offset:53248
	ds_read_b128 v[168:171], v233 offset:54272
	ds_read_b128 v[172:175], v233 offset:55296
	ds_read_b128 v[176:179], v233 offset:56320
	global_load_lds_dwordx4 v[2:3], off
	v_lshl_add_u64 v[2:3], v[214:215], 0, s[12:13]
	s_mov_b32 m0, s56
	s_nop 0
	global_load_lds_dwordx4 v[2:3], off
	s_add_u32 s26, s26, 0xc000
	s_addc_u32 s27, s27, 0
	s_add_i32 s28, s65, s48
	v_lshl_add_u64 v[2:3], s[26:27], 0, v[196:197]
	s_mov_b32 m0, s28
	s_nop 0
	global_load_lds_dwordx4 v[2:3], off
	v_lshl_add_u64 v[2:3], s[26:27], 0, v[200:201]
	s_add_i32 m0, s28, 0x2000
	s_nop 0
	global_load_lds_dwordx4 v[2:3], off
	s_waitcnt vmcnt(8)
	s_waitcnt lgkmcnt(0)
	s_barrier
	v_mfma_f32_16x16x32_bf16 v[96:99], v[132:135], v[148:151], v[96:99]
	v_mfma_f32_16x16x32_bf16 v[92:95], v[140:143], v[148:151], v[92:95]
	v_mfma_f32_16x16x32_bf16 v[88:91], v[132:135], v[156:159], v[88:91]
	v_mfma_f32_16x16x32_bf16 v[84:87], v[140:143], v[156:159], v[84:87]
	v_mfma_f32_16x16x32_bf16 v[80:83], v[132:135], v[164:167], v[80:83]
	v_mfma_f32_16x16x32_bf16 v[76:79], v[140:143], v[164:167], v[76:79]
	v_mfma_f32_16x16x32_bf16 v[72:75], v[132:135], v[172:175], v[72:75]
	v_mfma_f32_16x16x32_bf16 v[68:71], v[140:143], v[172:175], v[68:71]
	v_mfma_f32_16x16x32_bf16 v[96:99], v[136:139], v[152:155], v[96:99]
	v_mfma_f32_16x16x32_bf16 v[92:95], v[144:147], v[152:155], v[92:95]
	v_mfma_f32_16x16x32_bf16 v[88:91], v[136:139], v[160:163], v[88:91]
	v_mfma_f32_16x16x32_bf16 v[84:87], v[144:147], v[160:163], v[84:87]
	v_mfma_f32_16x16x32_bf16 v[80:83], v[136:139], v[168:171], v[80:83]
	v_mfma_f32_16x16x32_bf16 v[76:79], v[144:147], v[168:171], v[76:79]
	v_mfma_f32_16x16x32_bf16 v[72:75], v[136:139], v[176:179], v[72:75]
	v_mfma_f32_16x16x32_bf16 v[68:71], v[144:147], v[176:179], v[68:71]
	v_mfma_f32_16x16x32_bf16 v[64:67], v[180:183], v[148:151], v[64:67]
	v_mfma_f32_16x16x32_bf16 v[60:63], v[188:191], v[148:151], v[60:63]
	v_mfma_f32_16x16x32_bf16 v[56:59], v[180:183], v[156:159], v[56:59]
	v_mfma_f32_16x16x32_bf16 v[52:55], v[188:191], v[156:159], v[52:55]
	v_mfma_f32_16x16x32_bf16 v[48:51], v[180:183], v[164:167], v[48:51]
	v_mfma_f32_16x16x32_bf16 v[44:47], v[188:191], v[164:167], v[44:47]
	v_mfma_f32_16x16x32_bf16 v[40:43], v[180:183], v[172:175], v[40:43]
	v_mfma_f32_16x16x32_bf16 v[36:39], v[188:191], v[172:175], v[36:39]
	v_mfma_f32_16x16x32_bf16 v[64:67], v[184:187], v[152:155], v[64:67]
	v_mfma_f32_16x16x32_bf16 v[60:63], v[192:195], v[152:155], v[60:63]
	v_mfma_f32_16x16x32_bf16 v[56:59], v[184:187], v[160:163], v[56:59]
	v_mfma_f32_16x16x32_bf16 v[52:55], v[192:195], v[160:163], v[52:55]
	v_mfma_f32_16x16x32_bf16 v[48:51], v[184:187], v[168:171], v[48:51]
	v_mfma_f32_16x16x32_bf16 v[44:47], v[192:195], v[168:171], v[44:47]
	v_mfma_f32_16x16x32_bf16 v[40:43], v[184:187], v[176:179], v[40:43]
	v_mfma_f32_16x16x32_bf16 v[36:39], v[192:195], v[176:179], v[36:39]
	s_add_i32 s63, s63, 2
	s_add_u32 s61, s61, 0x10000
	s_addc_u32 s62, s62, 0
	s_add_u32 s24, s24, 0x100
	s_addc_u32 s25, s25, 0
	s_cmp_gt_u32 s63, 13
	s_barrier
	s_cbranch_scc0 .LBB0_613
	s_cmp_eq_u32 s78, 0
	s_cbranch_scc0 .Lhalf_skip_x_4
	s_barrier

; #define PG8_STAGE(bufoff, gbase, voff) do { _Pragma("unroll") for (int _i = 0; _i < 2; ++_i) \
;         __builtin_amdgcn_global_load_lds((const unsigned*)((const char*)(gbase) + (voff)[_i]), (PG8_LAS unsigned*)(lds + (bufoff) + ldsw + _i * 8192), 16, 0, 0); } while (0)
; #define PG8_LDA(dst, b, h) do { _Pragma("unroll") for (int m = 0; m < 4; ++m) _Pragma("unroll") for (int k = 0; k < 2; ++k) dst[m][k] = *(const PG8_LAS bf16x8*)(lds + PG8_SA(b, h) + aoff + m * 2048 + k * 1024); } while (0)
; #define PG8_LDB(dst, b, h) do { _Pragma("unroll") for (int n = 0; n < 2; ++n) _Pragma("unroll") for (int k = 0; k < 2; ++k) dst[n][k] = *(const PG8_LAS bf16x8*)(lds + PG8_SB(b, h) + boff + n * 2048 + k * 1024); } while (0)
; #define PG8_MMA(ai, bj, At, Bt) do { __builtin_amdgcn_s_setprio(1); _Pragma("unroll") for (int m = 0; m < 4; ++m) _Pragma("unroll") for (int n = 0; n < 2; ++n) _Pragma("unroll") for (int k = 0; k < 2; ++k) \
;         acc[ai][bj][m][n] = __builtin_amdgcn_mfma_f32_16x16x32_bf16(Bt[n][k], At[m][k], acc[ai][bj][m][n], 0, 0, 0); __builtin_amdgcn_s_setprio(0); } while (0)
; #define PG8_WAIT_V(n) asm volatile("s_waitcnt vmcnt(" #n ")" ::: "memory")
; template <class Epi, class Sched>
; __device__ __forceinline__ void gemm_phase(PG8_LAS unsigned char* lds, const Gemm g, const Sched& S, const Epi& E) {
;     ...
;         for (int t = 0; t < nt; t += 2) {
;             const bool last = (t == nt - 2);
;             const char* a1 = cA + (size_t)(t + 1) * kstep;
;             const char* a2 = last ? nA : cA + (size_t)(t + 2) * kstep; const char* b2 = last ? nB : cB + (size_t)(t + 2) * kstepB;
;             const char* a3 = a2 + kstep; const char* b3 = b2 + kstepB;
;             if (last && has_next) S.a_ready(nxt);
;             PG8_LDB(B0, 0, 0); PG8_SCHED; PG8_LDA(At, 0, 0); PG8_STAGE(PG8_SA(1, 1), a1 + hstep, voffA);
;             PG8_WAIT_L(8); PG8_BAR; PG8_WAIT_L(0); PG8_MMA(0, 0, At, B0); PG8_BAR; PG8_SCHED;
;             PG8_LDB(B1, 0, 1); PG8_STAGE(PG8_SB(0, 0), b2, voffB);
;             PG8_BAR; PG8_WAIT_L(0); PG8_MMA(0, 1, At, B1); PG8_BAR;
;             PG8_LDA(At, 0, 1); PG8_STAGE(PG8_SA(0, 0), a2, voffA);
;             PG8_BAR; PG8_WAIT_L(0); PG8_MMA(1, 0, At, B0); PG8_BAR; PG8_SCHED;
;             PG8_STAGE(PG8_SB(0, 1), b2 + hstepB, voffB);
;             PG8_WAIT_V(6); PG8_BAR; PG8_MMA(1, 1, At, B1); PG8_BAR;
.Lhalf_skip_y_5:
.LBB0_783:
	ds_read_b128 v[128:131], v197
	ds_read_b128 v[132:135], v197 offset:1024
	ds_read_b128 v[136:139], v197 offset:2048
	ds_read_b128 v[140:143], v197 offset:3072
	s_add_u32 s30, s28, 0x100
	s_addc_u32 s31, s29, 0
	s_cmp_eq_u32 s69, 28
	s_cselect_b32 s39, s19, s31
	s_cselect_b32 s38, s65, s30
	s_cselect_b32 s37, s21, s68
	s_cselect_b32 s36, s66, s67
	v_lshl_add_u64 v[192:193], s[28:29], 0, v[172:173]
	s_add_i32 m0, s27, 0xc000
	ds_read_b128 v[144:147], v198
	ds_read_b128 v[148:151], v198 offset:1024
	ds_read_b128 v[152:155], v198 offset:2048
	ds_read_b128 v[156:159], v198 offset:3072
	ds_read_b128 v[160:163], v198 offset:4096
	ds_read_b128 v[180:183], v198 offset:5120
	ds_read_b128 v[184:187], v198 offset:6144
	ds_read_b128 v[188:191], v198 offset:7168
	global_load_lds_dwordx4 v[192:193], off
	v_lshl_add_u64 v[192:193], s[28:29], 0, v[174:175]
	s_add_i32 m0, s27, 0xe000
	s_nop 0
	global_load_lds_dwordx4 v[192:193], off
	s_add_i32 s28, s62, s54
	v_lshl_add_u64 v[192:193], s[36:37], 0, v[164:165]
	s_mov_b32 m0, s28
	ds_read_b128 v[200:203], v199
	ds_read_b128 v[204:207], v199 offset:1024
	ds_read_b128 v[208:211], v199 offset:2048
	ds_read_b128 v[212:215], v199 offset:3072
	s_waitcnt vmcnt(8)
	s_waitcnt lgkmcnt(0)
	s_barrier
	v_mfma_f32_16x16x32_bf16 v[124:127], v[128:131], v[144:147], v[124:127]
	v_mfma_f32_16x16x32_bf16 v[120:123], v[136:139], v[144:147], v[120:123]
	v_mfma_f32_16x16x32_bf16 v[116:119], v[128:131], v[152:155], v[116:119]
	v_mfma_f32_16x16x32_bf16 v[104:107], v[136:139], v[152:155], v[104:107]
	v_mfma_f32_16x16x32_bf16 v[92:95], v[128:131], v[160:163], v[92:95]
	v_mfma_f32_16x16x32_bf16 v[88:91], v[136:139], v[160:163], v[88:91]
	v_mfma_f32_16x16x32_bf16 v[76:79], v[128:131], v[184:187], v[76:79]
	v_mfma_f32_16x16x32_bf16 v[72:75], v[136:139], v[184:187], v[72:75]
	v_mfma_f32_16x16x32_bf16 v[124:127], v[132:135], v[148:151], v[124:127]
	v_mfma_f32_16x16x32_bf16 v[120:123], v[140:143], v[148:151], v[120:123]
	v_mfma_f32_16x16x32_bf16 v[116:119], v[132:135], v[156:159], v[116:119]
	v_mfma_f32_16x16x32_bf16 v[104:107], v[140:143], v[156:159], v[104:107]
	v_mfma_f32_16x16x32_bf16 v[92:95], v[132:135], v[180:183], v[92:95]
	v_mfma_f32_16x16x32_bf16 v[88:91], v[140:143], v[180:183], v[88:91]
	v_mfma_f32_16x16x32_bf16 v[76:79], v[132:135], v[188:191], v[76:79]
	v_mfma_f32_16x16x32_bf16 v[72:75], v[140:143], v[188:191], v[72:75]
	v_mfma_f32_16x16x32_bf16 v[112:115], v[200:203], v[144:147], v[112:115]
	v_mfma_f32_16x16x32_bf16 v[108:111], v[208:211], v[144:147], v[108:111]
	v_mfma_f32_16x16x32_bf16 v[100:103], v[200:203], v[152:155], v[100:103]
	v_mfma_f32_16x16x32_bf16 v[96:99], v[208:211], v[152:155], v[96:99]
	v_mfma_f32_16x16x32_bf16 v[84:87], v[200:203], v[160:163], v[84:87]
	v_mfma_f32_16x16x32_bf16 v[80:83], v[208:211], v[160:163], v[80:83]
	v_mfma_f32_16x16x32_bf16 v[68:71], v[200:203], v[184:187], v[68:71]
	v_mfma_f32_16x16x32_bf16 v[64:67], v[208:211], v[184:187], v[64:67]
	v_mfma_f32_16x16x32_bf16 v[112:115], v[204:207], v[148:151], v[112:115]
	v_mfma_f32_16x16x32_bf16 v[108:111], v[212:215], v[148:151], v[108:111]
	v_mfma_f32_16x16x32_bf16 v[100:103], v[204:207], v[156:159], v[100:103]
	v_mfma_f32_16x16x32_bf16 v[96:99], v[212:215], v[156:159], v[96:99]
	v_mfma_f32_16x16x32_bf16 v[84:87], v[204:207], v[180:183], v[84:87]
	v_mfma_f32_16x16x32_bf16 v[80:83], v[212:215], v[180:183], v[80:83]
	v_mfma_f32_16x16x32_bf16 v[68:71], v[204:207], v[188:191], v[68:71]
	v_mfma_f32_16x16x32_bf16 v[64:67], v[212:215], v[188:191], v[64:67]
	s_barrier
	global_load_lds_dwordx4 v[192:193], off
	v_lshl_add_u64 v[192:193], s[36:37], 0, v[168:169]
	s_add_i32 m0, s28, 0x2000
	s_nop 0
	global_load_lds_dwordx4 v[192:193], off
	s_mov_b32 m0, s27
	v_lshl_add_u64 v[192:193], s[38:39], 0, v[166:167]
	ds_read_b128 v[144:147], v198 offset:16384
	ds_read_b128 v[148:151], v198 offset:17408
	ds_read_b128 v[152:155], v198 offset:18432
	ds_read_b128 v[156:159], v198 offset:19456
	ds_read_b128 v[160:163], v198 offset:20480
	ds_read_b128 v[180:183], v198 offset:21504
	ds_read_b128 v[184:187], v198 offset:22528
	ds_read_b128 v[188:191], v198 offset:23552
	global_load_lds_dwordx4 v[192:193], off
	v_lshl_add_u64 v[216:217], s[38:39], 0, v[170:171]
	s_mov_b32 m0, s55
	s_nop 0
	global_load_lds_dwordx4 v[216:217], off
	s_add_u32 s28, s36, 0x4000
	s_addc_u32 s29, s37, 0
	s_add_i32 s70, s63, s54
	v_lshl_add_u64 v[250:251], s[28:29], 0, v[164:165]
	s_mov_b32 m0, s70
	s_nop 0
	global_load_lds_dwordx4 v[250:251], off
	v_lshl_add_u64 v[250:251], s[28:29], 0, v[168:169]
	s_add_i32 m0, s70, 0x2000
	s_nop 0
	global_load_lds_dwordx4 v[250:251], off
	s_waitcnt vmcnt(8)
	s_waitcnt lgkmcnt(0)
	s_barrier
; #define PG8_STAGE(bufoff, gbase, voff) do { _Pragma("unroll") for (int _i = 0; _i < 2; ++_i) \
;         __builtin_amdgcn_global_load_lds((const unsigned*)((const char*)(gbase) + (voff)[_i]), (PG8_LAS unsigned*)(lds + (bufoff) + ldsw + _i * 8192), 16, 0, 0); } while (0)
; #define PG8_LDA(dst, b, h) do { _Pragma("unroll") for (int m = 0; m < 4; ++m) _Pragma("unroll") for (int k = 0; k < 2; ++k) dst[m][k] = *(const PG8_LAS bf16x8*)(lds + PG8_SA(b, h) + aoff + m * 2048 + k * 1024); } while (0)
; #define PG8_LDB(dst, b, h) do { _Pragma("unroll") for (int n = 0; n < 2; ++n) _Pragma("unroll") for (int k = 0; k < 2; ++k) dst[n][k] = *(const PG8_LAS bf16x8*)(lds + PG8_SB(b, h) + boff + n * 2048 + k * 1024); } while (0)
; #define PG8_MMA(ai, bj, At, Bt) do { __builtin_amdgcn_s_setprio(1); _Pragma("unroll") for (int m = 0; m < 4; ++m) _Pragma("unroll") for (int n = 0; n < 2; ++n) _Pragma("unroll") for (int k = 0; k < 2; ++k) \
;         acc[ai][bj][m][n] = __builtin_amdgcn_mfma_f32_16x16x32_bf16(Bt[n][k], At[m][k], acc[ai][bj][m][n], 0, 0, 0); __builtin_amdgcn_s_setprio(0); } while (0)
; #define PG8_WAIT_V(n) asm volatile("s_waitcnt vmcnt(" #n ")" ::: "memory")
; #define PG8_WAIT_L(n) asm volatile("s_waitcnt lgkmcnt(" #n ")" ::: "memory")
; #define PG8_BAR __builtin_amdgcn_s_barrier()
; #define PG8_SCHED __builtin_amdgcn_sched_barrier(0)
; template <class Epi, class Sched>
; __device__ __forceinline__ void gemm_phase(PG8_LAS unsigned char* lds, const Gemm g, const Sched& S, const Epi& E) {
;     ...
;             PG8_BAR; PG8_WAIT_L(0); PG8_MMA(1, 0, At, B0); PG8_BAR; PG8_SCHED;
;             PG8_STAGE(PG8_SB(0, 1), b2 + hstepB, voffB);
;             PG8_WAIT_V(6); PG8_BAR; PG8_MMA(1, 1, At, B1); PG8_BAR;
;             PG8_LDB(B0, 1, 0); PG8_SCHED; PG8_LDA(At, 1, 0); PG8_STAGE(PG8_SA(0, 1), a2 + hstep, voffA);
;             PG8_WAIT_L(8); PG8_BAR; PG8_WAIT_L(0); PG8_MMA(0, 0, At, B0); PG8_BAR; PG8_SCHED;
;             PG8_LDB(B1, 1, 1); PG8_STAGE(PG8_SB(1, 0), b3, voffB);
;             PG8_BAR; PG8_WAIT_L(0); PG8_MMA(0, 1, At, B1); PG8_BAR;
	v_mfma_f32_16x16x32_bf16 v[60:63], v[128:131], v[144:147], v[60:63]
	v_mfma_f32_16x16x32_bf16 v[56:59], v[136:139], v[144:147], v[56:59]
	v_mfma_f32_16x16x32_bf16 v[44:47], v[128:131], v[152:155], v[44:47]
	v_mfma_f32_16x16x32_bf16 v[40:43], v[136:139], v[152:155], v[40:43]
	v_mfma_f32_16x16x32_bf16 v[28:31], v[128:131], v[160:163], v[28:31]
	v_mfma_f32_16x16x32_bf16 v[24:27], v[136:139], v[160:163], v[24:27]
	v_mfma_f32_16x16x32_bf16 v[12:15], v[128:131], v[184:187], v[12:15]
	v_mfma_f32_16x16x32_bf16 v[8:11], v[136:139], v[184:187], v[8:11]
	v_mfma_f32_16x16x32_bf16 v[60:63], v[132:135], v[148:151], v[60:63]
	v_mfma_f32_16x16x32_bf16 v[56:59], v[140:143], v[148:151], v[56:59]
	v_mfma_f32_16x16x32_bf16 v[44:47], v[132:135], v[156:159], v[44:47]
	v_mfma_f32_16x16x32_bf16 v[40:43], v[140:143], v[156:159], v[40:43]
	v_mfma_f32_16x16x32_bf16 v[28:31], v[132:135], v[180:183], v[28:31]
	v_mfma_f32_16x16x32_bf16 v[24:27], v[140:143], v[180:183], v[24:27]
	v_mfma_f32_16x16x32_bf16 v[12:15], v[132:135], v[188:191], v[12:15]
	v_mfma_f32_16x16x32_bf16 v[8:11], v[140:143], v[188:191], v[8:11]
	v_mfma_f32_16x16x32_bf16 v[52:55], v[200:203], v[144:147], v[52:55]
	v_mfma_f32_16x16x32_bf16 v[48:51], v[208:211], v[144:147], v[48:51]
	v_mfma_f32_16x16x32_bf16 v[36:39], v[200:203], v[152:155], v[36:39]
	v_mfma_f32_16x16x32_bf16 v[32:35], v[208:211], v[152:155], v[32:35]
	v_mfma_f32_16x16x32_bf16 v[20:23], v[200:203], v[160:163], v[20:23]
	v_mfma_f32_16x16x32_bf16 v[16:19], v[208:211], v[160:163], v[16:19]
	v_mfma_f32_16x16x32_bf16 v[4:7], v[200:203], v[184:187], v[4:7]
	v_mfma_f32_16x16x32_bf16 v[0:3], v[208:211], v[184:187], v[0:3]
	v_mfma_f32_16x16x32_bf16 v[52:55], v[204:207], v[148:151], v[52:55]
	v_mfma_f32_16x16x32_bf16 v[48:51], v[212:215], v[148:151], v[48:51]
	v_mfma_f32_16x16x32_bf16 v[36:39], v[204:207], v[156:159], v[36:39]
	v_mfma_f32_16x16x32_bf16 v[32:35], v[212:215], v[156:159], v[32:35]
	v_mfma_f32_16x16x32_bf16 v[20:23], v[204:207], v[180:183], v[20:23]
	v_mfma_f32_16x16x32_bf16 v[16:19], v[212:215], v[180:183], v[16:19]
	v_mfma_f32_16x16x32_bf16 v[4:7], v[204:207], v[188:191], v[4:7]
	v_mfma_f32_16x16x32_bf16 v[0:3], v[212:215], v[188:191], v[0:3]
	s_barrier
	s_add_i32 s70, 0, 0x18000
	v_add_u32_e32 v140, s70, v195
	ds_read_b128 v[128:131], v140
	ds_read_b128 v[132:135], v140 offset:1024
	ds_read_b128 v[136:139], v140 offset:2048
	ds_read_b128 v[140:143], v140 offset:3072
	s_add_u32 s28, s38, 0x80000
	s_addc_u32 s29, s39, 0
	s_mov_b32 m0, s56
	v_lshl_add_u64 v[200:201], s[28:29], 0, v[166:167]
	ds_read_b128 v[144:147], v198 offset:32768
	ds_read_b128 v[148:151], v198 offset:33792
	ds_read_b128 v[152:155], v198 offset:34816
	ds_read_b128 v[156:159], v198 offset:35840
	ds_read_b128 v[160:163], v198 offset:36864
	ds_read_b128 v[180:183], v198 offset:37888
	ds_read_b128 v[184:187], v198 offset:38912
	ds_read_b128 v[188:191], v198 offset:39936
	global_load_lds_dwordx4 v[200:201], off
	v_lshl_add_u64 v[200:201], s[28:29], 0, v[170:171]
	s_mov_b32 m0, s57
	s_nop 0
	global_load_lds_dwordx4 v[200:201], off
	s_add_i32 s38, 0, 0x1c000
	s_add_u32 s28, s36, 0x8000
	s_addc_u32 s29, s37, 0
	s_add_i32 s39, s70, s54
	v_add_u32_e32 v212, s38, v195
	v_lshl_add_u64 v[218:219], s[28:29], 0, v[164:165]
	s_mov_b32 m0, s39
	ds_read_b128 v[200:203], v212
	ds_read_b128 v[204:207], v212 offset:1024
	ds_read_b128 v[208:211], v212 offset:2048
	ds_read_b128 v[212:215], v212 offset:3072
	s_waitcnt vmcnt(8)
	s_waitcnt lgkmcnt(0)
	s_barrier
	v_mfma_f32_16x16x32_bf16 v[124:127], v[128:131], v[144:147], v[124:127]
	v_mfma_f32_16x16x32_bf16 v[120:123], v[136:139], v[144:147], v[120:123]
	v_mfma_f32_16x16x32_bf16 v[116:119], v[128:131], v[152:155], v[116:119]
	v_mfma_f32_16x16x32_bf16 v[104:107], v[136:139], v[152:155], v[104:107]
	v_mfma_f32_16x16x32_bf16 v[92:95], v[128:131], v[160:163], v[92:95]
	v_mfma_f32_16x16x32_bf16 v[88:91], v[136:139], v[160:163], v[88:91]
	v_mfma_f32_16x16x32_bf16 v[76:79], v[128:131], v[184:187], v[76:79]
	v_mfma_f32_16x16x32_bf16 v[72:75], v[136:139], v[184:187], v[72:75]
	v_mfma_f32_16x16x32_bf16 v[124:127], v[132:135], v[148:151], v[124:127]
	v_mfma_f32_16x16x32_bf16 v[120:123], v[140:143], v[148:151], v[120:123]
	v_mfma_f32_16x16x32_bf16 v[116:119], v[132:135], v[156:159], v[116:119]
	v_mfma_f32_16x16x32_bf16 v[104:107], v[140:143], v[156:159], v[104:107]
	v_mfma_f32_16x16x32_bf16 v[92:95], v[132:135], v[180:183], v[92:95]
	v_mfma_f32_16x16x32_bf16 v[88:91], v[140:143], v[180:183], v[88:91]
	v_mfma_f32_16x16x32_bf16 v[76:79], v[132:135], v[188:191], v[76:79]
	v_mfma_f32_16x16x32_bf16 v[72:75], v[140:143], v[188:191], v[72:75]
	v_mfma_f32_16x16x32_bf16 v[112:115], v[200:203], v[144:147], v[112:115]
	v_mfma_f32_16x16x32_bf16 v[108:111], v[208:211], v[144:147], v[108:111]
	v_mfma_f32_16x16x32_bf16 v[100:103], v[200:203], v[152:155], v[100:103]
	v_mfma_f32_16x16x32_bf16 v[96:99], v[208:211], v[152:155], v[96:99]
	v_mfma_f32_16x16x32_bf16 v[84:87], v[200:203], v[160:163], v[84:87]
	v_mfma_f32_16x16x32_bf16 v[80:83], v[208:211], v[160:163], v[80:83]
	v_mfma_f32_16x16x32_bf16 v[68:71], v[200:203], v[184:187], v[68:71]
	v_mfma_f32_16x16x32_bf16 v[64:67], v[208:211], v[184:187], v[64:67]
	v_mfma_f32_16x16x32_bf16 v[112:115], v[204:207], v[148:151], v[112:115]
	v_mfma_f32_16x16x32_bf16 v[108:111], v[212:215], v[148:151], v[108:111]
	v_mfma_f32_16x16x32_bf16 v[100:103], v[204:207], v[156:159], v[100:103]
	v_mfma_f32_16x16x32_bf16 v[96:99], v[212:215], v[156:159], v[96:99]
	v_mfma_f32_16x16x32_bf16 v[84:87], v[204:207], v[180:183], v[84:87]
	v_mfma_f32_16x16x32_bf16 v[80:83], v[212:215], v[180:183], v[80:83]
	v_mfma_f32_16x16x32_bf16 v[68:71], v[204:207], v[188:191], v[68:71]
	v_mfma_f32_16x16x32_bf16 v[64:67], v[212:215], v[188:191], v[64:67]
	s_barrier
; #define PG8_STAGE(bufoff, gbase, voff) do { _Pragma("unroll") for (int _i = 0; _i < 2; ++_i) \
;         __builtin_amdgcn_global_load_lds((const unsigned*)((const char*)(gbase) + (voff)[_i]), (PG8_LAS unsigned*)(lds + (bufoff) + ldsw + _i * 8192), 16, 0, 0); } while (0)
; #define PG8_LDA(dst, b, h) do { _Pragma("unroll") for (int m = 0; m < 4; ++m) _Pragma("unroll") for (int k = 0; k < 2; ++k) dst[m][k] = *(const PG8_LAS bf16x8*)(lds + PG8_SA(b, h) + aoff + m * 2048 + k * 1024); } while (0)
; #define PG8_LDB(dst, b, h) do { _Pragma("unroll") for (int n = 0; n < 2; ++n) _Pragma("unroll") for (int k = 0; k < 2; ++k) dst[n][k] = *(const PG8_LAS bf16x8*)(lds + PG8_SB(b, h) + boff + n * 2048 + k * 1024); } while (0)
; #define PG8_MMA(ai, bj, At, Bt) do { __builtin_amdgcn_s_setprio(1); _Pragma("unroll") for (int m = 0; m < 4; ++m) _Pragma("unroll") for (int n = 0; n < 2; ++n) _Pragma("unroll") for (int k = 0; k < 2; ++k) \
;         acc[ai][bj][m][n] = __builtin_amdgcn_mfma_f32_16x16x32_bf16(Bt[n][k], At[m][k], acc[ai][bj][m][n], 0, 0, 0); __builtin_amdgcn_s_setprio(0); } while (0)
; #define PG8_WAIT_V(n) asm volatile("s_waitcnt vmcnt(" #n ")" ::: "memory")
; #define PG8_WAIT_L(n) asm volatile("s_waitcnt lgkmcnt(" #n ")" ::: "memory")
; #define PG8_BAR __builtin_amdgcn_s_barrier()
; #define PG8_SCHED __builtin_amdgcn_sched_barrier(0)
; template <class Epi, class Sched>
; __device__ __forceinline__ void gemm_phase(PG8_LAS unsigned char* lds, const Gemm g, const Sched& S, const Epi& E) {
;     ...
;             PG8_LDB(B1, 1, 1); PG8_STAGE(PG8_SB(1, 0), b3, voffB);
;             PG8_BAR; PG8_WAIT_L(0); PG8_MMA(0, 1, At, B1); PG8_BAR;
;             PG8_LDA(At, 1, 1); PG8_STAGE(PG8_SA(1, 0), a3, voffA);
;             PG8_BAR; PG8_WAIT_L(0); PG8_MMA(1, 0, At, B0); PG8_BAR; PG8_SCHED;
;             PG8_STAGE(PG8_SB(1, 1), b3 + hstepB, voffB);
;             PG8_WAIT_V(6); PG8_BAR; PG8_MMA(1, 1, At, B1); PG8_BAR;
;         }
	global_load_lds_dwordx4 v[218:219], off
	v_lshl_add_u64 v[218:219], s[28:29], 0, v[168:169]
	s_add_i32 m0, s39, 0x2000
	s_nop 0
	global_load_lds_dwordx4 v[218:219], off
	s_mov_b32 m0, s59
	v_lshl_add_u64 v[192:193], v[192:193], 0, s[10:11]
	ds_read_b128 v[144:147], v198 offset:49152
	ds_read_b128 v[148:151], v198 offset:50176
	ds_read_b128 v[152:155], v198 offset:51200
	ds_read_b128 v[156:159], v198 offset:52224
	ds_read_b128 v[160:163], v198 offset:53248
	ds_read_b128 v[180:183], v198 offset:54272
	ds_read_b128 v[184:187], v198 offset:55296
	ds_read_b128 v[188:191], v198 offset:56320
	global_load_lds_dwordx4 v[192:193], off
	v_lshl_add_u64 v[192:193], v[216:217], 0, s[10:11]
	s_mov_b32 m0, s60
	s_nop 0
	global_load_lds_dwordx4 v[192:193], off
	s_add_u32 s28, s36, 0xc000
	s_addc_u32 s29, s37, 0
	s_add_i32 s36, s38, s54
	v_lshl_add_u64 v[252:253], s[28:29], 0, v[164:165]
	s_mov_b32 m0, s36
	s_nop 0
	global_load_lds_dwordx4 v[252:253], off
	v_lshl_add_u64 v[252:253], s[28:29], 0, v[168:169]
	s_add_i32 m0, s36, 0x2000
	s_nop 0
	global_load_lds_dwordx4 v[252:253], off
	s_waitcnt vmcnt(8)
	s_waitcnt lgkmcnt(0)
	s_barrier
	v_mfma_f32_16x16x32_bf16 v[60:63], v[128:131], v[144:147], v[60:63]
	v_mfma_f32_16x16x32_bf16 v[56:59], v[136:139], v[144:147], v[56:59]
	v_mfma_f32_16x16x32_bf16 v[44:47], v[128:131], v[152:155], v[44:47]
	v_mfma_f32_16x16x32_bf16 v[40:43], v[136:139], v[152:155], v[40:43]
	v_mfma_f32_16x16x32_bf16 v[28:31], v[128:131], v[160:163], v[28:31]
	v_mfma_f32_16x16x32_bf16 v[24:27], v[136:139], v[160:163], v[24:27]
	v_mfma_f32_16x16x32_bf16 v[12:15], v[128:131], v[184:187], v[12:15]
	v_mfma_f32_16x16x32_bf16 v[8:11], v[136:139], v[184:187], v[8:11]
	v_mfma_f32_16x16x32_bf16 v[60:63], v[132:135], v[148:151], v[60:63]
	v_mfma_f32_16x16x32_bf16 v[56:59], v[140:143], v[148:151], v[56:59]
	v_mfma_f32_16x16x32_bf16 v[44:47], v[132:135], v[156:159], v[44:47]
	v_mfma_f32_16x16x32_bf16 v[40:43], v[140:143], v[156:159], v[40:43]
	v_mfma_f32_16x16x32_bf16 v[28:31], v[132:135], v[180:183], v[28:31]
	v_mfma_f32_16x16x32_bf16 v[24:27], v[140:143], v[180:183], v[24:27]
	v_mfma_f32_16x16x32_bf16 v[12:15], v[132:135], v[188:191], v[12:15]
	v_mfma_f32_16x16x32_bf16 v[8:11], v[140:143], v[188:191], v[8:11]
	v_mfma_f32_16x16x32_bf16 v[52:55], v[200:203], v[144:147], v[52:55]
	v_mfma_f32_16x16x32_bf16 v[48:51], v[208:211], v[144:147], v[48:51]
	v_mfma_f32_16x16x32_bf16 v[36:39], v[200:203], v[152:155], v[36:39]
	v_mfma_f32_16x16x32_bf16 v[32:35], v[208:211], v[152:155], v[32:35]
	v_mfma_f32_16x16x32_bf16 v[20:23], v[200:203], v[160:163], v[20:23]
	v_mfma_f32_16x16x32_bf16 v[16:19], v[208:211], v[160:163], v[16:19]
	v_mfma_f32_16x16x32_bf16 v[4:7], v[200:203], v[184:187], v[4:7]
	v_mfma_f32_16x16x32_bf16 v[0:3], v[208:211], v[184:187], v[0:3]
	v_mfma_f32_16x16x32_bf16 v[52:55], v[204:207], v[148:151], v[52:55]
	v_mfma_f32_16x16x32_bf16 v[48:51], v[212:215], v[148:151], v[48:51]
	v_mfma_f32_16x16x32_bf16 v[36:39], v[204:207], v[156:159], v[36:39]
	v_mfma_f32_16x16x32_bf16 v[32:35], v[212:215], v[156:159], v[32:35]
	v_mfma_f32_16x16x32_bf16 v[20:23], v[204:207], v[180:183], v[20:23]
	v_mfma_f32_16x16x32_bf16 v[16:19], v[212:215], v[180:183], v[16:19]
	v_mfma_f32_16x16x32_bf16 v[4:7], v[204:207], v[188:191], v[4:7]
	v_mfma_f32_16x16x32_bf16 v[0:3], v[212:215], v[188:191], v[0:3]
	s_add_i32 s69, s69, 2
	s_add_u32 s67, s67, 0x10000
	s_addc_u32 s68, s68, 0
	s_cmp_gt_u32 s69, 29
	s_mov_b64 s[28:29], s[30:31]
	s_barrier
	s_cbranch_scc0 .LBB0_783
	s_cmp_eq_u32 s78, 0
	s_cbranch_scc0 .Lhalf_skip_x_5
	s_barrier

; #define PG8_STAGE(bufoff, gbase, voff) do { _Pragma("unroll") for (int _i = 0; _i < 2; ++_i) \
;         __builtin_amdgcn_global_load_lds((const unsigned*)((const char*)(gbase) + (voff)[_i]), (PG8_LAS unsigned*)(lds + (bufoff) + ldsw + _i * 8192), 16, 0, 0); } while (0)
; #define PG8_LDA(dst, b, h) do { _Pragma("unroll") for (int m = 0; m < 4; ++m) _Pragma("unroll") for (int k = 0; k < 2; ++k) dst[m][k] = *(const PG8_LAS bf16x8*)(lds + PG8_SA(b, h) + aoff + m * 2048 + k * 1024); } while (0)
; #define PG8_LDB(dst, b, h) do { _Pragma("unroll") for (int n = 0; n < 2; ++n) _Pragma("unroll") for (int k = 0; k < 2; ++k) dst[n][k] = *(const PG8_LAS bf16x8*)(lds + PG8_SB(b, h) + boff + n * 2048 + k * 1024); } while (0)
; #define PG8_MMA(ai, bj, At, Bt) do { __builtin_amdgcn_s_setprio(1); _Pragma("unroll") for (int m = 0; m < 4; ++m) _Pragma("unroll") for (int n = 0; n < 2; ++n) _Pragma("unroll") for (int k = 0; k < 2; ++k) \
;         acc[ai][bj][m][n] = __builtin_amdgcn_mfma_f32_16x16x32_bf16(Bt[n][k], At[m][k], acc[ai][bj][m][n], 0, 0, 0); __builtin_amdgcn_s_setprio(0); } while (0)
; #define PG8_WAIT_V(n) asm volatile("s_waitcnt vmcnt(" #n ")" ::: "memory")
; template <class Epi, class Sched>
; __device__ __forceinline__ void gemm_phase(PG8_LAS unsigned char* lds, const Gemm g, const Sched& S, const Epi& E) {
;     ...
;         for (int t = 0; t < nt; t += 2) {
;             const bool last = (t == nt - 2);
;             const char* a1 = cA + (size_t)(t + 1) * kstep;
;             const char* a2 = last ? nA : cA + (size_t)(t + 2) * kstep; const char* b2 = last ? nB : cB + (size_t)(t + 2) * kstepB;
;             const char* a3 = a2 + kstep; const char* b3 = b2 + kstepB;
;             if (last && has_next) S.a_ready(nxt);
;             PG8_LDB(B0, 0, 0); PG8_SCHED; PG8_LDA(At, 0, 0); PG8_STAGE(PG8_SA(1, 1), a1 + hstep, voffA);
;             PG8_WAIT_L(8); PG8_BAR; PG8_WAIT_L(0); PG8_MMA(0, 0, At, B0); PG8_BAR; PG8_SCHED;
;             PG8_LDB(B1, 0, 1); PG8_STAGE(PG8_SB(0, 0), b2, voffB);
;             PG8_BAR; PG8_WAIT_L(0); PG8_MMA(0, 1, At, B1); PG8_BAR;
;             PG8_LDA(At, 0, 1); PG8_STAGE(PG8_SA(0, 0), a2, voffA);
;             PG8_BAR; PG8_WAIT_L(0); PG8_MMA(1, 0, At, B0); PG8_BAR; PG8_SCHED;
;             PG8_STAGE(PG8_SB(0, 1), b2 + hstepB, voffB);
;             PG8_WAIT_V(6); PG8_BAR; PG8_MMA(1, 1, At, B1); PG8_BAR;
.Lhalf_skip_y_6:
.LBB0_904:
	ds_read_b128 v[152:155], v149
	ds_read_b128 v[156:159], v149 offset:1024
	ds_read_b128 v[160:163], v149 offset:2048
	ds_read_b128 v[164:167], v149 offset:3072
	s_add_u32 s22, s20, 0xfff80080
	s_addc_u32 s23, s21, -1
	s_cmp_eq_u32 s61, 28
	s_cselect_b32 s25, s11, s23
	s_cselect_b32 s24, s57, s22
	s_cselect_b32 s23, s13, s60
	s_cselect_b32 s22, s58, s59
	v_lshl_add_u64 v[144:145], s[20:21], 0, v[136:137]
	s_add_i32 m0, s19, 0xc000
	ds_read_b128 v[168:171], v150
	ds_read_b128 v[172:175], v150 offset:1024
	ds_read_b128 v[176:179], v150 offset:2048
	ds_read_b128 v[180:183], v150 offset:3072
	ds_read_b128 v[184:187], v150 offset:4096
	ds_read_b128 v[188:191], v150 offset:5120
	ds_read_b128 v[192:195], v150 offset:6144
	ds_read_b128 v[196:199], v150 offset:7168
	global_load_lds_dwordx4 v[144:145], off
	v_lshl_add_u64 v[144:145], s[20:21], 0, v[138:139]
	s_add_i32 m0, s19, 0xe000
	s_nop 0
	global_load_lds_dwordx4 v[144:145], off
	s_add_i32 s62, s53, s38
	v_lshl_add_u64 v[144:145], s[22:23], 0, v[128:129]
	s_mov_b32 m0, s62
	ds_read_b128 v[200:203], v151
	ds_read_b128 v[204:207], v151 offset:1024
	ds_read_b128 v[208:211], v151 offset:2048
	ds_read_b128 v[212:215], v151 offset:3072
	s_waitcnt vmcnt(8)
	s_waitcnt lgkmcnt(0)
	s_barrier
	v_mfma_f32_16x16x32_bf16 v[124:127], v[152:155], v[168:171], v[124:127]
	v_mfma_f32_16x16x32_bf16 v[120:123], v[160:163], v[168:171], v[120:123]
	v_mfma_f32_16x16x32_bf16 v[108:111], v[152:155], v[176:179], v[108:111]
	v_mfma_f32_16x16x32_bf16 v[104:107], v[160:163], v[176:179], v[104:107]
	v_mfma_f32_16x16x32_bf16 v[92:95], v[152:155], v[184:187], v[92:95]
	v_mfma_f32_16x16x32_bf16 v[88:91], v[160:163], v[184:187], v[88:91]
	v_mfma_f32_16x16x32_bf16 v[76:79], v[152:155], v[192:195], v[76:79]
	v_mfma_f32_16x16x32_bf16 v[72:75], v[160:163], v[192:195], v[72:75]
	v_mfma_f32_16x16x32_bf16 v[124:127], v[156:159], v[172:175], v[124:127]
	v_mfma_f32_16x16x32_bf16 v[120:123], v[164:167], v[172:175], v[120:123]
	v_mfma_f32_16x16x32_bf16 v[108:111], v[156:159], v[180:183], v[108:111]
	v_mfma_f32_16x16x32_bf16 v[104:107], v[164:167], v[180:183], v[104:107]
	v_mfma_f32_16x16x32_bf16 v[92:95], v[156:159], v[188:191], v[92:95]
	v_mfma_f32_16x16x32_bf16 v[88:91], v[164:167], v[188:191], v[88:91]
	v_mfma_f32_16x16x32_bf16 v[76:79], v[156:159], v[196:199], v[76:79]
	v_mfma_f32_16x16x32_bf16 v[72:75], v[164:167], v[196:199], v[72:75]
	v_mfma_f32_16x16x32_bf16 v[116:119], v[200:203], v[168:171], v[116:119]
	v_mfma_f32_16x16x32_bf16 v[112:115], v[208:211], v[168:171], v[112:115]
	v_mfma_f32_16x16x32_bf16 v[100:103], v[200:203], v[176:179], v[100:103]
	v_mfma_f32_16x16x32_bf16 v[96:99], v[208:211], v[176:179], v[96:99]
	v_mfma_f32_16x16x32_bf16 v[84:87], v[200:203], v[184:187], v[84:87]
	v_mfma_f32_16x16x32_bf16 v[80:83], v[208:211], v[184:187], v[80:83]
	v_mfma_f32_16x16x32_bf16 v[68:71], v[200:203], v[192:195], v[68:71]
	v_mfma_f32_16x16x32_bf16 v[64:67], v[208:211], v[192:195], v[64:67]
	v_mfma_f32_16x16x32_bf16 v[116:119], v[204:207], v[172:175], v[116:119]
	v_mfma_f32_16x16x32_bf16 v[112:115], v[212:215], v[172:175], v[112:115]
	v_mfma_f32_16x16x32_bf16 v[100:103], v[204:207], v[180:183], v[100:103]
	v_mfma_f32_16x16x32_bf16 v[96:99], v[212:215], v[180:183], v[96:99]
	v_mfma_f32_16x16x32_bf16 v[84:87], v[204:207], v[188:191], v[84:87]
	v_mfma_f32_16x16x32_bf16 v[80:83], v[212:215], v[188:191], v[80:83]
	v_mfma_f32_16x16x32_bf16 v[68:71], v[204:207], v[196:199], v[68:71]
	v_mfma_f32_16x16x32_bf16 v[64:67], v[212:215], v[196:199], v[64:67]
	s_barrier
	global_load_lds_dwordx4 v[144:145], off
	v_lshl_add_u64 v[144:145], s[22:23], 0, v[130:131]
	s_add_i32 m0, s62, 0x2000
	s_nop 0
	global_load_lds_dwordx4 v[144:145], off
	s_mov_b32 m0, s19
	v_lshl_add_u64 v[144:145], s[24:25], 0, v[134:135]
	ds_read_b128 v[168:171], v150 offset:16384
	ds_read_b128 v[172:175], v150 offset:17408
	ds_read_b128 v[176:179], v150 offset:18432
	ds_read_b128 v[180:183], v150 offset:19456
	ds_read_b128 v[184:187], v150 offset:20480
	ds_read_b128 v[188:191], v150 offset:21504
	ds_read_b128 v[192:195], v150 offset:22528
	ds_read_b128 v[196:199], v150 offset:23552
	global_load_lds_dwordx4 v[144:145], off
	v_lshl_add_u64 v[216:217], s[24:25], 0, v[132:133]
	s_mov_b32 m0, s46
	s_nop 0
	global_load_lds_dwordx4 v[216:217], off
	s_add_u32 s62, s22, 0x4000
	s_addc_u32 s63, s23, 0
	s_add_i32 s64, s54, s38
	v_lshl_add_u64 v[250:251], s[62:63], 0, v[128:129]
	s_mov_b32 m0, s64
	s_nop 0
	global_load_lds_dwordx4 v[250:251], off
	v_lshl_add_u64 v[250:251], s[62:63], 0, v[130:131]
	s_add_i32 m0, s64, 0x2000
	s_nop 0
	global_load_lds_dwordx4 v[250:251], off
	s_waitcnt vmcnt(8)
	s_waitcnt lgkmcnt(0)
	s_barrier
; #define PG8_STAGE(bufoff, gbase, voff) do { _Pragma("unroll") for (int _i = 0; _i < 2; ++_i) \
;         __builtin_amdgcn_global_load_lds((const unsigned*)((const char*)(gbase) + (voff)[_i]), (PG8_LAS unsigned*)(lds + (bufoff) + ldsw + _i * 8192), 16, 0, 0); } while (0)
; #define PG8_LDA(dst, b, h) do { _Pragma("unroll") for (int m = 0; m < 4; ++m) _Pragma("unroll") for (int k = 0; k < 2; ++k) dst[m][k] = *(const PG8_LAS bf16x8*)(lds + PG8_SA(b, h) + aoff + m * 2048 + k * 1024); } while (0)
; #define PG8_LDB(dst, b, h) do { _Pragma("unroll") for (int n = 0; n < 2; ++n) _Pragma("unroll") for (int k = 0; k < 2; ++k) dst[n][k] = *(const PG8_LAS bf16x8*)(lds + PG8_SB(b, h) + boff + n * 2048 + k * 1024); } while (0)
; #define PG8_MMA(ai, bj, At, Bt) do { __builtin_amdgcn_s_setprio(1); _Pragma("unroll") for (int m = 0; m < 4; ++m) _Pragma("unroll") for (int n = 0; n < 2; ++n) _Pragma("unroll") for (int k = 0; k < 2; ++k) \
;         acc[ai][bj][m][n] = __builtin_amdgcn_mfma_f32_16x16x32_bf16(Bt[n][k], At[m][k], acc[ai][bj][m][n], 0, 0, 0); __builtin_amdgcn_s_setprio(0); } while (0)
; #define PG8_WAIT_V(n) asm volatile("s_waitcnt vmcnt(" #n ")" ::: "memory")
; #define PG8_WAIT_L(n) asm volatile("s_waitcnt lgkmcnt(" #n ")" ::: "memory")
; #define PG8_BAR __builtin_amdgcn_s_barrier()
; #define PG8_SCHED __builtin_amdgcn_sched_barrier(0)
; template <class Epi, class Sched>
; __device__ __forceinline__ void gemm_phase(PG8_LAS unsigned char* lds, const Gemm g, const Sched& S, const Epi& E) {
;     ...
;             PG8_BAR; PG8_WAIT_L(0); PG8_MMA(1, 0, At, B0); PG8_BAR; PG8_SCHED;
;             PG8_STAGE(PG8_SB(0, 1), b2 + hstepB, voffB);
;             PG8_WAIT_V(6); PG8_BAR; PG8_MMA(1, 1, At, B1); PG8_BAR;
;             PG8_LDB(B0, 1, 0); PG8_SCHED; PG8_LDA(At, 1, 0); PG8_STAGE(PG8_SA(0, 1), a2 + hstep, voffA);
;             PG8_WAIT_L(8); PG8_BAR; PG8_WAIT_L(0); PG8_MMA(0, 0, At, B0); PG8_BAR; PG8_SCHED;
;             PG8_LDB(B1, 1, 1); PG8_STAGE(PG8_SB(1, 0), b3, voffB);
;             PG8_BAR; PG8_WAIT_L(0); PG8_MMA(0, 1, At, B1); PG8_BAR;
	v_mfma_f32_16x16x32_bf16 v[60:63], v[152:155], v[168:171], v[60:63]
	v_mfma_f32_16x16x32_bf16 v[56:59], v[160:163], v[168:171], v[56:59]
	v_mfma_f32_16x16x32_bf16 v[44:47], v[152:155], v[176:179], v[44:47]
	v_mfma_f32_16x16x32_bf16 v[40:43], v[160:163], v[176:179], v[40:43]
	v_mfma_f32_16x16x32_bf16 v[28:31], v[152:155], v[184:187], v[28:31]
	v_mfma_f32_16x16x32_bf16 v[24:27], v[160:163], v[184:187], v[24:27]
	v_mfma_f32_16x16x32_bf16 v[12:15], v[152:155], v[192:195], v[12:15]
	v_mfma_f32_16x16x32_bf16 v[8:11], v[160:163], v[192:195], v[8:11]
	v_mfma_f32_16x16x32_bf16 v[60:63], v[156:159], v[172:175], v[60:63]
	v_mfma_f32_16x16x32_bf16 v[56:59], v[164:167], v[172:175], v[56:59]
	v_mfma_f32_16x16x32_bf16 v[44:47], v[156:159], v[180:183], v[44:47]
	v_mfma_f32_16x16x32_bf16 v[40:43], v[164:167], v[180:183], v[40:43]
	v_mfma_f32_16x16x32_bf16 v[28:31], v[156:159], v[188:191], v[28:31]
	v_mfma_f32_16x16x32_bf16 v[24:27], v[164:167], v[188:191], v[24:27]
	v_mfma_f32_16x16x32_bf16 v[12:15], v[156:159], v[196:199], v[12:15]
	v_mfma_f32_16x16x32_bf16 v[8:11], v[164:167], v[196:199], v[8:11]
	v_mfma_f32_16x16x32_bf16 v[52:55], v[200:203], v[168:171], v[52:55]
	v_mfma_f32_16x16x32_bf16 v[48:51], v[208:211], v[168:171], v[48:51]
	v_mfma_f32_16x16x32_bf16 v[36:39], v[200:203], v[176:179], v[36:39]
	v_mfma_f32_16x16x32_bf16 v[32:35], v[208:211], v[176:179], v[32:35]
	v_mfma_f32_16x16x32_bf16 v[20:23], v[200:203], v[184:187], v[20:23]
	v_mfma_f32_16x16x32_bf16 v[16:19], v[208:211], v[184:187], v[16:19]
	v_mfma_f32_16x16x32_bf16 v[4:7], v[200:203], v[192:195], v[4:7]
	v_mfma_f32_16x16x32_bf16 v[0:3], v[208:211], v[192:195], v[0:3]
	v_mfma_f32_16x16x32_bf16 v[52:55], v[204:207], v[172:175], v[52:55]
	v_mfma_f32_16x16x32_bf16 v[48:51], v[212:215], v[172:175], v[48:51]
	v_mfma_f32_16x16x32_bf16 v[36:39], v[204:207], v[180:183], v[36:39]
	v_mfma_f32_16x16x32_bf16 v[32:35], v[212:215], v[180:183], v[32:35]
	v_mfma_f32_16x16x32_bf16 v[20:23], v[204:207], v[188:191], v[20:23]
	v_mfma_f32_16x16x32_bf16 v[16:19], v[212:215], v[188:191], v[16:19]
	v_mfma_f32_16x16x32_bf16 v[4:7], v[204:207], v[196:199], v[4:7]
	v_mfma_f32_16x16x32_bf16 v[0:3], v[212:215], v[196:199], v[0:3]
	s_barrier
	s_add_i32 s62, 0, 0x18000
	v_add_u32_e32 v164, s62, v147
	ds_read_b128 v[152:155], v164
	ds_read_b128 v[156:159], v164 offset:1024
	ds_read_b128 v[160:163], v164 offset:2048
	ds_read_b128 v[164:167], v164 offset:3072
	s_add_u32 s24, s24, 0x80000
	s_addc_u32 s25, s25, 0
	s_mov_b32 m0, s47
	v_lshl_add_u64 v[200:201], s[24:25], 0, v[134:135]
	ds_read_b128 v[168:171], v150 offset:32768
	ds_read_b128 v[172:175], v150 offset:33792
	ds_read_b128 v[176:179], v150 offset:34816
	ds_read_b128 v[180:183], v150 offset:35840
	ds_read_b128 v[184:187], v150 offset:36864
	ds_read_b128 v[188:191], v150 offset:37888
	ds_read_b128 v[192:195], v150 offset:38912
	ds_read_b128 v[196:199], v150 offset:39936
	global_load_lds_dwordx4 v[200:201], off
	v_lshl_add_u64 v[200:201], s[24:25], 0, v[132:133]
	s_mov_b32 m0, s48
	s_nop 0
	global_load_lds_dwordx4 v[200:201], off
	s_add_i32 s63, 0, 0x1c000
	s_add_u32 s24, s22, 0x8000
	s_addc_u32 s25, s23, 0
	s_add_i32 s62, s62, s38
	v_add_u32_e32 v212, s63, v147
	v_lshl_add_u64 v[218:219], s[24:25], 0, v[128:129]
	s_mov_b32 m0, s62
	ds_read_b128 v[200:203], v212
	ds_read_b128 v[204:207], v212 offset:1024
	ds_read_b128 v[208:211], v212 offset:2048
	ds_read_b128 v[212:215], v212 offset:3072
	s_waitcnt vmcnt(8)
	s_waitcnt lgkmcnt(0)
	s_barrier
	v_mfma_f32_16x16x32_bf16 v[124:127], v[152:155], v[168:171], v[124:127]
	v_mfma_f32_16x16x32_bf16 v[120:123], v[160:163], v[168:171], v[120:123]
	v_mfma_f32_16x16x32_bf16 v[108:111], v[152:155], v[176:179], v[108:111]
	v_mfma_f32_16x16x32_bf16 v[104:107], v[160:163], v[176:179], v[104:107]
	v_mfma_f32_16x16x32_bf16 v[92:95], v[152:155], v[184:187], v[92:95]
	v_mfma_f32_16x16x32_bf16 v[88:91], v[160:163], v[184:187], v[88:91]
	v_mfma_f32_16x16x32_bf16 v[76:79], v[152:155], v[192:195], v[76:79]
	v_mfma_f32_16x16x32_bf16 v[72:75], v[160:163], v[192:195], v[72:75]
	v_mfma_f32_16x16x32_bf16 v[124:127], v[156:159], v[172:175], v[124:127]
	v_mfma_f32_16x16x32_bf16 v[120:123], v[164:167], v[172:175], v[120:123]
	v_mfma_f32_16x16x32_bf16 v[108:111], v[156:159], v[180:183], v[108:111]
	v_mfma_f32_16x16x32_bf16 v[104:107], v[164:167], v[180:183], v[104:107]
	v_mfma_f32_16x16x32_bf16 v[92:95], v[156:159], v[188:191], v[92:95]
	v_mfma_f32_16x16x32_bf16 v[88:91], v[164:167], v[188:191], v[88:91]
	v_mfma_f32_16x16x32_bf16 v[76:79], v[156:159], v[196:199], v[76:79]
	v_mfma_f32_16x16x32_bf16 v[72:75], v[164:167], v[196:199], v[72:75]
	v_mfma_f32_16x16x32_bf16 v[116:119], v[200:203], v[168:171], v[116:119]
	v_mfma_f32_16x16x32_bf16 v[112:115], v[208:211], v[168:171], v[112:115]
	v_mfma_f32_16x16x32_bf16 v[100:103], v[200:203], v[176:179], v[100:103]
	v_mfma_f32_16x16x32_bf16 v[96:99], v[208:211], v[176:179], v[96:99]
	v_mfma_f32_16x16x32_bf16 v[84:87], v[200:203], v[184:187], v[84:87]
	v_mfma_f32_16x16x32_bf16 v[80:83], v[208:211], v[184:187], v[80:83]
	v_mfma_f32_16x16x32_bf16 v[68:71], v[200:203], v[192:195], v[68:71]
	v_mfma_f32_16x16x32_bf16 v[64:67], v[208:211], v[192:195], v[64:67]
	v_mfma_f32_16x16x32_bf16 v[116:119], v[204:207], v[172:175], v[116:119]
	v_mfma_f32_16x16x32_bf16 v[112:115], v[212:215], v[172:175], v[112:115]
	v_mfma_f32_16x16x32_bf16 v[100:103], v[204:207], v[180:183], v[100:103]
	v_mfma_f32_16x16x32_bf16 v[96:99], v[212:215], v[180:183], v[96:99]
	v_mfma_f32_16x16x32_bf16 v[84:87], v[204:207], v[188:191], v[84:87]
	v_mfma_f32_16x16x32_bf16 v[80:83], v[212:215], v[188:191], v[80:83]
	v_mfma_f32_16x16x32_bf16 v[68:71], v[204:207], v[196:199], v[68:71]
	v_mfma_f32_16x16x32_bf16 v[64:67], v[212:215], v[196:199], v[64:67]
	s_barrier
; #define PG8_STAGE(bufoff, gbase, voff) do { _Pragma("unroll") for (int _i = 0; _i < 2; ++_i) \
;         __builtin_amdgcn_global_load_lds((const unsigned*)((const char*)(gbase) + (voff)[_i]), (PG8_LAS unsigned*)(lds + (bufoff) + ldsw + _i * 8192), 16, 0, 0); } while (0)
; #define PG8_LDA(dst, b, h) do { _Pragma("unroll") for (int m = 0; m < 4; ++m) _Pragma("unroll") for (int k = 0; k < 2; ++k) dst[m][k] = *(const PG8_LAS bf16x8*)(lds + PG8_SA(b, h) + aoff + m * 2048 + k * 1024); } while (0)
; #define PG8_LDB(dst, b, h) do { _Pragma("unroll") for (int n = 0; n < 2; ++n) _Pragma("unroll") for (int k = 0; k < 2; ++k) dst[n][k] = *(const PG8_LAS bf16x8*)(lds + PG8_SB(b, h) + boff + n * 2048 + k * 1024); } while (0)
; #define PG8_MMA(ai, bj, At, Bt) do { __builtin_amdgcn_s_setprio(1); _Pragma("unroll") for (int m = 0; m < 4; ++m) _Pragma("unroll") for (int n = 0; n < 2; ++n) _Pragma("unroll") for (int k = 0; k < 2; ++k) \
;         acc[ai][bj][m][n] = __builtin_amdgcn_mfma_f32_16x16x32_bf16(Bt[n][k], At[m][k], acc[ai][bj][m][n], 0, 0, 0); __builtin_amdgcn_s_setprio(0); } while (0)
; #define PG8_WAIT_V(n) asm volatile("s_waitcnt vmcnt(" #n ")" ::: "memory")
; #define PG8_WAIT_L(n) asm volatile("s_waitcnt lgkmcnt(" #n ")" ::: "memory")
; #define PG8_BAR __builtin_amdgcn_s_barrier()
; #define PG8_SCHED __builtin_amdgcn_sched_barrier(0)
; template <class Epi, class Sched>
; __device__ __forceinline__ void gemm_phase(PG8_LAS unsigned char* lds, const Gemm g, const Sched& S, const Epi& E) {
;     ...
;             PG8_LDB(B1, 1, 1); PG8_STAGE(PG8_SB(1, 0), b3, voffB);
;             PG8_BAR; PG8_WAIT_L(0); PG8_MMA(0, 1, At, B1); PG8_BAR;
;             PG8_LDA(At, 1, 1); PG8_STAGE(PG8_SA(1, 0), a3, voffA);
;             PG8_BAR; PG8_WAIT_L(0); PG8_MMA(1, 0, At, B0); PG8_BAR; PG8_SCHED;
;             PG8_STAGE(PG8_SB(1, 1), b3 + hstepB, voffB);
;             PG8_WAIT_V(6); PG8_BAR; PG8_MMA(1, 1, At, B1); PG8_BAR;
;         }
	global_load_lds_dwordx4 v[218:219], off
	v_lshl_add_u64 v[218:219], s[24:25], 0, v[130:131]
	s_add_i32 m0, s62, 0x2000
	s_nop 0
	global_load_lds_dwordx4 v[218:219], off
	s_mov_b32 m0, s50
	v_lshl_add_u64 v[144:145], v[144:145], 0, s[8:9]
	ds_read_b128 v[168:171], v150 offset:49152
	ds_read_b128 v[172:175], v150 offset:50176
	ds_read_b128 v[176:179], v150 offset:51200
	ds_read_b128 v[180:183], v150 offset:52224
	ds_read_b128 v[184:187], v150 offset:53248
	ds_read_b128 v[188:191], v150 offset:54272
	ds_read_b128 v[192:195], v150 offset:55296
	ds_read_b128 v[196:199], v150 offset:56320
	global_load_lds_dwordx4 v[144:145], off
	v_lshl_add_u64 v[144:145], v[216:217], 0, s[8:9]
	s_mov_b32 m0, s51
	s_nop 0
	global_load_lds_dwordx4 v[144:145], off
	s_add_u32 s22, s22, 0xc000
	s_addc_u32 s23, s23, 0
	s_add_i32 s24, s63, s38
	v_lshl_add_u64 v[144:145], s[22:23], 0, v[128:129]
	s_mov_b32 m0, s24
	s_nop 0
	global_load_lds_dwordx4 v[144:145], off
	v_lshl_add_u64 v[144:145], s[22:23], 0, v[130:131]
	s_add_i32 m0, s24, 0x2000
	s_nop 0
	global_load_lds_dwordx4 v[144:145], off
	s_waitcnt vmcnt(8)
	s_waitcnt lgkmcnt(0)
	s_barrier
	v_mfma_f32_16x16x32_bf16 v[60:63], v[152:155], v[168:171], v[60:63]
	v_mfma_f32_16x16x32_bf16 v[56:59], v[160:163], v[168:171], v[56:59]
	v_mfma_f32_16x16x32_bf16 v[44:47], v[152:155], v[176:179], v[44:47]
	v_mfma_f32_16x16x32_bf16 v[40:43], v[160:163], v[176:179], v[40:43]
	v_mfma_f32_16x16x32_bf16 v[28:31], v[152:155], v[184:187], v[28:31]
	v_mfma_f32_16x16x32_bf16 v[24:27], v[160:163], v[184:187], v[24:27]
	v_mfma_f32_16x16x32_bf16 v[12:15], v[152:155], v[192:195], v[12:15]
	v_mfma_f32_16x16x32_bf16 v[8:11], v[160:163], v[192:195], v[8:11]
	v_mfma_f32_16x16x32_bf16 v[60:63], v[156:159], v[172:175], v[60:63]
	v_mfma_f32_16x16x32_bf16 v[56:59], v[164:167], v[172:175], v[56:59]
	v_mfma_f32_16x16x32_bf16 v[44:47], v[156:159], v[180:183], v[44:47]
	v_mfma_f32_16x16x32_bf16 v[40:43], v[164:167], v[180:183], v[40:43]
	v_mfma_f32_16x16x32_bf16 v[28:31], v[156:159], v[188:191], v[28:31]
	v_mfma_f32_16x16x32_bf16 v[24:27], v[164:167], v[188:191], v[24:27]
	v_mfma_f32_16x16x32_bf16 v[12:15], v[156:159], v[196:199], v[12:15]
	v_mfma_f32_16x16x32_bf16 v[8:11], v[164:167], v[196:199], v[8:11]
	v_mfma_f32_16x16x32_bf16 v[52:55], v[200:203], v[168:171], v[52:55]
	v_mfma_f32_16x16x32_bf16 v[48:51], v[208:211], v[168:171], v[48:51]
	v_mfma_f32_16x16x32_bf16 v[36:39], v[200:203], v[176:179], v[36:39]
	v_mfma_f32_16x16x32_bf16 v[32:35], v[208:211], v[176:179], v[32:35]
	v_mfma_f32_16x16x32_bf16 v[20:23], v[200:203], v[184:187], v[20:23]
	v_mfma_f32_16x16x32_bf16 v[16:19], v[208:211], v[184:187], v[16:19]
	v_mfma_f32_16x16x32_bf16 v[4:7], v[200:203], v[192:195], v[4:7]
	v_mfma_f32_16x16x32_bf16 v[0:3], v[208:211], v[192:195], v[0:3]
	v_mfma_f32_16x16x32_bf16 v[52:55], v[204:207], v[172:175], v[52:55]
	v_mfma_f32_16x16x32_bf16 v[48:51], v[212:215], v[172:175], v[48:51]
	v_mfma_f32_16x16x32_bf16 v[36:39], v[204:207], v[180:183], v[36:39]
	v_mfma_f32_16x16x32_bf16 v[32:35], v[212:215], v[180:183], v[32:35]
	v_mfma_f32_16x16x32_bf16 v[20:23], v[204:207], v[188:191], v[20:23]
	v_mfma_f32_16x16x32_bf16 v[16:19], v[212:215], v[188:191], v[16:19]
	v_mfma_f32_16x16x32_bf16 v[4:7], v[204:207], v[196:199], v[4:7]
	v_mfma_f32_16x16x32_bf16 v[0:3], v[212:215], v[196:199], v[0:3]
	s_add_i32 s61, s61, 2
	s_add_u32 s59, s59, 0x10000
	s_addc_u32 s60, s60, 0
	s_add_u32 s20, s20, 0x100
	s_addc_u32 s21, s21, 0
	s_cmp_gt_u32 s61, 29
	s_barrier
	s_cbranch_scc0 .LBB0_904
	s_cmp_eq_u32 s78, 0
	s_cbranch_scc0 .Lhalf_skip_x_6
	s_barrier

; #define PG8_STAGE(bufoff, gbase, voff) do { _Pragma("unroll") for (int _i = 0; _i < 2; ++_i) \
;         __builtin_amdgcn_global_load_lds((const unsigned*)((const char*)(gbase) + (voff)[_i]), (PG8_LAS unsigned*)(lds + (bufoff) + ldsw + _i * 8192), 16, 0, 0); } while (0)
; #define PG8_LDA(dst, b, h) do { _Pragma("unroll") for (int m = 0; m < 4; ++m) _Pragma("unroll") for (int k = 0; k < 2; ++k) dst[m][k] = *(const PG8_LAS bf16x8*)(lds + PG8_SA(b, h) + aoff + m * 2048 + k * 1024); } while (0)
; #define PG8_LDB(dst, b, h) do { _Pragma("unroll") for (int n = 0; n < 2; ++n) _Pragma("unroll") for (int k = 0; k < 2; ++k) dst[n][k] = *(const PG8_LAS bf16x8*)(lds + PG8_SB(b, h) + boff + n * 2048 + k * 1024); } while (0)
; #define PG8_MMA(ai, bj, At, Bt) do { __builtin_amdgcn_s_setprio(1); _Pragma("unroll") for (int m = 0; m < 4; ++m) _Pragma("unroll") for (int n = 0; n < 2; ++n) _Pragma("unroll") for (int k = 0; k < 2; ++k) \
;         acc[ai][bj][m][n] = __builtin_amdgcn_mfma_f32_16x16x32_bf16(Bt[n][k], At[m][k], acc[ai][bj][m][n], 0, 0, 0); __builtin_amdgcn_s_setprio(0); } while (0)
; #define PG8_WAIT_V(n) asm volatile("s_waitcnt vmcnt(" #n ")" ::: "memory")
; template <class Epi, class Sched>
; __device__ __forceinline__ void gemm_phase(PG8_LAS unsigned char* lds, const Gemm g, const Sched& S, const Epi& E) {
;     ...
;         for (int t = 0; t < nt; t += 2) {
;             const bool last = (t == nt - 2);
;             const char* a1 = cA + (size_t)(t + 1) * kstep;
;             const char* a2 = last ? nA : cA + (size_t)(t + 2) * kstep; const char* b2 = last ? nB : cB + (size_t)(t + 2) * kstepB;
;             const char* a3 = a2 + kstep; const char* b3 = b2 + kstepB;
;             if (last && has_next) S.a_ready(nxt);
;             PG8_LDB(B0, 0, 0); PG8_SCHED; PG8_LDA(At, 0, 0); PG8_STAGE(PG8_SA(1, 1), a1 + hstep, voffA);
;             PG8_WAIT_L(8); PG8_BAR; PG8_WAIT_L(0); PG8_MMA(0, 0, At, B0); PG8_BAR; PG8_SCHED;
;             PG8_LDB(B1, 0, 1); PG8_STAGE(PG8_SB(0, 0), b2, voffB);
;             PG8_BAR; PG8_WAIT_L(0); PG8_MMA(0, 1, At, B1); PG8_BAR;
;             PG8_LDA(At, 0, 1); PG8_STAGE(PG8_SA(0, 0), a2, voffA);
;             PG8_BAR; PG8_WAIT_L(0); PG8_MMA(1, 0, At, B0); PG8_BAR; PG8_SCHED;
;             PG8_STAGE(PG8_SB(0, 1), b2 + hstepB, voffB);
;             PG8_WAIT_V(6); PG8_BAR; PG8_MMA(1, 1, At, B1); PG8_BAR;
.Lhalf_skip_y_7:
.LBB0_980:
	ds_read_b128 v[128:131], v197
	ds_read_b128 v[132:135], v197 offset:1024
	ds_read_b128 v[136:139], v197 offset:2048
	ds_read_b128 v[140:143], v197 offset:3072
	s_add_u32 s24, s22, 0x100
	s_addc_u32 s25, s23, 0
	s_cmpk_eq_i32 s65, 0x52
	s_cselect_b32 s29, s7, s25
	s_cselect_b32 s28, s6, s24
	s_cselect_b32 s27, s9, s64
	s_cselect_b32 s26, s8, s63
	v_lshl_add_u64 v[192:193], s[22:23], 0, v[172:173]
	s_add_i32 m0, s49, 0xc000
	ds_read_b128 v[144:147], v198
	ds_read_b128 v[148:151], v198 offset:1024
	ds_read_b128 v[152:155], v198 offset:2048
	ds_read_b128 v[156:159], v198 offset:3072
	ds_read_b128 v[160:163], v198 offset:4096
	ds_read_b128 v[180:183], v198 offset:5120
	ds_read_b128 v[184:187], v198 offset:6144
	ds_read_b128 v[188:191], v198 offset:7168
	global_load_lds_dwordx4 v[192:193], off
	v_lshl_add_u64 v[192:193], s[22:23], 0, v[174:175]
	s_add_i32 m0, s49, 0xe000
	s_nop 0
	global_load_lds_dwordx4 v[192:193], off
	s_add_i32 s22, s57, s48
	v_lshl_add_u64 v[192:193], s[26:27], 0, v[164:165]
	s_mov_b32 m0, s22
	ds_read_b128 v[200:203], v199
	ds_read_b128 v[204:207], v199 offset:1024
	ds_read_b128 v[208:211], v199 offset:2048
	ds_read_b128 v[212:215], v199 offset:3072
	s_waitcnt vmcnt(8)
	s_waitcnt lgkmcnt(0)
	s_barrier
	v_mfma_f32_16x16x32_bf16 v[124:127], v[128:131], v[144:147], v[124:127]
	v_mfma_f32_16x16x32_bf16 v[120:123], v[136:139], v[144:147], v[120:123]
	v_mfma_f32_16x16x32_bf16 v[116:119], v[128:131], v[152:155], v[116:119]
	v_mfma_f32_16x16x32_bf16 v[104:107], v[136:139], v[152:155], v[104:107]
	v_mfma_f32_16x16x32_bf16 v[92:95], v[128:131], v[160:163], v[92:95]
	v_mfma_f32_16x16x32_bf16 v[88:91], v[136:139], v[160:163], v[88:91]
	v_mfma_f32_16x16x32_bf16 v[76:79], v[128:131], v[184:187], v[76:79]
	v_mfma_f32_16x16x32_bf16 v[72:75], v[136:139], v[184:187], v[72:75]
	v_mfma_f32_16x16x32_bf16 v[124:127], v[132:135], v[148:151], v[124:127]
	v_mfma_f32_16x16x32_bf16 v[120:123], v[140:143], v[148:151], v[120:123]
	v_mfma_f32_16x16x32_bf16 v[116:119], v[132:135], v[156:159], v[116:119]
	v_mfma_f32_16x16x32_bf16 v[104:107], v[140:143], v[156:159], v[104:107]
	v_mfma_f32_16x16x32_bf16 v[92:95], v[132:135], v[180:183], v[92:95]
	v_mfma_f32_16x16x32_bf16 v[88:91], v[140:143], v[180:183], v[88:91]
	v_mfma_f32_16x16x32_bf16 v[76:79], v[132:135], v[188:191], v[76:79]
	v_mfma_f32_16x16x32_bf16 v[72:75], v[140:143], v[188:191], v[72:75]
	v_mfma_f32_16x16x32_bf16 v[112:115], v[200:203], v[144:147], v[112:115]
	v_mfma_f32_16x16x32_bf16 v[108:111], v[208:211], v[144:147], v[108:111]
	v_mfma_f32_16x16x32_bf16 v[100:103], v[200:203], v[152:155], v[100:103]
	v_mfma_f32_16x16x32_bf16 v[96:99], v[208:211], v[152:155], v[96:99]
	v_mfma_f32_16x16x32_bf16 v[84:87], v[200:203], v[160:163], v[84:87]
	v_mfma_f32_16x16x32_bf16 v[80:83], v[208:211], v[160:163], v[80:83]
	v_mfma_f32_16x16x32_bf16 v[68:71], v[200:203], v[184:187], v[68:71]
	v_mfma_f32_16x16x32_bf16 v[64:67], v[208:211], v[184:187], v[64:67]
	v_mfma_f32_16x16x32_bf16 v[112:115], v[204:207], v[148:151], v[112:115]
	v_mfma_f32_16x16x32_bf16 v[108:111], v[212:215], v[148:151], v[108:111]
	v_mfma_f32_16x16x32_bf16 v[100:103], v[204:207], v[156:159], v[100:103]
	v_mfma_f32_16x16x32_bf16 v[96:99], v[212:215], v[156:159], v[96:99]
	v_mfma_f32_16x16x32_bf16 v[84:87], v[204:207], v[180:183], v[84:87]
	v_mfma_f32_16x16x32_bf16 v[80:83], v[212:215], v[180:183], v[80:83]
	v_mfma_f32_16x16x32_bf16 v[68:71], v[204:207], v[188:191], v[68:71]
	v_mfma_f32_16x16x32_bf16 v[64:67], v[212:215], v[188:191], v[64:67]
	s_barrier
	global_load_lds_dwordx4 v[192:193], off
	v_lshl_add_u64 v[192:193], s[26:27], 0, v[168:169]
	s_add_i32 m0, s22, 0x2000
	s_nop 0
	global_load_lds_dwordx4 v[192:193], off
	s_mov_b32 m0, s49
	v_lshl_add_u64 v[192:193], s[28:29], 0, v[166:167]
	ds_read_b128 v[144:147], v198 offset:16384
	ds_read_b128 v[148:151], v198 offset:17408
	ds_read_b128 v[152:155], v198 offset:18432
	ds_read_b128 v[156:159], v198 offset:19456
	ds_read_b128 v[160:163], v198 offset:20480
	ds_read_b128 v[180:183], v198 offset:21504
	ds_read_b128 v[184:187], v198 offset:22528
	ds_read_b128 v[188:191], v198 offset:23552
	global_load_lds_dwordx4 v[192:193], off
	v_lshl_add_u64 v[216:217], s[28:29], 0, v[170:171]
	s_mov_b32 m0, s50
	s_nop 0
	global_load_lds_dwordx4 v[216:217], off
	s_add_u32 s22, s26, 0x4000
	s_addc_u32 s23, s27, 0
	s_add_i32 s66, s58, s48
	v_lshl_add_u64 v[250:251], s[22:23], 0, v[164:165]
	s_mov_b32 m0, s66
	s_nop 0
	global_load_lds_dwordx4 v[250:251], off
	v_lshl_add_u64 v[250:251], s[22:23], 0, v[168:169]
	s_add_i32 m0, s66, 0x2000
	s_nop 0
	global_load_lds_dwordx4 v[250:251], off
	s_waitcnt vmcnt(8)
	s_waitcnt lgkmcnt(0)
	s_barrier
; #define PG8_STAGE(bufoff, gbase, voff) do { _Pragma("unroll") for (int _i = 0; _i < 2; ++_i) \
;         __builtin_amdgcn_global_load_lds((const unsigned*)((const char*)(gbase) + (voff)[_i]), (PG8_LAS unsigned*)(lds + (bufoff) + ldsw + _i * 8192), 16, 0, 0); } while (0)
; #define PG8_LDA(dst, b, h) do { _Pragma("unroll") for (int m = 0; m < 4; ++m) _Pragma("unroll") for (int k = 0; k < 2; ++k) dst[m][k] = *(const PG8_LAS bf16x8*)(lds + PG8_SA(b, h) + aoff + m * 2048 + k * 1024); } while (0)
; #define PG8_LDB(dst, b, h) do { _Pragma("unroll") for (int n = 0; n < 2; ++n) _Pragma("unroll") for (int k = 0; k < 2; ++k) dst[n][k] = *(const PG8_LAS bf16x8*)(lds + PG8_SB(b, h) + boff + n * 2048 + k * 1024); } while (0)
; #define PG8_MMA(ai, bj, At, Bt) do { __builtin_amdgcn_s_setprio(1); _Pragma("unroll") for (int m = 0; m < 4; ++m) _Pragma("unroll") for (int n = 0; n < 2; ++n) _Pragma("unroll") for (int k = 0; k < 2; ++k) \
;         acc[ai][bj][m][n] = __builtin_amdgcn_mfma_f32_16x16x32_bf16(Bt[n][k], At[m][k], acc[ai][bj][m][n], 0, 0, 0); __builtin_amdgcn_s_setprio(0); } while (0)
; #define PG8_WAIT_V(n) asm volatile("s_waitcnt vmcnt(" #n ")" ::: "memory")
; #define PG8_WAIT_L(n) asm volatile("s_waitcnt lgkmcnt(" #n ")" ::: "memory")
; #define PG8_BAR __builtin_amdgcn_s_barrier()
; #define PG8_SCHED __builtin_amdgcn_sched_barrier(0)
; template <class Epi, class Sched>
; __device__ __forceinline__ void gemm_phase(PG8_LAS unsigned char* lds, const Gemm g, const Sched& S, const Epi& E) {
;     ...
;             PG8_BAR; PG8_WAIT_L(0); PG8_MMA(1, 0, At, B0); PG8_BAR; PG8_SCHED;
;             PG8_STAGE(PG8_SB(0, 1), b2 + hstepB, voffB);
;             PG8_WAIT_V(6); PG8_BAR; PG8_MMA(1, 1, At, B1); PG8_BAR;
;             PG8_LDB(B0, 1, 0); PG8_SCHED; PG8_LDA(At, 1, 0); PG8_STAGE(PG8_SA(0, 1), a2 + hstep, voffA);
;             PG8_WAIT_L(8); PG8_BAR; PG8_WAIT_L(0); PG8_MMA(0, 0, At, B0); PG8_BAR; PG8_SCHED;
;             PG8_LDB(B1, 1, 1); PG8_STAGE(PG8_SB(1, 0), b3, voffB);
;             PG8_BAR; PG8_WAIT_L(0); PG8_MMA(0, 1, At, B1); PG8_BAR;
	v_mfma_f32_16x16x32_bf16 v[60:63], v[128:131], v[144:147], v[60:63]
	v_mfma_f32_16x16x32_bf16 v[56:59], v[136:139], v[144:147], v[56:59]
	v_mfma_f32_16x16x32_bf16 v[44:47], v[128:131], v[152:155], v[44:47]
	v_mfma_f32_16x16x32_bf16 v[40:43], v[136:139], v[152:155], v[40:43]
	v_mfma_f32_16x16x32_bf16 v[28:31], v[128:131], v[160:163], v[28:31]
	v_mfma_f32_16x16x32_bf16 v[24:27], v[136:139], v[160:163], v[24:27]
	v_mfma_f32_16x16x32_bf16 v[12:15], v[128:131], v[184:187], v[12:15]
	v_mfma_f32_16x16x32_bf16 v[8:11], v[136:139], v[184:187], v[8:11]
	v_mfma_f32_16x16x32_bf16 v[60:63], v[132:135], v[148:151], v[60:63]
	v_mfma_f32_16x16x32_bf16 v[56:59], v[140:143], v[148:151], v[56:59]
	v_mfma_f32_16x16x32_bf16 v[44:47], v[132:135], v[156:159], v[44:47]
	v_mfma_f32_16x16x32_bf16 v[40:43], v[140:143], v[156:159], v[40:43]
	v_mfma_f32_16x16x32_bf16 v[28:31], v[132:135], v[180:183], v[28:31]
	v_mfma_f32_16x16x32_bf16 v[24:27], v[140:143], v[180:183], v[24:27]
	v_mfma_f32_16x16x32_bf16 v[12:15], v[132:135], v[188:191], v[12:15]
	v_mfma_f32_16x16x32_bf16 v[8:11], v[140:143], v[188:191], v[8:11]
	v_mfma_f32_16x16x32_bf16 v[52:55], v[200:203], v[144:147], v[52:55]
	v_mfma_f32_16x16x32_bf16 v[48:51], v[208:211], v[144:147], v[48:51]
	v_mfma_f32_16x16x32_bf16 v[36:39], v[200:203], v[152:155], v[36:39]
	v_mfma_f32_16x16x32_bf16 v[32:35], v[208:211], v[152:155], v[32:35]
	v_mfma_f32_16x16x32_bf16 v[20:23], v[200:203], v[160:163], v[20:23]
	v_mfma_f32_16x16x32_bf16 v[16:19], v[208:211], v[160:163], v[16:19]
	v_mfma_f32_16x16x32_bf16 v[4:7], v[200:203], v[184:187], v[4:7]
	v_mfma_f32_16x16x32_bf16 v[0:3], v[208:211], v[184:187], v[0:3]
	v_mfma_f32_16x16x32_bf16 v[52:55], v[204:207], v[148:151], v[52:55]
	v_mfma_f32_16x16x32_bf16 v[48:51], v[212:215], v[148:151], v[48:51]
	v_mfma_f32_16x16x32_bf16 v[36:39], v[204:207], v[156:159], v[36:39]
	v_mfma_f32_16x16x32_bf16 v[32:35], v[212:215], v[156:159], v[32:35]
	v_mfma_f32_16x16x32_bf16 v[20:23], v[204:207], v[180:183], v[20:23]
	v_mfma_f32_16x16x32_bf16 v[16:19], v[212:215], v[180:183], v[16:19]
	v_mfma_f32_16x16x32_bf16 v[4:7], v[204:207], v[188:191], v[4:7]
	v_mfma_f32_16x16x32_bf16 v[0:3], v[212:215], v[188:191], v[0:3]
	s_barrier
	s_add_i32 s66, 0, 0x18000
	v_add_u32_e32 v140, s66, v195
	ds_read_b128 v[128:131], v140
	ds_read_b128 v[132:135], v140 offset:1024
	ds_read_b128 v[136:139], v140 offset:2048
	ds_read_b128 v[140:143], v140 offset:3072
	s_add_u32 s22, s28, 0x158000
	s_addc_u32 s23, s29, 0
	s_mov_b32 m0, s51
	v_lshl_add_u64 v[200:201], s[22:23], 0, v[166:167]
	ds_read_b128 v[144:147], v198 offset:32768
	ds_read_b128 v[148:151], v198 offset:33792
	ds_read_b128 v[152:155], v198 offset:34816
	ds_read_b128 v[156:159], v198 offset:35840
	ds_read_b128 v[160:163], v198 offset:36864
	ds_read_b128 v[180:183], v198 offset:37888
	ds_read_b128 v[184:187], v198 offset:38912
	ds_read_b128 v[188:191], v198 offset:39936
	global_load_lds_dwordx4 v[200:201], off
	v_lshl_add_u64 v[200:201], s[22:23], 0, v[170:171]
	s_mov_b32 m0, s52
	s_nop 0
	global_load_lds_dwordx4 v[200:201], off
	s_add_i32 s28, 0, 0x1c000
	s_add_u32 s22, s26, 0x8000
	s_addc_u32 s23, s27, 0
	s_add_i32 s29, s66, s48
	v_add_u32_e32 v212, s28, v195
	v_lshl_add_u64 v[218:219], s[22:23], 0, v[164:165]
	s_mov_b32 m0, s29
	ds_read_b128 v[200:203], v212
	ds_read_b128 v[204:207], v212 offset:1024
	ds_read_b128 v[208:211], v212 offset:2048
	ds_read_b128 v[212:215], v212 offset:3072
	s_waitcnt vmcnt(8)
	s_waitcnt lgkmcnt(0)
	s_barrier
	v_mfma_f32_16x16x32_bf16 v[124:127], v[128:131], v[144:147], v[124:127]
	v_mfma_f32_16x16x32_bf16 v[120:123], v[136:139], v[144:147], v[120:123]
	v_mfma_f32_16x16x32_bf16 v[116:119], v[128:131], v[152:155], v[116:119]
	v_mfma_f32_16x16x32_bf16 v[104:107], v[136:139], v[152:155], v[104:107]
	v_mfma_f32_16x16x32_bf16 v[92:95], v[128:131], v[160:163], v[92:95]
	v_mfma_f32_16x16x32_bf16 v[88:91], v[136:139], v[160:163], v[88:91]
	v_mfma_f32_16x16x32_bf16 v[76:79], v[128:131], v[184:187], v[76:79]
	v_mfma_f32_16x16x32_bf16 v[72:75], v[136:139], v[184:187], v[72:75]
	v_mfma_f32_16x16x32_bf16 v[124:127], v[132:135], v[148:151], v[124:127]
	v_mfma_f32_16x16x32_bf16 v[120:123], v[140:143], v[148:151], v[120:123]
	v_mfma_f32_16x16x32_bf16 v[116:119], v[132:135], v[156:159], v[116:119]
	v_mfma_f32_16x16x32_bf16 v[104:107], v[140:143], v[156:159], v[104:107]
	v_mfma_f32_16x16x32_bf16 v[92:95], v[132:135], v[180:183], v[92:95]
	v_mfma_f32_16x16x32_bf16 v[88:91], v[140:143], v[180:183], v[88:91]
	v_mfma_f32_16x16x32_bf16 v[76:79], v[132:135], v[188:191], v[76:79]
	v_mfma_f32_16x16x32_bf16 v[72:75], v[140:143], v[188:191], v[72:75]
	v_mfma_f32_16x16x32_bf16 v[112:115], v[200:203], v[144:147], v[112:115]
	v_mfma_f32_16x16x32_bf16 v[108:111], v[208:211], v[144:147], v[108:111]
	v_mfma_f32_16x16x32_bf16 v[100:103], v[200:203], v[152:155], v[100:103]
	v_mfma_f32_16x16x32_bf16 v[96:99], v[208:211], v[152:155], v[96:99]
	v_mfma_f32_16x16x32_bf16 v[84:87], v[200:203], v[160:163], v[84:87]
	v_mfma_f32_16x16x32_bf16 v[80:83], v[208:211], v[160:163], v[80:83]
	v_mfma_f32_16x16x32_bf16 v[68:71], v[200:203], v[184:187], v[68:71]
	v_mfma_f32_16x16x32_bf16 v[64:67], v[208:211], v[184:187], v[64:67]
	v_mfma_f32_16x16x32_bf16 v[112:115], v[204:207], v[148:151], v[112:115]
	v_mfma_f32_16x16x32_bf16 v[108:111], v[212:215], v[148:151], v[108:111]
	v_mfma_f32_16x16x32_bf16 v[100:103], v[204:207], v[156:159], v[100:103]
	v_mfma_f32_16x16x32_bf16 v[96:99], v[212:215], v[156:159], v[96:99]
	v_mfma_f32_16x16x32_bf16 v[84:87], v[204:207], v[180:183], v[84:87]
	v_mfma_f32_16x16x32_bf16 v[80:83], v[212:215], v[180:183], v[80:83]
	v_mfma_f32_16x16x32_bf16 v[68:71], v[204:207], v[188:191], v[68:71]
	v_mfma_f32_16x16x32_bf16 v[64:67], v[212:215], v[188:191], v[64:67]
	s_barrier
; #define PG8_STAGE(bufoff, gbase, voff) do { _Pragma("unroll") for (int _i = 0; _i < 2; ++_i) \
;         __builtin_amdgcn_global_load_lds((const unsigned*)((const char*)(gbase) + (voff)[_i]), (PG8_LAS unsigned*)(lds + (bufoff) + ldsw + _i * 8192), 16, 0, 0); } while (0)
; #define PG8_LDA(dst, b, h) do { _Pragma("unroll") for (int m = 0; m < 4; ++m) _Pragma("unroll") for (int k = 0; k < 2; ++k) dst[m][k] = *(const PG8_LAS bf16x8*)(lds + PG8_SA(b, h) + aoff + m * 2048 + k * 1024); } while (0)
; #define PG8_LDB(dst, b, h) do { _Pragma("unroll") for (int n = 0; n < 2; ++n) _Pragma("unroll") for (int k = 0; k < 2; ++k) dst[n][k] = *(const PG8_LAS bf16x8*)(lds + PG8_SB(b, h) + boff + n * 2048 + k * 1024); } while (0)
; #define PG8_MMA(ai, bj, At, Bt) do { __builtin_amdgcn_s_setprio(1); _Pragma("unroll") for (int m = 0; m < 4; ++m) _Pragma("unroll") for (int n = 0; n < 2; ++n) _Pragma("unroll") for (int k = 0; k < 2; ++k) \
;         acc[ai][bj][m][n] = __builtin_amdgcn_mfma_f32_16x16x32_bf16(Bt[n][k], At[m][k], acc[ai][bj][m][n], 0, 0, 0); __builtin_amdgcn_s_setprio(0); } while (0)
; #define PG8_WAIT_V(n) asm volatile("s_waitcnt vmcnt(" #n ")" ::: "memory")
; #define PG8_WAIT_L(n) asm volatile("s_waitcnt lgkmcnt(" #n ")" ::: "memory")
; #define PG8_BAR __builtin_amdgcn_s_barrier()
; #define PG8_SCHED __builtin_amdgcn_sched_barrier(0)
; template <class Epi, class Sched>
; __device__ __forceinline__ void gemm_phase(PG8_LAS unsigned char* lds, const Gemm g, const Sched& S, const Epi& E) {
;     ...
;             PG8_LDB(B1, 1, 1); PG8_STAGE(PG8_SB(1, 0), b3, voffB);
;             PG8_BAR; PG8_WAIT_L(0); PG8_MMA(0, 1, At, B1); PG8_BAR;
;             PG8_LDA(At, 1, 1); PG8_STAGE(PG8_SA(1, 0), a3, voffA);
;             PG8_BAR; PG8_WAIT_L(0); PG8_MMA(1, 0, At, B0); PG8_BAR; PG8_SCHED;
;             PG8_STAGE(PG8_SB(1, 1), b3 + hstepB, voffB);
;             PG8_WAIT_V(6); PG8_BAR; PG8_MMA(1, 1, At, B1); PG8_BAR;
;         }
	global_load_lds_dwordx4 v[218:219], off
	v_lshl_add_u64 v[218:219], s[22:23], 0, v[168:169]
	s_add_i32 m0, s29, 0x2000
	s_nop 0
	global_load_lds_dwordx4 v[218:219], off
	s_mov_b32 m0, s54
	v_lshl_add_u64 v[192:193], v[192:193], 0, s[12:13]
	ds_read_b128 v[144:147], v198 offset:49152
	ds_read_b128 v[148:151], v198 offset:50176
	ds_read_b128 v[152:155], v198 offset:51200
	ds_read_b128 v[156:159], v198 offset:52224
	ds_read_b128 v[160:163], v198 offset:53248
	ds_read_b128 v[180:183], v198 offset:54272
	ds_read_b128 v[184:187], v198 offset:55296
	ds_read_b128 v[188:191], v198 offset:56320
	global_load_lds_dwordx4 v[192:193], off
	v_lshl_add_u64 v[192:193], v[216:217], 0, s[12:13]
	s_mov_b32 m0, s55
	s_nop 0
	global_load_lds_dwordx4 v[192:193], off
	s_add_u32 s22, s26, 0xc000
	s_addc_u32 s23, s27, 0
	s_add_i32 s26, s28, s48
	v_lshl_add_u64 v[252:253], s[22:23], 0, v[164:165]
	s_mov_b32 m0, s26
	s_nop 0
	global_load_lds_dwordx4 v[252:253], off
	v_lshl_add_u64 v[252:253], s[22:23], 0, v[168:169]
	s_add_i32 m0, s26, 0x2000
	s_nop 0
	global_load_lds_dwordx4 v[252:253], off
	s_waitcnt vmcnt(8)
	s_waitcnt lgkmcnt(0)
	s_barrier
	v_mfma_f32_16x16x32_bf16 v[60:63], v[128:131], v[144:147], v[60:63]
	v_mfma_f32_16x16x32_bf16 v[56:59], v[136:139], v[144:147], v[56:59]
	v_mfma_f32_16x16x32_bf16 v[44:47], v[128:131], v[152:155], v[44:47]
	v_mfma_f32_16x16x32_bf16 v[40:43], v[136:139], v[152:155], v[40:43]
	v_mfma_f32_16x16x32_bf16 v[28:31], v[128:131], v[160:163], v[28:31]
	v_mfma_f32_16x16x32_bf16 v[24:27], v[136:139], v[160:163], v[24:27]
	v_mfma_f32_16x16x32_bf16 v[12:15], v[128:131], v[184:187], v[12:15]
	v_mfma_f32_16x16x32_bf16 v[8:11], v[136:139], v[184:187], v[8:11]
	v_mfma_f32_16x16x32_bf16 v[60:63], v[132:135], v[148:151], v[60:63]
	v_mfma_f32_16x16x32_bf16 v[56:59], v[140:143], v[148:151], v[56:59]
	v_mfma_f32_16x16x32_bf16 v[44:47], v[132:135], v[156:159], v[44:47]
	v_mfma_f32_16x16x32_bf16 v[40:43], v[140:143], v[156:159], v[40:43]
	v_mfma_f32_16x16x32_bf16 v[28:31], v[132:135], v[180:183], v[28:31]
	v_mfma_f32_16x16x32_bf16 v[24:27], v[140:143], v[180:183], v[24:27]
	v_mfma_f32_16x16x32_bf16 v[12:15], v[132:135], v[188:191], v[12:15]
	v_mfma_f32_16x16x32_bf16 v[8:11], v[140:143], v[188:191], v[8:11]
	v_mfma_f32_16x16x32_bf16 v[52:55], v[200:203], v[144:147], v[52:55]
	v_mfma_f32_16x16x32_bf16 v[48:51], v[208:211], v[144:147], v[48:51]
	v_mfma_f32_16x16x32_bf16 v[36:39], v[200:203], v[152:155], v[36:39]
	v_mfma_f32_16x16x32_bf16 v[32:35], v[208:211], v[152:155], v[32:35]
	v_mfma_f32_16x16x32_bf16 v[20:23], v[200:203], v[160:163], v[20:23]
	v_mfma_f32_16x16x32_bf16 v[16:19], v[208:211], v[160:163], v[16:19]
	v_mfma_f32_16x16x32_bf16 v[4:7], v[200:203], v[184:187], v[4:7]
	v_mfma_f32_16x16x32_bf16 v[0:3], v[208:211], v[184:187], v[0:3]
	v_mfma_f32_16x16x32_bf16 v[52:55], v[204:207], v[148:151], v[52:55]
	v_mfma_f32_16x16x32_bf16 v[48:51], v[212:215], v[148:151], v[48:51]
	v_mfma_f32_16x16x32_bf16 v[36:39], v[204:207], v[156:159], v[36:39]
	v_mfma_f32_16x16x32_bf16 v[32:35], v[212:215], v[156:159], v[32:35]
	v_mfma_f32_16x16x32_bf16 v[20:23], v[204:207], v[180:183], v[20:23]
	v_mfma_f32_16x16x32_bf16 v[16:19], v[212:215], v[180:183], v[16:19]
	v_mfma_f32_16x16x32_bf16 v[4:7], v[204:207], v[188:191], v[4:7]
	v_mfma_f32_16x16x32_bf16 v[0:3], v[212:215], v[188:191], v[0:3]
	s_add_i32 s65, s65, 2
	s_add_u32 s63, s63, 0x10000
	s_addc_u32 s64, s64, 0
	s_cmpk_gt_u32 s65, 0x53
	s_mov_b64 s[22:23], s[24:25]
	s_barrier
	s_cbranch_scc0 .LBB0_980
	s_cmp_eq_u32 s78, 0
	s_cbranch_scc0 .Lhalf_skip_x_7
	s_barrier
